# as previous + redundant post-barrier lgkmcnt waits and mid-segment setprio flips removed in K-loops
# speedup vs baseline: 1.0080x; 1.0020x over previous
.Lrestag_187:
	ds_read_b128 v[162:165], v157
	ds_read_b128 v[170:173], v157 offset:1024
	ds_read_b128 v[174:177], v157 offset:2048
	ds_read_b128 v[178:181], v157 offset:3072
	ds_read_b128 v[182:185], v158
	ds_read_b128 v[186:189], v158 offset:1024
	ds_read_b128 v[190:193], v158 offset:2048
	ds_read_b128 v[194:197], v158 offset:3072
	s_add_u32 s26, s24, 0x100
	s_addc_u32 s27, s25, 0
	s_cmp_eq_u32 s59, 12
	s_cselect_b32 s31, s17, s27
	s_cselect_b32 s30, s55, s26
	s_cselect_b32 s29, s15, s58
	s_cselect_b32 s28, s56, s57
	s_add_i32 m0, s23, 0xc000
	ds_read_b128 v[198:201], v159
	ds_read_b128 v[202:205], v159 offset:1024
	ds_read_b128 v[206:209], v159 offset:2048
	ds_read_b128 v[210:213], v159 offset:3072
	ds_read_b128 v[214:217], v159 offset:4096
	ds_read_b128 v[218:221], v159 offset:5120
	ds_read_b128 v[222:225], v159 offset:6144
	ds_read_b128 v[226:229], v159 offset:7168
	global_load_lds_dwordx4 v142, s[24:25]
	s_add_i32 m0, s23, 0xe000
	s_nop 0
	global_load_lds_dwordx4 v144, s[24:25]
	s_nop 0
	s_waitcnt lgkmcnt(0)
	s_barrier
	s_setprio 1
	v_mfma_f32_16x16x32_bf16 v[124:127], v[162:165], v[198:201], 0
	v_mfma_f32_16x16x32_bf16 v[120:123], v[174:177], v[198:201], 0
	v_mfma_f32_16x16x32_bf16 v[112:115], v[162:165], v[206:209], 0
	v_mfma_f32_16x16x32_bf16 v[104:107], v[174:177], v[206:209], 0
	v_mfma_f32_16x16x32_bf16 v[96:99], v[162:165], v[214:217], 0
	v_mfma_f32_16x16x32_bf16 v[88:91], v[174:177], v[214:217], 0
	v_mfma_f32_16x16x32_bf16 v[80:83], v[162:165], v[222:225], 0
	v_mfma_f32_16x16x32_bf16 v[72:75], v[174:177], v[222:225], 0
	v_mfma_f32_16x16x32_bf16 v[124:127], v[170:173], v[202:205], v[124:127]
	v_mfma_f32_16x16x32_bf16 v[120:123], v[178:181], v[202:205], v[120:123]
	v_mfma_f32_16x16x32_bf16 v[112:115], v[170:173], v[210:213], v[112:115]
	v_mfma_f32_16x16x32_bf16 v[104:107], v[178:181], v[210:213], v[104:107]
	v_mfma_f32_16x16x32_bf16 v[96:99], v[170:173], v[218:221], v[96:99]
	v_mfma_f32_16x16x32_bf16 v[88:91], v[178:181], v[218:221], v[88:91]
	v_mfma_f32_16x16x32_bf16 v[80:83], v[170:173], v[226:229], v[80:83]
	v_mfma_f32_16x16x32_bf16 v[72:75], v[178:181], v[226:229], v[72:75]
	v_mfma_f32_16x16x32_bf16 v[116:119], v[182:185], v[198:201], 0
	v_mfma_f32_16x16x32_bf16 v[108:111], v[190:193], v[198:201], 0
	v_mfma_f32_16x16x32_bf16 v[100:103], v[182:185], v[206:209], 0
	v_mfma_f32_16x16x32_bf16 v[92:95], v[190:193], v[206:209], 0
	v_mfma_f32_16x16x32_bf16 v[84:87], v[182:185], v[214:217], 0
	v_mfma_f32_16x16x32_bf16 v[76:79], v[190:193], v[214:217], 0
	v_mfma_f32_16x16x32_bf16 v[68:71], v[182:185], v[222:225], 0
	v_mfma_f32_16x16x32_bf16 v[64:67], v[190:193], v[222:225], 0
	v_mfma_f32_16x16x32_bf16 v[116:119], v[186:189], v[202:205], v[116:119]
	v_mfma_f32_16x16x32_bf16 v[108:111], v[194:197], v[202:205], v[108:111]
	v_mfma_f32_16x16x32_bf16 v[100:103], v[186:189], v[210:213], v[100:103]
	v_mfma_f32_16x16x32_bf16 v[92:95], v[194:197], v[210:213], v[92:95]
	v_mfma_f32_16x16x32_bf16 v[84:87], v[186:189], v[218:221], v[84:87]
	v_mfma_f32_16x16x32_bf16 v[76:79], v[194:197], v[218:221], v[76:79]
	v_mfma_f32_16x16x32_bf16 v[68:71], v[186:189], v[226:229], v[68:71]
	v_mfma_f32_16x16x32_bf16 v[64:67], v[194:197], v[226:229], v[64:67]
	s_setprio 0
	s_barrier
	s_add_i32 s0, s51, s41
	v_lshl_add_u64 v[166:167], s[28:29], 0, v[130:131]
	s_mov_b32 m0, s0
	ds_read_b128 v[198:201], v159 offset:16384
	ds_read_b128 v[202:205], v159 offset:17408
	ds_read_b128 v[206:209], v159 offset:18432
	ds_read_b128 v[210:213], v159 offset:19456
	ds_read_b128 v[214:217], v159 offset:20480
	ds_read_b128 v[218:221], v159 offset:21504
	ds_read_b128 v[222:225], v159 offset:22528
	ds_read_b128 v[226:229], v159 offset:23552
	global_load_lds_dwordx4 v[166:167], off
	s_add_i32 m0, s0, 0x2000
	s_add_u32 s0, s28, 0x40000
	v_lshl_add_u64 v[230:231], s[28:29], 0, v[134:135]
	s_addc_u32 s1, s29, 0
	s_add_i32 s24, s52, s41
	global_load_lds_dwordx4 v[230:231], off
	s_mov_b32 m0, s24
	v_lshl_add_u64 v[234:235], s[30:31], 0, v[132:133]
	global_load_lds_dwordx4 v130, s[0:1]
	s_add_i32 m0, s24, 0x2000
	s_nop 0
	global_load_lds_dwordx4 v134, s[0:1]
	v_lshl_add_u64 v[232:233], s[30:31], 0, v[128:129]
	s_nop 0
	s_waitcnt lgkmcnt(0)
	s_barrier
	s_setprio 1
	v_mfma_f32_16x16x32_bf16 v[60:63], v[162:165], v[198:201], 0
	v_mfma_f32_16x16x32_bf16 v[56:59], v[174:177], v[198:201], 0
	v_mfma_f32_16x16x32_bf16 v[48:51], v[162:165], v[206:209], 0
	v_mfma_f32_16x16x32_bf16 v[40:43], v[174:177], v[206:209], 0
	v_mfma_f32_16x16x32_bf16 v[32:35], v[162:165], v[214:217], 0
	v_mfma_f32_16x16x32_bf16 v[24:27], v[174:177], v[214:217], 0
	v_mfma_f32_16x16x32_bf16 v[16:19], v[162:165], v[222:225], 0
	v_mfma_f32_16x16x32_bf16 v[8:11], v[174:177], v[222:225], 0
	v_mfma_f32_16x16x32_bf16 v[60:63], v[170:173], v[202:205], v[60:63]
	v_mfma_f32_16x16x32_bf16 v[56:59], v[178:181], v[202:205], v[56:59]
	v_mfma_f32_16x16x32_bf16 v[48:51], v[170:173], v[210:213], v[48:51]
	v_mfma_f32_16x16x32_bf16 v[40:43], v[178:181], v[210:213], v[40:43]
	v_mfma_f32_16x16x32_bf16 v[32:35], v[170:173], v[218:221], v[32:35]
	v_mfma_f32_16x16x32_bf16 v[24:27], v[178:181], v[218:221], v[24:27]
	v_mfma_f32_16x16x32_bf16 v[16:19], v[170:173], v[226:229], v[16:19]
	v_mfma_f32_16x16x32_bf16 v[8:11], v[178:181], v[226:229], v[8:11]
	v_mfma_f32_16x16x32_bf16 v[52:55], v[182:185], v[198:201], 0
	v_mfma_f32_16x16x32_bf16 v[44:47], v[190:193], v[198:201], 0
	v_mfma_f32_16x16x32_bf16 v[36:39], v[182:185], v[206:209], 0
	v_mfma_f32_16x16x32_bf16 v[28:31], v[190:193], v[206:209], 0
	v_mfma_f32_16x16x32_bf16 v[20:23], v[182:185], v[214:217], 0
	v_mfma_f32_16x16x32_bf16 v[12:15], v[190:193], v[214:217], 0
	v_mfma_f32_16x16x32_bf16 v[4:7], v[182:185], v[222:225], 0
	v_mfma_f32_16x16x32_bf16 v[0:3], v[190:193], v[222:225], 0
	v_mfma_f32_16x16x32_bf16 v[52:55], v[186:189], v[202:205], v[52:55]
	v_mfma_f32_16x16x32_bf16 v[44:47], v[194:197], v[202:205], v[44:47]
	v_mfma_f32_16x16x32_bf16 v[36:39], v[186:189], v[210:213], v[36:39]
	v_mfma_f32_16x16x32_bf16 v[28:31], v[194:197], v[210:213], v[28:31]
	v_mfma_f32_16x16x32_bf16 v[20:23], v[186:189], v[218:221], v[20:23]
	v_mfma_f32_16x16x32_bf16 v[12:15], v[194:197], v[218:221], v[12:15]
	v_mfma_f32_16x16x32_bf16 v[4:7], v[186:189], v[226:229], v[4:7]
	v_mfma_f32_16x16x32_bf16 v[0:3], v[194:197], v[226:229], v[0:3]
	s_setprio 0
	s_barrier
	s_add_i32 s24, 0, 0x18000
	v_add_u32_e32 v150, s24, v153
	s_add_i32 s25, 0, 0x1c000
	ds_read_b128 v[162:165], v150
	ds_read_b128 v[170:173], v150 offset:1024
	ds_read_b128 v[174:177], v150 offset:2048
	ds_read_b128 v[178:181], v150 offset:3072
	v_add_u32_e32 v150, s25, v153
	ds_read_b128 v[182:185], v150
	ds_read_b128 v[186:189], v150 offset:1024
	ds_read_b128 v[190:193], v150 offset:2048
	ds_read_b128 v[194:197], v150 offset:3072
	s_add_u32 s0, s30, 0x40000
	s_addc_u32 s1, s31, 0
	s_mov_b32 m0, s43
	ds_read_b128 v[198:201], v159 offset:32768
	ds_read_b128 v[202:205], v159 offset:33792
	ds_read_b128 v[206:209], v159 offset:34816
	ds_read_b128 v[210:213], v159 offset:35840
	ds_read_b128 v[214:217], v159 offset:36864
	ds_read_b128 v[218:221], v159 offset:37888
	ds_read_b128 v[222:225], v159 offset:38912
	ds_read_b128 v[226:229], v159 offset:39936
	global_load_lds_dwordx4 v128, s[0:1]
	s_mov_b32 m0, s44
	s_nop 0
	global_load_lds_dwordx4 v132, s[0:1]
	s_mov_b32 m0, s23
	s_nop 0
	global_load_lds_dwordx4 v[232:233], off
	s_mov_b32 m0, s42
	s_nop 0
	global_load_lds_dwordx4 v[234:235], off
	s_waitcnt vmcnt(8)
	s_waitcnt lgkmcnt(0)
	s_barrier
	s_setprio 1
	v_mfma_f32_16x16x32_bf16 v[124:127], v[162:165], v[198:201], v[124:127]
	v_mfma_f32_16x16x32_bf16 v[120:123], v[174:177], v[198:201], v[120:123]
	v_mfma_f32_16x16x32_bf16 v[112:115], v[162:165], v[206:209], v[112:115]
	v_mfma_f32_16x16x32_bf16 v[104:107], v[174:177], v[206:209], v[104:107]
	v_mfma_f32_16x16x32_bf16 v[96:99], v[162:165], v[214:217], v[96:99]
	v_mfma_f32_16x16x32_bf16 v[88:91], v[174:177], v[214:217], v[88:91]
	v_mfma_f32_16x16x32_bf16 v[80:83], v[162:165], v[222:225], v[80:83]
	v_mfma_f32_16x16x32_bf16 v[72:75], v[174:177], v[222:225], v[72:75]
	v_mfma_f32_16x16x32_bf16 v[124:127], v[170:173], v[202:205], v[124:127]
	v_mfma_f32_16x16x32_bf16 v[120:123], v[178:181], v[202:205], v[120:123]
	v_mfma_f32_16x16x32_bf16 v[112:115], v[170:173], v[210:213], v[112:115]
	v_mfma_f32_16x16x32_bf16 v[104:107], v[178:181], v[210:213], v[104:107]
	v_mfma_f32_16x16x32_bf16 v[96:99], v[170:173], v[218:221], v[96:99]
	v_mfma_f32_16x16x32_bf16 v[88:91], v[178:181], v[218:221], v[88:91]
	v_mfma_f32_16x16x32_bf16 v[80:83], v[170:173], v[226:229], v[80:83]
	v_mfma_f32_16x16x32_bf16 v[72:75], v[178:181], v[226:229], v[72:75]
	v_mfma_f32_16x16x32_bf16 v[116:119], v[182:185], v[198:201], v[116:119]
	v_mfma_f32_16x16x32_bf16 v[108:111], v[190:193], v[198:201], v[108:111]
	v_mfma_f32_16x16x32_bf16 v[100:103], v[182:185], v[206:209], v[100:103]
	v_mfma_f32_16x16x32_bf16 v[92:95], v[190:193], v[206:209], v[92:95]
	v_mfma_f32_16x16x32_bf16 v[84:87], v[182:185], v[214:217], v[84:87]
	v_mfma_f32_16x16x32_bf16 v[76:79], v[190:193], v[214:217], v[76:79]
	v_mfma_f32_16x16x32_bf16 v[68:71], v[182:185], v[222:225], v[68:71]
	v_mfma_f32_16x16x32_bf16 v[64:67], v[190:193], v[222:225], v[64:67]
	v_mfma_f32_16x16x32_bf16 v[116:119], v[186:189], v[202:205], v[116:119]
	v_mfma_f32_16x16x32_bf16 v[108:111], v[194:197], v[202:205], v[108:111]
	v_mfma_f32_16x16x32_bf16 v[100:103], v[186:189], v[210:213], v[100:103]
	v_mfma_f32_16x16x32_bf16 v[92:95], v[194:197], v[210:213], v[92:95]
	v_mfma_f32_16x16x32_bf16 v[84:87], v[186:189], v[218:221], v[84:87]
	v_mfma_f32_16x16x32_bf16 v[76:79], v[194:197], v[218:221], v[76:79]
	v_mfma_f32_16x16x32_bf16 v[68:71], v[186:189], v[226:229], v[68:71]
	v_mfma_f32_16x16x32_bf16 v[64:67], v[194:197], v[226:229], v[64:67]
	s_setprio 0
	s_barrier
	s_add_i32 s0, s24, s41
	v_lshl_add_u64 v[166:167], v[166:167], 0, s[8:9]
	s_mov_b32 m0, s0
	ds_read_b128 v[198:201], v159 offset:49152
	ds_read_b128 v[202:205], v159 offset:50176
	ds_read_b128 v[206:209], v159 offset:51200
	ds_read_b128 v[210:213], v159 offset:52224
	ds_read_b128 v[214:217], v159 offset:53248
	ds_read_b128 v[218:221], v159 offset:54272
	ds_read_b128 v[222:225], v159 offset:55296
	ds_read_b128 v[226:229], v159 offset:56320
	global_load_lds_dwordx4 v[166:167], off
	s_add_i32 m0, s0, 0x2000
	s_add_u32 s0, s28, 0x40080
	v_lshl_add_u64 v[166:167], v[230:231], 0, s[8:9]
	s_addc_u32 s1, s29, 0
	s_add_i32 s24, s25, s41
	global_load_lds_dwordx4 v[166:167], off
	s_mov_b32 m0, s24
	s_nop 0
	global_load_lds_dwordx4 v130, s[0:1]
	s_add_i32 m0, s24, 0x2000
	s_nop 0
	global_load_lds_dwordx4 v134, s[0:1]
	v_lshl_add_u64 v[166:167], v[232:233], 0, s[8:9]
	s_mov_b32 m0, s47
	s_nop 0
	global_load_lds_dwordx4 v[166:167], off
	v_lshl_add_u64 v[166:167], v[234:235], 0, s[8:9]
	s_mov_b32 m0, s48
	s_nop 0
	global_load_lds_dwordx4 v[166:167], off
	s_waitcnt vmcnt(6)
	s_waitcnt lgkmcnt(0)
	s_barrier
	s_setprio 1
	v_mfma_f32_16x16x32_bf16 v[60:63], v[162:165], v[198:201], v[60:63]
	v_mfma_f32_16x16x32_bf16 v[56:59], v[174:177], v[198:201], v[56:59]
	v_mfma_f32_16x16x32_bf16 v[48:51], v[162:165], v[206:209], v[48:51]
	v_mfma_f32_16x16x32_bf16 v[40:43], v[174:177], v[206:209], v[40:43]
	v_mfma_f32_16x16x32_bf16 v[32:35], v[162:165], v[214:217], v[32:35]
	v_mfma_f32_16x16x32_bf16 v[24:27], v[174:177], v[214:217], v[24:27]
	v_mfma_f32_16x16x32_bf16 v[16:19], v[162:165], v[222:225], v[16:19]
	v_mfma_f32_16x16x32_bf16 v[8:11], v[174:177], v[222:225], v[8:11]
	v_mfma_f32_16x16x32_bf16 v[60:63], v[170:173], v[202:205], v[60:63]
	v_mfma_f32_16x16x32_bf16 v[56:59], v[178:181], v[202:205], v[56:59]
	v_mfma_f32_16x16x32_bf16 v[48:51], v[170:173], v[210:213], v[48:51]
	v_mfma_f32_16x16x32_bf16 v[40:43], v[178:181], v[210:213], v[40:43]
	v_mfma_f32_16x16x32_bf16 v[32:35], v[170:173], v[218:221], v[32:35]
	v_mfma_f32_16x16x32_bf16 v[24:27], v[178:181], v[218:221], v[24:27]
	v_mfma_f32_16x16x32_bf16 v[16:19], v[170:173], v[226:229], v[16:19]
	v_mfma_f32_16x16x32_bf16 v[8:11], v[178:181], v[226:229], v[8:11]
	v_mfma_f32_16x16x32_bf16 v[52:55], v[182:185], v[198:201], v[52:55]
	v_mfma_f32_16x16x32_bf16 v[44:47], v[190:193], v[198:201], v[44:47]
	v_mfma_f32_16x16x32_bf16 v[36:39], v[182:185], v[206:209], v[36:39]
	v_mfma_f32_16x16x32_bf16 v[28:31], v[190:193], v[206:209], v[28:31]
	v_mfma_f32_16x16x32_bf16 v[20:23], v[182:185], v[214:217], v[20:23]
	v_mfma_f32_16x16x32_bf16 v[12:15], v[190:193], v[214:217], v[12:15]
	v_mfma_f32_16x16x32_bf16 v[4:7], v[182:185], v[222:225], v[4:7]
	v_mfma_f32_16x16x32_bf16 v[0:3], v[190:193], v[222:225], v[0:3]
	v_mfma_f32_16x16x32_bf16 v[52:55], v[186:189], v[202:205], v[52:55]
	v_mfma_f32_16x16x32_bf16 v[44:47], v[194:197], v[202:205], v[44:47]
	v_mfma_f32_16x16x32_bf16 v[36:39], v[186:189], v[210:213], v[36:39]
	v_mfma_f32_16x16x32_bf16 v[28:31], v[194:197], v[210:213], v[28:31]
	v_mfma_f32_16x16x32_bf16 v[20:23], v[186:189], v[218:221], v[20:23]
	v_mfma_f32_16x16x32_bf16 v[12:15], v[194:197], v[218:221], v[12:15]
	v_mfma_f32_16x16x32_bf16 v[4:7], v[186:189], v[226:229], v[4:7]
	v_mfma_f32_16x16x32_bf16 v[0:3], v[194:197], v[226:229], v[0:3]
	s_setprio 0
	s_barrier
	s_add_i32 s59, s59, 2
	s_add_u32 s57, s57, 0x100
	s_addc_u32 s58, s58, 0
	s_cmp_gt_u32 s59, 13
	s_mov_b64 s[24:25], s[26:27]
.LBB0_187:
	ds_read_b128 v[162:165], v157
	ds_read_b128 v[170:173], v157 offset:1024
	ds_read_b128 v[174:177], v157 offset:2048
	ds_read_b128 v[178:181], v157 offset:3072
	ds_read_b128 v[182:185], v158
	ds_read_b128 v[186:189], v158 offset:1024
	ds_read_b128 v[190:193], v158 offset:2048
	ds_read_b128 v[194:197], v158 offset:3072
	s_add_u32 s26, s24, 0x100
	s_addc_u32 s27, s25, 0
	s_cmp_eq_u32 s59, 12
	s_cselect_b32 s31, s17, s27
	s_cselect_b32 s30, s55, s26
	s_cselect_b32 s29, s15, s58
	s_cselect_b32 s28, s56, s57
	s_add_i32 m0, s23, 0xc000
	ds_read_b128 v[198:201], v159
	ds_read_b128 v[202:205], v159 offset:1024
	ds_read_b128 v[206:209], v159 offset:2048
	ds_read_b128 v[210:213], v159 offset:3072
	ds_read_b128 v[214:217], v159 offset:4096
	ds_read_b128 v[218:221], v159 offset:5120
	ds_read_b128 v[222:225], v159 offset:6144
	ds_read_b128 v[226:229], v159 offset:7168
	global_load_lds_dwordx4 v142, s[24:25]
	s_add_i32 m0, s23, 0xe000
	s_nop 0
	global_load_lds_dwordx4 v144, s[24:25]
	s_waitcnt vmcnt(8)
	s_waitcnt lgkmcnt(0)
	s_barrier
	s_setprio 1
	v_mfma_f32_16x16x32_bf16 v[124:127], v[162:165], v[198:201], v[124:127]
	v_mfma_f32_16x16x32_bf16 v[120:123], v[174:177], v[198:201], v[120:123]
	v_mfma_f32_16x16x32_bf16 v[112:115], v[162:165], v[206:209], v[112:115]
	v_mfma_f32_16x16x32_bf16 v[104:107], v[174:177], v[206:209], v[104:107]
	v_mfma_f32_16x16x32_bf16 v[96:99], v[162:165], v[214:217], v[96:99]
	v_mfma_f32_16x16x32_bf16 v[88:91], v[174:177], v[214:217], v[88:91]
	v_mfma_f32_16x16x32_bf16 v[80:83], v[162:165], v[222:225], v[80:83]
	v_mfma_f32_16x16x32_bf16 v[72:75], v[174:177], v[222:225], v[72:75]
	v_mfma_f32_16x16x32_bf16 v[124:127], v[170:173], v[202:205], v[124:127]
	v_mfma_f32_16x16x32_bf16 v[120:123], v[178:181], v[202:205], v[120:123]
	v_mfma_f32_16x16x32_bf16 v[112:115], v[170:173], v[210:213], v[112:115]
	v_mfma_f32_16x16x32_bf16 v[104:107], v[178:181], v[210:213], v[104:107]
	v_mfma_f32_16x16x32_bf16 v[96:99], v[170:173], v[218:221], v[96:99]
	v_mfma_f32_16x16x32_bf16 v[88:91], v[178:181], v[218:221], v[88:91]
	v_mfma_f32_16x16x32_bf16 v[80:83], v[170:173], v[226:229], v[80:83]
	v_mfma_f32_16x16x32_bf16 v[72:75], v[178:181], v[226:229], v[72:75]
	v_mfma_f32_16x16x32_bf16 v[116:119], v[182:185], v[198:201], v[116:119]
	v_mfma_f32_16x16x32_bf16 v[108:111], v[190:193], v[198:201], v[108:111]
	v_mfma_f32_16x16x32_bf16 v[100:103], v[182:185], v[206:209], v[100:103]
	v_mfma_f32_16x16x32_bf16 v[92:95], v[190:193], v[206:209], v[92:95]
	v_mfma_f32_16x16x32_bf16 v[84:87], v[182:185], v[214:217], v[84:87]
	v_mfma_f32_16x16x32_bf16 v[76:79], v[190:193], v[214:217], v[76:79]
	v_mfma_f32_16x16x32_bf16 v[68:71], v[182:185], v[222:225], v[68:71]
	v_mfma_f32_16x16x32_bf16 v[64:67], v[190:193], v[222:225], v[64:67]
	v_mfma_f32_16x16x32_bf16 v[116:119], v[186:189], v[202:205], v[116:119]
	v_mfma_f32_16x16x32_bf16 v[108:111], v[194:197], v[202:205], v[108:111]
	v_mfma_f32_16x16x32_bf16 v[100:103], v[186:189], v[210:213], v[100:103]
	v_mfma_f32_16x16x32_bf16 v[92:95], v[194:197], v[210:213], v[92:95]
	v_mfma_f32_16x16x32_bf16 v[84:87], v[186:189], v[218:221], v[84:87]
	v_mfma_f32_16x16x32_bf16 v[76:79], v[194:197], v[218:221], v[76:79]
	v_mfma_f32_16x16x32_bf16 v[68:71], v[186:189], v[226:229], v[68:71]
	v_mfma_f32_16x16x32_bf16 v[64:67], v[194:197], v[226:229], v[64:67]
	s_setprio 0
	s_barrier
	s_add_i32 s0, s51, s41
	v_lshl_add_u64 v[166:167], s[28:29], 0, v[130:131]
	s_mov_b32 m0, s0
	ds_read_b128 v[198:201], v159 offset:16384
	ds_read_b128 v[202:205], v159 offset:17408
	ds_read_b128 v[206:209], v159 offset:18432
	ds_read_b128 v[210:213], v159 offset:19456
	ds_read_b128 v[214:217], v159 offset:20480
	ds_read_b128 v[218:221], v159 offset:21504
	ds_read_b128 v[222:225], v159 offset:22528
	ds_read_b128 v[226:229], v159 offset:23552
	global_load_lds_dwordx4 v[166:167], off
	s_add_i32 m0, s0, 0x2000
	s_add_u32 s0, s28, 0x40000
	v_lshl_add_u64 v[230:231], s[28:29], 0, v[134:135]
	s_addc_u32 s1, s29, 0
	s_add_i32 s24, s52, s41
	global_load_lds_dwordx4 v[230:231], off
	s_mov_b32 m0, s24
	v_lshl_add_u64 v[234:235], s[30:31], 0, v[132:133]
	global_load_lds_dwordx4 v130, s[0:1]
	s_add_i32 m0, s24, 0x2000
	s_nop 0
	global_load_lds_dwordx4 v134, s[0:1]
	v_lshl_add_u64 v[232:233], s[30:31], 0, v[128:129]
	s_waitcnt vmcnt(6)
	s_waitcnt lgkmcnt(0)
	s_barrier
	s_setprio 1
	v_mfma_f32_16x16x32_bf16 v[60:63], v[162:165], v[198:201], v[60:63]
	v_mfma_f32_16x16x32_bf16 v[56:59], v[174:177], v[198:201], v[56:59]
	v_mfma_f32_16x16x32_bf16 v[48:51], v[162:165], v[206:209], v[48:51]
	v_mfma_f32_16x16x32_bf16 v[40:43], v[174:177], v[206:209], v[40:43]
	v_mfma_f32_16x16x32_bf16 v[32:35], v[162:165], v[214:217], v[32:35]
	v_mfma_f32_16x16x32_bf16 v[24:27], v[174:177], v[214:217], v[24:27]
	v_mfma_f32_16x16x32_bf16 v[16:19], v[162:165], v[222:225], v[16:19]
	v_mfma_f32_16x16x32_bf16 v[8:11], v[174:177], v[222:225], v[8:11]
	v_mfma_f32_16x16x32_bf16 v[60:63], v[170:173], v[202:205], v[60:63]
	v_mfma_f32_16x16x32_bf16 v[56:59], v[178:181], v[202:205], v[56:59]
	v_mfma_f32_16x16x32_bf16 v[48:51], v[170:173], v[210:213], v[48:51]
	v_mfma_f32_16x16x32_bf16 v[40:43], v[178:181], v[210:213], v[40:43]
	v_mfma_f32_16x16x32_bf16 v[32:35], v[170:173], v[218:221], v[32:35]
	v_mfma_f32_16x16x32_bf16 v[24:27], v[178:181], v[218:221], v[24:27]
	v_mfma_f32_16x16x32_bf16 v[16:19], v[170:173], v[226:229], v[16:19]
	v_mfma_f32_16x16x32_bf16 v[8:11], v[178:181], v[226:229], v[8:11]
	v_mfma_f32_16x16x32_bf16 v[52:55], v[182:185], v[198:201], v[52:55]
	v_mfma_f32_16x16x32_bf16 v[44:47], v[190:193], v[198:201], v[44:47]
	v_mfma_f32_16x16x32_bf16 v[36:39], v[182:185], v[206:209], v[36:39]
	v_mfma_f32_16x16x32_bf16 v[28:31], v[190:193], v[206:209], v[28:31]
	v_mfma_f32_16x16x32_bf16 v[20:23], v[182:185], v[214:217], v[20:23]
	v_mfma_f32_16x16x32_bf16 v[12:15], v[190:193], v[214:217], v[12:15]
	v_mfma_f32_16x16x32_bf16 v[4:7], v[182:185], v[222:225], v[4:7]
	v_mfma_f32_16x16x32_bf16 v[0:3], v[190:193], v[222:225], v[0:3]
	v_mfma_f32_16x16x32_bf16 v[52:55], v[186:189], v[202:205], v[52:55]
	v_mfma_f32_16x16x32_bf16 v[44:47], v[194:197], v[202:205], v[44:47]
	v_mfma_f32_16x16x32_bf16 v[36:39], v[186:189], v[210:213], v[36:39]
	v_mfma_f32_16x16x32_bf16 v[28:31], v[194:197], v[210:213], v[28:31]
	v_mfma_f32_16x16x32_bf16 v[20:23], v[186:189], v[218:221], v[20:23]
	v_mfma_f32_16x16x32_bf16 v[12:15], v[194:197], v[218:221], v[12:15]
	v_mfma_f32_16x16x32_bf16 v[4:7], v[186:189], v[226:229], v[4:7]
	v_mfma_f32_16x16x32_bf16 v[0:3], v[194:197], v[226:229], v[0:3]
	s_setprio 0
	s_barrier
	s_add_i32 s24, 0, 0x18000
	v_add_u32_e32 v150, s24, v153
	s_add_i32 s25, 0, 0x1c000
	ds_read_b128 v[162:165], v150
	ds_read_b128 v[170:173], v150 offset:1024
	ds_read_b128 v[174:177], v150 offset:2048
	ds_read_b128 v[178:181], v150 offset:3072
	v_add_u32_e32 v150, s25, v153
	ds_read_b128 v[182:185], v150
	ds_read_b128 v[186:189], v150 offset:1024
	ds_read_b128 v[190:193], v150 offset:2048
	ds_read_b128 v[194:197], v150 offset:3072
	s_add_u32 s0, s30, 0x40000
	s_addc_u32 s1, s31, 0
	s_mov_b32 m0, s43
	ds_read_b128 v[198:201], v159 offset:32768
	ds_read_b128 v[202:205], v159 offset:33792
	ds_read_b128 v[206:209], v159 offset:34816
	ds_read_b128 v[210:213], v159 offset:35840
	ds_read_b128 v[214:217], v159 offset:36864
	ds_read_b128 v[218:221], v159 offset:37888
	ds_read_b128 v[222:225], v159 offset:38912
	ds_read_b128 v[226:229], v159 offset:39936
	global_load_lds_dwordx4 v128, s[0:1]
	s_mov_b32 m0, s44
	s_nop 0
	global_load_lds_dwordx4 v132, s[0:1]
	s_mov_b32 m0, s23
	s_nop 0
	global_load_lds_dwordx4 v[232:233], off
	s_mov_b32 m0, s42
	s_nop 0
	global_load_lds_dwordx4 v[234:235], off
	s_waitcnt vmcnt(8)
	s_waitcnt lgkmcnt(0)
	s_barrier
	s_setprio 1
	v_mfma_f32_16x16x32_bf16 v[124:127], v[162:165], v[198:201], v[124:127]
	v_mfma_f32_16x16x32_bf16 v[120:123], v[174:177], v[198:201], v[120:123]
	v_mfma_f32_16x16x32_bf16 v[112:115], v[162:165], v[206:209], v[112:115]
	v_mfma_f32_16x16x32_bf16 v[104:107], v[174:177], v[206:209], v[104:107]
	v_mfma_f32_16x16x32_bf16 v[96:99], v[162:165], v[214:217], v[96:99]
	v_mfma_f32_16x16x32_bf16 v[88:91], v[174:177], v[214:217], v[88:91]
	v_mfma_f32_16x16x32_bf16 v[80:83], v[162:165], v[222:225], v[80:83]
	v_mfma_f32_16x16x32_bf16 v[72:75], v[174:177], v[222:225], v[72:75]
	v_mfma_f32_16x16x32_bf16 v[124:127], v[170:173], v[202:205], v[124:127]
	v_mfma_f32_16x16x32_bf16 v[120:123], v[178:181], v[202:205], v[120:123]
	v_mfma_f32_16x16x32_bf16 v[112:115], v[170:173], v[210:213], v[112:115]
	v_mfma_f32_16x16x32_bf16 v[104:107], v[178:181], v[210:213], v[104:107]
	v_mfma_f32_16x16x32_bf16 v[96:99], v[170:173], v[218:221], v[96:99]
	v_mfma_f32_16x16x32_bf16 v[88:91], v[178:181], v[218:221], v[88:91]
	v_mfma_f32_16x16x32_bf16 v[80:83], v[170:173], v[226:229], v[80:83]
	v_mfma_f32_16x16x32_bf16 v[72:75], v[178:181], v[226:229], v[72:75]
	v_mfma_f32_16x16x32_bf16 v[116:119], v[182:185], v[198:201], v[116:119]
	v_mfma_f32_16x16x32_bf16 v[108:111], v[190:193], v[198:201], v[108:111]
	v_mfma_f32_16x16x32_bf16 v[100:103], v[182:185], v[206:209], v[100:103]
	v_mfma_f32_16x16x32_bf16 v[92:95], v[190:193], v[206:209], v[92:95]
	v_mfma_f32_16x16x32_bf16 v[84:87], v[182:185], v[214:217], v[84:87]
	v_mfma_f32_16x16x32_bf16 v[76:79], v[190:193], v[214:217], v[76:79]
	v_mfma_f32_16x16x32_bf16 v[68:71], v[182:185], v[222:225], v[68:71]
	v_mfma_f32_16x16x32_bf16 v[64:67], v[190:193], v[222:225], v[64:67]
	v_mfma_f32_16x16x32_bf16 v[116:119], v[186:189], v[202:205], v[116:119]
	v_mfma_f32_16x16x32_bf16 v[108:111], v[194:197], v[202:205], v[108:111]
	v_mfma_f32_16x16x32_bf16 v[100:103], v[186:189], v[210:213], v[100:103]
	v_mfma_f32_16x16x32_bf16 v[92:95], v[194:197], v[210:213], v[92:95]
	v_mfma_f32_16x16x32_bf16 v[84:87], v[186:189], v[218:221], v[84:87]
	v_mfma_f32_16x16x32_bf16 v[76:79], v[194:197], v[218:221], v[76:79]
	v_mfma_f32_16x16x32_bf16 v[68:71], v[186:189], v[226:229], v[68:71]
	v_mfma_f32_16x16x32_bf16 v[64:67], v[194:197], v[226:229], v[64:67]
	s_setprio 0
	s_barrier
	s_add_i32 s0, s24, s41
	v_lshl_add_u64 v[166:167], v[166:167], 0, s[8:9]
	s_mov_b32 m0, s0
	ds_read_b128 v[198:201], v159 offset:49152
	ds_read_b128 v[202:205], v159 offset:50176
	ds_read_b128 v[206:209], v159 offset:51200
	ds_read_b128 v[210:213], v159 offset:52224
	ds_read_b128 v[214:217], v159 offset:53248
	ds_read_b128 v[218:221], v159 offset:54272
	ds_read_b128 v[222:225], v159 offset:55296
	ds_read_b128 v[226:229], v159 offset:56320
	global_load_lds_dwordx4 v[166:167], off
	s_add_i32 m0, s0, 0x2000
	s_add_u32 s0, s28, 0x40080
	v_lshl_add_u64 v[166:167], v[230:231], 0, s[8:9]
	s_addc_u32 s1, s29, 0
	s_add_i32 s24, s25, s41
	global_load_lds_dwordx4 v[166:167], off
	s_mov_b32 m0, s24
	s_nop 0
	global_load_lds_dwordx4 v130, s[0:1]
	s_add_i32 m0, s24, 0x2000
	s_nop 0
	global_load_lds_dwordx4 v134, s[0:1]
	v_lshl_add_u64 v[166:167], v[232:233], 0, s[8:9]
	s_mov_b32 m0, s47
	s_nop 0
	global_load_lds_dwordx4 v[166:167], off
	v_lshl_add_u64 v[166:167], v[234:235], 0, s[8:9]
	s_mov_b32 m0, s48
	s_nop 0
	global_load_lds_dwordx4 v[166:167], off
	s_waitcnt vmcnt(6)
	s_waitcnt lgkmcnt(0)
	s_barrier
	s_setprio 1
	v_mfma_f32_16x16x32_bf16 v[60:63], v[162:165], v[198:201], v[60:63]
	v_mfma_f32_16x16x32_bf16 v[56:59], v[174:177], v[198:201], v[56:59]
	v_mfma_f32_16x16x32_bf16 v[48:51], v[162:165], v[206:209], v[48:51]
	v_mfma_f32_16x16x32_bf16 v[40:43], v[174:177], v[206:209], v[40:43]
	v_mfma_f32_16x16x32_bf16 v[32:35], v[162:165], v[214:217], v[32:35]
	v_mfma_f32_16x16x32_bf16 v[24:27], v[174:177], v[214:217], v[24:27]
	v_mfma_f32_16x16x32_bf16 v[16:19], v[162:165], v[222:225], v[16:19]
	v_mfma_f32_16x16x32_bf16 v[8:11], v[174:177], v[222:225], v[8:11]
	v_mfma_f32_16x16x32_bf16 v[60:63], v[170:173], v[202:205], v[60:63]
	v_mfma_f32_16x16x32_bf16 v[56:59], v[178:181], v[202:205], v[56:59]
	v_mfma_f32_16x16x32_bf16 v[48:51], v[170:173], v[210:213], v[48:51]
	v_mfma_f32_16x16x32_bf16 v[40:43], v[178:181], v[210:213], v[40:43]
	v_mfma_f32_16x16x32_bf16 v[32:35], v[170:173], v[218:221], v[32:35]
	v_mfma_f32_16x16x32_bf16 v[24:27], v[178:181], v[218:221], v[24:27]
	v_mfma_f32_16x16x32_bf16 v[16:19], v[170:173], v[226:229], v[16:19]
	v_mfma_f32_16x16x32_bf16 v[8:11], v[178:181], v[226:229], v[8:11]
	v_mfma_f32_16x16x32_bf16 v[52:55], v[182:185], v[198:201], v[52:55]
	v_mfma_f32_16x16x32_bf16 v[44:47], v[190:193], v[198:201], v[44:47]
	v_mfma_f32_16x16x32_bf16 v[36:39], v[182:185], v[206:209], v[36:39]
	v_mfma_f32_16x16x32_bf16 v[28:31], v[190:193], v[206:209], v[28:31]
	v_mfma_f32_16x16x32_bf16 v[20:23], v[182:185], v[214:217], v[20:23]
	v_mfma_f32_16x16x32_bf16 v[12:15], v[190:193], v[214:217], v[12:15]
	v_mfma_f32_16x16x32_bf16 v[4:7], v[182:185], v[222:225], v[4:7]
	v_mfma_f32_16x16x32_bf16 v[0:3], v[190:193], v[222:225], v[0:3]
	v_mfma_f32_16x16x32_bf16 v[52:55], v[186:189], v[202:205], v[52:55]
	v_mfma_f32_16x16x32_bf16 v[44:47], v[194:197], v[202:205], v[44:47]
	v_mfma_f32_16x16x32_bf16 v[36:39], v[186:189], v[210:213], v[36:39]
	v_mfma_f32_16x16x32_bf16 v[28:31], v[194:197], v[210:213], v[28:31]
	v_mfma_f32_16x16x32_bf16 v[20:23], v[186:189], v[218:221], v[20:23]
	v_mfma_f32_16x16x32_bf16 v[12:15], v[194:197], v[218:221], v[12:15]
	v_mfma_f32_16x16x32_bf16 v[4:7], v[186:189], v[226:229], v[4:7]
	v_mfma_f32_16x16x32_bf16 v[0:3], v[194:197], v[226:229], v[0:3]
	s_setprio 0
	s_barrier
	s_add_i32 s59, s59, 2
	s_add_u32 s57, s57, 0x100
	s_addc_u32 s58, s58, 0
	s_cmp_gt_u32 s59, 13
	s_mov_b64 s[24:25], s[26:27]
	s_cbranch_scc0 .LBB0_187
	s_and_b64 vcc, exec, s[12:13]
	s_cbranch_vccz .LBB0_190
	s_barrier

.Lrestag_265:
	ds_read_b128 v[86:89], v84
	ds_read_b128 v[90:93], v84 offset:1024
	ds_read_b128 v[94:97], v84 offset:2048
	ds_read_b128 v[98:101], v84 offset:3072
	s_add_u32 s6, s20, 0x100
	s_addc_u32 s7, s21, 0
	s_cmp_eq_u32 s53, 4
	s_cselect_b32 s25, s17, s7
	s_cselect_b32 s24, s16, s6
	s_cselect_b32 s23, s15, s52
	s_cselect_b32 s22, s50, s51
	s_add_i32 m0, s34, 0xc000
	ds_read_b128 v[102:105], v85
	ds_read_b128 v[106:109], v85 offset:1024
	ds_read_b128 v[110:113], v85 offset:2048
	ds_read_b128 v[114:117], v85 offset:3072
	ds_read_b128 v[118:121], v85 offset:4096
	ds_read_b128 v[122:125], v85 offset:5120
	ds_read_b128 v[126:129], v85 offset:6144
	ds_read_b128 v[130:133], v85 offset:7168
	global_load_lds_dwordx4 v74, s[20:21]
	s_add_i32 m0, s34, 0xe000
	s_nop 0
	global_load_lds_dwordx4 v76, s[20:21]
	s_waitcnt vmcnt(8)
	s_waitcnt lgkmcnt(0)
	s_barrier
	s_setprio 1
	v_mfma_f32_16x16x32_bf16 v[60:63], v[86:89], v[102:105], 0
	v_mfma_f32_16x16x32_bf16 v[56:59], v[94:97], v[102:105], 0
	v_mfma_f32_16x16x32_bf16 v[52:55], v[86:89], v[110:113], 0
	v_mfma_f32_16x16x32_bf16 v[48:51], v[94:97], v[110:113], 0
	v_mfma_f32_16x16x32_bf16 v[44:47], v[86:89], v[118:121], 0
	v_mfma_f32_16x16x32_bf16 v[40:43], v[94:97], v[118:121], 0
	v_mfma_f32_16x16x32_bf16 v[36:39], v[86:89], v[126:129], 0
	v_mfma_f32_16x16x32_bf16 v[32:35], v[94:97], v[126:129], 0
	v_mfma_f32_16x16x32_bf16 v[60:63], v[90:93], v[106:109], v[60:63]
	v_mfma_f32_16x16x32_bf16 v[56:59], v[98:101], v[106:109], v[56:59]
	v_mfma_f32_16x16x32_bf16 v[52:55], v[90:93], v[114:117], v[52:55]
	v_mfma_f32_16x16x32_bf16 v[48:51], v[98:101], v[114:117], v[48:51]
	v_mfma_f32_16x16x32_bf16 v[44:47], v[90:93], v[122:125], v[44:47]
	v_mfma_f32_16x16x32_bf16 v[40:43], v[98:101], v[122:125], v[40:43]
	v_mfma_f32_16x16x32_bf16 v[36:39], v[90:93], v[130:133], v[36:39]
	v_mfma_f32_16x16x32_bf16 v[32:35], v[98:101], v[130:133], v[32:35]
	s_setprio 0
	s_setprio 1
	s_setprio 0
	s_barrier
	s_add_i32 s20, s48, s33
	v_lshl_add_u64 v[134:135], s[22:23], 0, v[66:67]
	s_mov_b32 m0, s20
	ds_read_b128 v[102:105], v85 offset:16384
	ds_read_b128 v[106:109], v85 offset:17408
	ds_read_b128 v[110:113], v85 offset:18432
	ds_read_b128 v[114:117], v85 offset:19456
	ds_read_b128 v[118:121], v85 offset:20480
	ds_read_b128 v[122:125], v85 offset:21504
	ds_read_b128 v[126:129], v85 offset:22528
	ds_read_b128 v[130:133], v85 offset:23552
	global_load_lds_dwordx4 v[134:135], off
	s_add_i32 m0, s20, 0x2000
	s_add_u32 s20, s22, 0x20000
	v_lshl_add_u64 v[136:137], s[22:23], 0, v[70:71]
	s_addc_u32 s21, s23, 0
	global_load_lds_dwordx4 v[136:137], off
	s_mov_b32 m0, s35
	v_lshl_add_u64 v[140:141], s[24:25], 0, v[68:69]
	global_load_lds_dwordx4 v66, s[20:21]
	s_mov_b32 m0, s36
	s_nop 0
	global_load_lds_dwordx4 v70, s[20:21]
	v_lshl_add_u64 v[138:139], s[24:25], 0, v[64:65]
	s_mov_b32 m0, s34
	s_nop 0
	global_load_lds_dwordx4 v[138:139], off
	s_mov_b32 m0, s0
	s_nop 0
	global_load_lds_dwordx4 v[140:141], off
	s_waitcnt vmcnt(8)
	s_waitcnt lgkmcnt(0)
	s_barrier
	s_setprio 1
	v_mfma_f32_16x16x32_bf16 v[28:31], v[86:89], v[102:105], 0
	v_mfma_f32_16x16x32_bf16 v[24:27], v[94:97], v[102:105], 0
	v_mfma_f32_16x16x32_bf16 v[20:23], v[86:89], v[110:113], 0
	v_mfma_f32_16x16x32_bf16 v[16:19], v[94:97], v[110:113], 0
	v_mfma_f32_16x16x32_bf16 v[12:15], v[86:89], v[118:121], 0
	v_mfma_f32_16x16x32_bf16 v[8:11], v[94:97], v[118:121], 0
	v_mfma_f32_16x16x32_bf16 v[4:7], v[86:89], v[126:129], 0
	v_mfma_f32_16x16x32_bf16 v[0:3], v[94:97], v[126:129], 0
	v_mfma_f32_16x16x32_bf16 v[28:31], v[90:93], v[106:109], v[28:31]
	v_mfma_f32_16x16x32_bf16 v[24:27], v[98:101], v[106:109], v[24:27]
	v_mfma_f32_16x16x32_bf16 v[20:23], v[90:93], v[114:117], v[20:23]
	v_mfma_f32_16x16x32_bf16 v[16:19], v[98:101], v[114:117], v[16:19]
	v_mfma_f32_16x16x32_bf16 v[12:15], v[90:93], v[122:125], v[12:15]
	v_mfma_f32_16x16x32_bf16 v[8:11], v[98:101], v[122:125], v[8:11]
	v_mfma_f32_16x16x32_bf16 v[4:7], v[90:93], v[130:133], v[4:7]
	v_mfma_f32_16x16x32_bf16 v[0:3], v[98:101], v[130:133], v[0:3]
	s_setprio 0
	s_setprio 1
	s_setprio 0
	s_barrier
	s_add_i32 s54, 0, 0x18000
	v_add_u32_e32 v98, s54, v83
	ds_read_b128 v[86:89], v98
	ds_read_b128 v[90:93], v98 offset:1024
	ds_read_b128 v[94:97], v98 offset:2048
	ds_read_b128 v[98:101], v98 offset:3072
	s_add_u32 s20, s24, 0x28000
	s_addc_u32 s21, s25, 0
	s_mov_b32 m0, s1
	ds_read_b128 v[102:105], v85 offset:32768
	ds_read_b128 v[106:109], v85 offset:33792
	ds_read_b128 v[110:113], v85 offset:34816
	ds_read_b128 v[114:117], v85 offset:35840
	ds_read_b128 v[118:121], v85 offset:36864
	ds_read_b128 v[122:125], v85 offset:37888
	ds_read_b128 v[126:129], v85 offset:38912
	ds_read_b128 v[130:133], v85 offset:39936
	global_load_lds_dwordx4 v64, s[20:21]
	s_mov_b32 m0, s37
	s_nop 0
	global_load_lds_dwordx4 v68, s[20:21]
	s_waitcnt vmcnt(8)
	s_waitcnt lgkmcnt(0)
	s_barrier
	s_setprio 1
	v_mfma_f32_16x16x32_bf16 v[60:63], v[86:89], v[102:105], v[60:63]
	v_mfma_f32_16x16x32_bf16 v[56:59], v[94:97], v[102:105], v[56:59]
	v_mfma_f32_16x16x32_bf16 v[52:55], v[86:89], v[110:113], v[52:55]
	v_mfma_f32_16x16x32_bf16 v[48:51], v[94:97], v[110:113], v[48:51]
	v_mfma_f32_16x16x32_bf16 v[44:47], v[86:89], v[118:121], v[44:47]
	v_mfma_f32_16x16x32_bf16 v[40:43], v[94:97], v[118:121], v[40:43]
	v_mfma_f32_16x16x32_bf16 v[36:39], v[86:89], v[126:129], v[36:39]
	v_mfma_f32_16x16x32_bf16 v[32:35], v[94:97], v[126:129], v[32:35]
	v_mfma_f32_16x16x32_bf16 v[60:63], v[90:93], v[106:109], v[60:63]
	v_mfma_f32_16x16x32_bf16 v[56:59], v[98:101], v[106:109], v[56:59]
	v_mfma_f32_16x16x32_bf16 v[52:55], v[90:93], v[114:117], v[52:55]
	v_mfma_f32_16x16x32_bf16 v[48:51], v[98:101], v[114:117], v[48:51]
	v_mfma_f32_16x16x32_bf16 v[44:47], v[90:93], v[122:125], v[44:47]
	v_mfma_f32_16x16x32_bf16 v[40:43], v[98:101], v[122:125], v[40:43]
	v_mfma_f32_16x16x32_bf16 v[36:39], v[90:93], v[130:133], v[36:39]
	v_mfma_f32_16x16x32_bf16 v[32:35], v[98:101], v[130:133], v[32:35]
	s_setprio 0
	s_setprio 1
	s_setprio 0
	s_barrier
	s_add_i32 s20, s54, s33
	v_lshl_add_u64 v[134:135], v[134:135], 0, s[8:9]
	s_mov_b32 m0, s20
	ds_read_b128 v[102:105], v85 offset:49152
	ds_read_b128 v[106:109], v85 offset:50176
	ds_read_b128 v[110:113], v85 offset:51200
	ds_read_b128 v[114:117], v85 offset:52224
	ds_read_b128 v[118:121], v85 offset:53248
	ds_read_b128 v[122:125], v85 offset:54272
	ds_read_b128 v[126:129], v85 offset:55296
	ds_read_b128 v[130:133], v85 offset:56320
	global_load_lds_dwordx4 v[134:135], off
	s_add_i32 m0, s20, 0x2000
	s_add_u32 s20, s22, 0x20080
	v_lshl_add_u64 v[134:135], v[136:137], 0, s[8:9]
	s_addc_u32 s21, s23, 0
	global_load_lds_dwordx4 v[134:135], off
	s_mov_b32 m0, s44
	s_nop 0
	global_load_lds_dwordx4 v66, s[20:21]
	s_mov_b32 m0, s45
	s_nop 0
	global_load_lds_dwordx4 v70, s[20:21]
	v_lshl_add_u64 v[134:135], v[138:139], 0, s[8:9]
	s_mov_b32 m0, s42
	s_nop 0
	global_load_lds_dwordx4 v[134:135], off
	v_lshl_add_u64 v[134:135], v[140:141], 0, s[8:9]
	s_mov_b32 m0, s43
	s_nop 0
	global_load_lds_dwordx4 v[134:135], off
	s_waitcnt vmcnt(8)
	s_waitcnt lgkmcnt(0)
	s_barrier
	s_setprio 1
	v_mfma_f32_16x16x32_bf16 v[28:31], v[86:89], v[102:105], v[28:31]
	v_mfma_f32_16x16x32_bf16 v[24:27], v[94:97], v[102:105], v[24:27]
	v_mfma_f32_16x16x32_bf16 v[20:23], v[86:89], v[110:113], v[20:23]
	v_mfma_f32_16x16x32_bf16 v[16:19], v[94:97], v[110:113], v[16:19]
	v_mfma_f32_16x16x32_bf16 v[12:15], v[86:89], v[118:121], v[12:15]
	v_mfma_f32_16x16x32_bf16 v[8:11], v[94:97], v[118:121], v[8:11]
	v_mfma_f32_16x16x32_bf16 v[4:7], v[86:89], v[126:129], v[4:7]
	v_mfma_f32_16x16x32_bf16 v[0:3], v[94:97], v[126:129], v[0:3]
	v_mfma_f32_16x16x32_bf16 v[28:31], v[90:93], v[106:109], v[28:31]
	v_mfma_f32_16x16x32_bf16 v[24:27], v[98:101], v[106:109], v[24:27]
	v_mfma_f32_16x16x32_bf16 v[20:23], v[90:93], v[114:117], v[20:23]
	v_mfma_f32_16x16x32_bf16 v[16:19], v[98:101], v[114:117], v[16:19]
	v_mfma_f32_16x16x32_bf16 v[12:15], v[90:93], v[122:125], v[12:15]
	v_mfma_f32_16x16x32_bf16 v[8:11], v[98:101], v[122:125], v[8:11]
	v_mfma_f32_16x16x32_bf16 v[4:7], v[90:93], v[130:133], v[4:7]
	v_mfma_f32_16x16x32_bf16 v[0:3], v[98:101], v[130:133], v[0:3]
	s_setprio 0
	s_setprio 1
	s_setprio 0
	s_barrier
	s_add_i32 s53, s53, 2
	s_add_u32 s51, s51, 0x100
	s_addc_u32 s52, s52, 0
	s_cmp_gt_u32 s53, 5
	s_mov_b64 s[20:21], s[6:7]
.LBB0_265:
	ds_read_b128 v[86:89], v84
	ds_read_b128 v[90:93], v84 offset:1024
	ds_read_b128 v[94:97], v84 offset:2048
	ds_read_b128 v[98:101], v84 offset:3072
	s_add_u32 s6, s20, 0x100
	s_addc_u32 s7, s21, 0
	s_cmp_eq_u32 s53, 4
	s_cselect_b32 s25, s17, s7
	s_cselect_b32 s24, s16, s6
	s_cselect_b32 s23, s15, s52
	s_cselect_b32 s22, s50, s51
	s_add_i32 m0, s34, 0xc000
	ds_read_b128 v[102:105], v85
	ds_read_b128 v[106:109], v85 offset:1024
	ds_read_b128 v[110:113], v85 offset:2048
	ds_read_b128 v[114:117], v85 offset:3072
	ds_read_b128 v[118:121], v85 offset:4096
	ds_read_b128 v[122:125], v85 offset:5120
	ds_read_b128 v[126:129], v85 offset:6144
	ds_read_b128 v[130:133], v85 offset:7168
	global_load_lds_dwordx4 v74, s[20:21]
	s_add_i32 m0, s34, 0xe000
	s_nop 0
	global_load_lds_dwordx4 v76, s[20:21]
	s_waitcnt vmcnt(8)
	s_waitcnt lgkmcnt(0)
	s_barrier
	s_setprio 1
	v_mfma_f32_16x16x32_bf16 v[60:63], v[86:89], v[102:105], v[60:63]
	v_mfma_f32_16x16x32_bf16 v[56:59], v[94:97], v[102:105], v[56:59]
	v_mfma_f32_16x16x32_bf16 v[52:55], v[86:89], v[110:113], v[52:55]
	v_mfma_f32_16x16x32_bf16 v[48:51], v[94:97], v[110:113], v[48:51]
	v_mfma_f32_16x16x32_bf16 v[44:47], v[86:89], v[118:121], v[44:47]
	v_mfma_f32_16x16x32_bf16 v[40:43], v[94:97], v[118:121], v[40:43]
	v_mfma_f32_16x16x32_bf16 v[36:39], v[86:89], v[126:129], v[36:39]
	v_mfma_f32_16x16x32_bf16 v[32:35], v[94:97], v[126:129], v[32:35]
	v_mfma_f32_16x16x32_bf16 v[60:63], v[90:93], v[106:109], v[60:63]
	v_mfma_f32_16x16x32_bf16 v[56:59], v[98:101], v[106:109], v[56:59]
	v_mfma_f32_16x16x32_bf16 v[52:55], v[90:93], v[114:117], v[52:55]
	v_mfma_f32_16x16x32_bf16 v[48:51], v[98:101], v[114:117], v[48:51]
	v_mfma_f32_16x16x32_bf16 v[44:47], v[90:93], v[122:125], v[44:47]
	v_mfma_f32_16x16x32_bf16 v[40:43], v[98:101], v[122:125], v[40:43]
	v_mfma_f32_16x16x32_bf16 v[36:39], v[90:93], v[130:133], v[36:39]
	v_mfma_f32_16x16x32_bf16 v[32:35], v[98:101], v[130:133], v[32:35]
	s_setprio 0
	s_setprio 1
	s_setprio 0
	s_barrier
	s_add_i32 s20, s48, s33
	v_lshl_add_u64 v[134:135], s[22:23], 0, v[66:67]
	s_mov_b32 m0, s20
	ds_read_b128 v[102:105], v85 offset:16384
	ds_read_b128 v[106:109], v85 offset:17408
	ds_read_b128 v[110:113], v85 offset:18432
	ds_read_b128 v[114:117], v85 offset:19456
	ds_read_b128 v[118:121], v85 offset:20480
	ds_read_b128 v[122:125], v85 offset:21504
	ds_read_b128 v[126:129], v85 offset:22528
	ds_read_b128 v[130:133], v85 offset:23552
	global_load_lds_dwordx4 v[134:135], off
	s_add_i32 m0, s20, 0x2000
	s_add_u32 s20, s22, 0x20000
	v_lshl_add_u64 v[136:137], s[22:23], 0, v[70:71]
	s_addc_u32 s21, s23, 0
	global_load_lds_dwordx4 v[136:137], off
	s_mov_b32 m0, s35
	v_lshl_add_u64 v[140:141], s[24:25], 0, v[68:69]
	global_load_lds_dwordx4 v66, s[20:21]
	s_mov_b32 m0, s36
	s_nop 0
	global_load_lds_dwordx4 v70, s[20:21]
	v_lshl_add_u64 v[138:139], s[24:25], 0, v[64:65]
	s_mov_b32 m0, s34
	s_nop 0
	global_load_lds_dwordx4 v[138:139], off
	s_mov_b32 m0, s0
	s_nop 0
	global_load_lds_dwordx4 v[140:141], off
	s_waitcnt vmcnt(8)
	s_waitcnt lgkmcnt(0)
	s_barrier
	s_setprio 1
	v_mfma_f32_16x16x32_bf16 v[28:31], v[86:89], v[102:105], v[28:31]
	v_mfma_f32_16x16x32_bf16 v[24:27], v[94:97], v[102:105], v[24:27]
	v_mfma_f32_16x16x32_bf16 v[20:23], v[86:89], v[110:113], v[20:23]
	v_mfma_f32_16x16x32_bf16 v[16:19], v[94:97], v[110:113], v[16:19]
	v_mfma_f32_16x16x32_bf16 v[12:15], v[86:89], v[118:121], v[12:15]
	v_mfma_f32_16x16x32_bf16 v[8:11], v[94:97], v[118:121], v[8:11]
	v_mfma_f32_16x16x32_bf16 v[4:7], v[86:89], v[126:129], v[4:7]
	v_mfma_f32_16x16x32_bf16 v[0:3], v[94:97], v[126:129], v[0:3]
	v_mfma_f32_16x16x32_bf16 v[28:31], v[90:93], v[106:109], v[28:31]
	v_mfma_f32_16x16x32_bf16 v[24:27], v[98:101], v[106:109], v[24:27]
	v_mfma_f32_16x16x32_bf16 v[20:23], v[90:93], v[114:117], v[20:23]
	v_mfma_f32_16x16x32_bf16 v[16:19], v[98:101], v[114:117], v[16:19]
	v_mfma_f32_16x16x32_bf16 v[12:15], v[90:93], v[122:125], v[12:15]
	v_mfma_f32_16x16x32_bf16 v[8:11], v[98:101], v[122:125], v[8:11]
	v_mfma_f32_16x16x32_bf16 v[4:7], v[90:93], v[130:133], v[4:7]
	v_mfma_f32_16x16x32_bf16 v[0:3], v[98:101], v[130:133], v[0:3]
	s_setprio 0
	s_setprio 1
	s_setprio 0
	s_barrier
	s_add_i32 s54, 0, 0x18000
	v_add_u32_e32 v98, s54, v83
	ds_read_b128 v[86:89], v98
	ds_read_b128 v[90:93], v98 offset:1024
	ds_read_b128 v[94:97], v98 offset:2048
	ds_read_b128 v[98:101], v98 offset:3072
	s_add_u32 s20, s24, 0x28000
	s_addc_u32 s21, s25, 0
	s_mov_b32 m0, s1
	ds_read_b128 v[102:105], v85 offset:32768
	ds_read_b128 v[106:109], v85 offset:33792
	ds_read_b128 v[110:113], v85 offset:34816
	ds_read_b128 v[114:117], v85 offset:35840
	ds_read_b128 v[118:121], v85 offset:36864
	ds_read_b128 v[122:125], v85 offset:37888
	ds_read_b128 v[126:129], v85 offset:38912
	ds_read_b128 v[130:133], v85 offset:39936
	global_load_lds_dwordx4 v64, s[20:21]
	s_mov_b32 m0, s37
	s_nop 0
	global_load_lds_dwordx4 v68, s[20:21]
	s_waitcnt vmcnt(8)
	s_waitcnt lgkmcnt(0)
	s_barrier
	s_setprio 1
	v_mfma_f32_16x16x32_bf16 v[60:63], v[86:89], v[102:105], v[60:63]
	v_mfma_f32_16x16x32_bf16 v[56:59], v[94:97], v[102:105], v[56:59]
	v_mfma_f32_16x16x32_bf16 v[52:55], v[86:89], v[110:113], v[52:55]
	v_mfma_f32_16x16x32_bf16 v[48:51], v[94:97], v[110:113], v[48:51]
	v_mfma_f32_16x16x32_bf16 v[44:47], v[86:89], v[118:121], v[44:47]
	v_mfma_f32_16x16x32_bf16 v[40:43], v[94:97], v[118:121], v[40:43]
	v_mfma_f32_16x16x32_bf16 v[36:39], v[86:89], v[126:129], v[36:39]
	v_mfma_f32_16x16x32_bf16 v[32:35], v[94:97], v[126:129], v[32:35]
	v_mfma_f32_16x16x32_bf16 v[60:63], v[90:93], v[106:109], v[60:63]
	v_mfma_f32_16x16x32_bf16 v[56:59], v[98:101], v[106:109], v[56:59]
	v_mfma_f32_16x16x32_bf16 v[52:55], v[90:93], v[114:117], v[52:55]
	v_mfma_f32_16x16x32_bf16 v[48:51], v[98:101], v[114:117], v[48:51]
	v_mfma_f32_16x16x32_bf16 v[44:47], v[90:93], v[122:125], v[44:47]
	v_mfma_f32_16x16x32_bf16 v[40:43], v[98:101], v[122:125], v[40:43]
	v_mfma_f32_16x16x32_bf16 v[36:39], v[90:93], v[130:133], v[36:39]
	v_mfma_f32_16x16x32_bf16 v[32:35], v[98:101], v[130:133], v[32:35]
	s_setprio 0
	s_setprio 1
	s_setprio 0
	s_barrier
	s_add_i32 s20, s54, s33
	v_lshl_add_u64 v[134:135], v[134:135], 0, s[8:9]
	s_mov_b32 m0, s20
	ds_read_b128 v[102:105], v85 offset:49152
	ds_read_b128 v[106:109], v85 offset:50176
	ds_read_b128 v[110:113], v85 offset:51200
	ds_read_b128 v[114:117], v85 offset:52224
	ds_read_b128 v[118:121], v85 offset:53248
	ds_read_b128 v[122:125], v85 offset:54272
	ds_read_b128 v[126:129], v85 offset:55296
	ds_read_b128 v[130:133], v85 offset:56320
	global_load_lds_dwordx4 v[134:135], off
	s_add_i32 m0, s20, 0x2000
	s_add_u32 s20, s22, 0x20080
	v_lshl_add_u64 v[134:135], v[136:137], 0, s[8:9]
	s_addc_u32 s21, s23, 0
	global_load_lds_dwordx4 v[134:135], off
	s_mov_b32 m0, s44
	s_nop 0
	global_load_lds_dwordx4 v66, s[20:21]
	s_mov_b32 m0, s45
	s_nop 0
	global_load_lds_dwordx4 v70, s[20:21]
	v_lshl_add_u64 v[134:135], v[138:139], 0, s[8:9]
	s_mov_b32 m0, s42
	s_nop 0
	global_load_lds_dwordx4 v[134:135], off
	v_lshl_add_u64 v[134:135], v[140:141], 0, s[8:9]
	s_mov_b32 m0, s43
	s_nop 0
	global_load_lds_dwordx4 v[134:135], off
	s_waitcnt vmcnt(8)
	s_waitcnt lgkmcnt(0)
	s_barrier
	s_setprio 1
	v_mfma_f32_16x16x32_bf16 v[28:31], v[86:89], v[102:105], v[28:31]
	v_mfma_f32_16x16x32_bf16 v[24:27], v[94:97], v[102:105], v[24:27]
	v_mfma_f32_16x16x32_bf16 v[20:23], v[86:89], v[110:113], v[20:23]
	v_mfma_f32_16x16x32_bf16 v[16:19], v[94:97], v[110:113], v[16:19]
	v_mfma_f32_16x16x32_bf16 v[12:15], v[86:89], v[118:121], v[12:15]
	v_mfma_f32_16x16x32_bf16 v[8:11], v[94:97], v[118:121], v[8:11]
	v_mfma_f32_16x16x32_bf16 v[4:7], v[86:89], v[126:129], v[4:7]
	v_mfma_f32_16x16x32_bf16 v[0:3], v[94:97], v[126:129], v[0:3]
	v_mfma_f32_16x16x32_bf16 v[28:31], v[90:93], v[106:109], v[28:31]
	v_mfma_f32_16x16x32_bf16 v[24:27], v[98:101], v[106:109], v[24:27]
	v_mfma_f32_16x16x32_bf16 v[20:23], v[90:93], v[114:117], v[20:23]
	v_mfma_f32_16x16x32_bf16 v[16:19], v[98:101], v[114:117], v[16:19]
	v_mfma_f32_16x16x32_bf16 v[12:15], v[90:93], v[122:125], v[12:15]
	v_mfma_f32_16x16x32_bf16 v[8:11], v[98:101], v[122:125], v[8:11]
	v_mfma_f32_16x16x32_bf16 v[4:7], v[90:93], v[130:133], v[4:7]
	v_mfma_f32_16x16x32_bf16 v[0:3], v[98:101], v[130:133], v[0:3]
	s_setprio 0
	s_setprio 1
	s_setprio 0
	s_barrier
	s_add_i32 s53, s53, 2
	s_add_u32 s51, s51, 0x100
	s_addc_u32 s52, s52, 0
	s_cmp_gt_u32 s53, 5
	s_mov_b64 s[20:21], s[6:7]
	s_cbranch_scc0 .LBB0_265
	s_and_b64 vcc, exec, s[12:13]
	s_cbranch_vccz .LBB0_268
	s_barrier

.Lrestag_402:
	ds_read_b128 v[120:123], v205
	ds_read_b128 v[124:127], v205 offset:1024
	ds_read_b128 v[132:135], v205 offset:2048
	ds_read_b128 v[140:143], v205 offset:3072
	ds_read_b128 v[144:147], v206
	ds_read_b128 v[148:151], v206 offset:1024
	ds_read_b128 v[152:155], v206 offset:2048
	ds_read_b128 v[156:159], v206 offset:3072
	s_add_u32 s22, s20, 0x100
	s_addc_u32 s23, s21, 0
	s_cmp_eq_u32 s54, 6
	s_cselect_b32 s27, s7, s23
	s_cselect_b32 s26, s6, s22
	s_cselect_b32 s25, s19, s53
	s_cselect_b32 s24, s18, s52
	s_add_i32 m0, s35, 0xc000
	ds_read_b128 v[180:183], v207
	ds_read_b128 v[184:187], v207 offset:1024
	ds_read_b128 v[188:191], v207 offset:2048
	ds_read_b128 v[192:195], v207 offset:3072
	ds_read_b128 v[196:199], v207 offset:4096
	ds_read_b128 v[208:211], v207 offset:5120
	ds_read_b128 v[212:215], v207 offset:6144
	ds_read_b128 v[216:219], v207 offset:7168
	global_load_lds_dwordx4 v172, s[20:21]
	s_add_i32 m0, s35, 0xe000
	s_nop 0
	global_load_lds_dwordx4 v174, s[20:21]
	s_nop 0
	s_waitcnt lgkmcnt(0)
	s_barrier
	s_setprio 1
	v_mfma_f32_16x16x32_bf16 v[136:139], v[120:123], v[180:183], 0
	v_mfma_f32_16x16x32_bf16 v[128:131], v[132:135], v[180:183], 0
	v_mfma_f32_16x16x32_bf16 v[116:119], v[120:123], v[188:191], 0
	v_mfma_f32_16x16x32_bf16 v[112:115], v[132:135], v[188:191], 0
	v_mfma_f32_16x16x32_bf16 v[108:111], v[120:123], v[196:199], 0
	v_mfma_f32_16x16x32_bf16 v[104:107], v[132:135], v[196:199], 0
	v_mfma_f32_16x16x32_bf16 v[100:103], v[120:123], v[212:215], 0
	v_mfma_f32_16x16x32_bf16 v[96:99], v[132:135], v[212:215], 0
	v_mfma_f32_16x16x32_bf16 v[136:139], v[124:127], v[184:187], v[136:139]
	v_mfma_f32_16x16x32_bf16 v[128:131], v[140:143], v[184:187], v[128:131]
	v_mfma_f32_16x16x32_bf16 v[116:119], v[124:127], v[192:195], v[116:119]
	v_mfma_f32_16x16x32_bf16 v[112:115], v[140:143], v[192:195], v[112:115]
	v_mfma_f32_16x16x32_bf16 v[108:111], v[124:127], v[208:211], v[108:111]
	v_mfma_f32_16x16x32_bf16 v[104:107], v[140:143], v[208:211], v[104:107]
	v_mfma_f32_16x16x32_bf16 v[100:103], v[124:127], v[216:219], v[100:103]
	v_mfma_f32_16x16x32_bf16 v[96:99], v[140:143], v[216:219], v[96:99]
	v_mfma_f32_16x16x32_bf16 v[60:63], v[144:147], v[180:183], 0
	v_mfma_f32_16x16x32_bf16 v[56:59], v[152:155], v[180:183], 0
	v_mfma_f32_16x16x32_bf16 v[52:55], v[144:147], v[188:191], 0
	v_mfma_f32_16x16x32_bf16 v[48:51], v[152:155], v[188:191], 0
	v_mfma_f32_16x16x32_bf16 v[44:47], v[144:147], v[196:199], 0
	v_mfma_f32_16x16x32_bf16 v[40:43], v[152:155], v[196:199], 0
	v_mfma_f32_16x16x32_bf16 v[36:39], v[144:147], v[212:215], 0
	v_mfma_f32_16x16x32_bf16 v[32:35], v[152:155], v[212:215], 0
	v_mfma_f32_16x16x32_bf16 v[60:63], v[148:151], v[184:187], v[60:63]
	v_mfma_f32_16x16x32_bf16 v[56:59], v[156:159], v[184:187], v[56:59]
	v_mfma_f32_16x16x32_bf16 v[52:55], v[148:151], v[192:195], v[52:55]
	v_mfma_f32_16x16x32_bf16 v[48:51], v[156:159], v[192:195], v[48:51]
	v_mfma_f32_16x16x32_bf16 v[44:47], v[148:151], v[208:211], v[44:47]
	v_mfma_f32_16x16x32_bf16 v[40:43], v[156:159], v[208:211], v[40:43]
	v_mfma_f32_16x16x32_bf16 v[36:39], v[148:151], v[216:219], v[36:39]
	v_mfma_f32_16x16x32_bf16 v[32:35], v[156:159], v[216:219], v[32:35]
	s_setprio 0
	s_barrier
	s_add_i32 s0, s46, s34
	v_lshl_add_u64 v[200:201], s[24:25], 0, v[162:163]
	s_mov_b32 m0, s0
	ds_read_b128 v[180:183], v207 offset:16384
	ds_read_b128 v[184:187], v207 offset:17408
	ds_read_b128 v[188:191], v207 offset:18432
	ds_read_b128 v[192:195], v207 offset:19456
	ds_read_b128 v[196:199], v207 offset:20480
	ds_read_b128 v[208:211], v207 offset:21504
	ds_read_b128 v[212:215], v207 offset:22528
	ds_read_b128 v[216:219], v207 offset:23552
	global_load_lds_dwordx4 v[200:201], off
	s_add_i32 m0, s0, 0x2000
	s_add_u32 s0, s24, 0x28000
	v_lshl_add_u64 v[220:221], s[24:25], 0, v[166:167]
	s_addc_u32 s1, s25, 0
	s_add_i32 s20, s47, s34
	global_load_lds_dwordx4 v[220:221], off
	s_mov_b32 m0, s20
	v_lshl_add_u64 v[224:225], s[26:27], 0, v[164:165]
	global_load_lds_dwordx4 v162, s[0:1]
	s_add_i32 m0, s20, 0x2000
	s_nop 0
	global_load_lds_dwordx4 v166, s[0:1]
	v_lshl_add_u64 v[222:223], s[26:27], 0, v[160:161]
	s_nop 0
	s_waitcnt lgkmcnt(0)
	s_barrier
	s_setprio 1
	v_mfma_f32_16x16x32_bf16 v[92:95], v[120:123], v[180:183], 0
	v_mfma_f32_16x16x32_bf16 v[88:91], v[132:135], v[180:183], 0
	v_mfma_f32_16x16x32_bf16 v[84:87], v[120:123], v[188:191], 0
	v_mfma_f32_16x16x32_bf16 v[80:83], v[132:135], v[188:191], 0
	v_mfma_f32_16x16x32_bf16 v[76:79], v[120:123], v[196:199], 0
	v_mfma_f32_16x16x32_bf16 v[72:75], v[132:135], v[196:199], 0
	v_mfma_f32_16x16x32_bf16 v[68:71], v[120:123], v[212:215], 0
	v_mfma_f32_16x16x32_bf16 v[64:67], v[132:135], v[212:215], 0
	v_mfma_f32_16x16x32_bf16 v[92:95], v[124:127], v[184:187], v[92:95]
	v_mfma_f32_16x16x32_bf16 v[88:91], v[140:143], v[184:187], v[88:91]
	v_mfma_f32_16x16x32_bf16 v[84:87], v[124:127], v[192:195], v[84:87]
	v_mfma_f32_16x16x32_bf16 v[80:83], v[140:143], v[192:195], v[80:83]
	v_mfma_f32_16x16x32_bf16 v[76:79], v[124:127], v[208:211], v[76:79]
	v_mfma_f32_16x16x32_bf16 v[72:75], v[140:143], v[208:211], v[72:75]
	v_mfma_f32_16x16x32_bf16 v[68:71], v[124:127], v[216:219], v[68:71]
	v_mfma_f32_16x16x32_bf16 v[64:67], v[140:143], v[216:219], v[64:67]
	v_mfma_f32_16x16x32_bf16 v[28:31], v[144:147], v[180:183], 0
	v_mfma_f32_16x16x32_bf16 v[24:27], v[152:155], v[180:183], 0
	v_mfma_f32_16x16x32_bf16 v[20:23], v[144:147], v[188:191], 0
	v_mfma_f32_16x16x32_bf16 v[16:19], v[152:155], v[188:191], 0
	v_mfma_f32_16x16x32_bf16 v[12:15], v[144:147], v[196:199], 0
	v_mfma_f32_16x16x32_bf16 v[8:11], v[152:155], v[196:199], 0
	v_mfma_f32_16x16x32_bf16 v[4:7], v[144:147], v[212:215], 0
	v_mfma_f32_16x16x32_bf16 v[0:3], v[152:155], v[212:215], 0
	v_mfma_f32_16x16x32_bf16 v[28:31], v[148:151], v[184:187], v[28:31]
	v_mfma_f32_16x16x32_bf16 v[24:27], v[156:159], v[184:187], v[24:27]
	v_mfma_f32_16x16x32_bf16 v[20:23], v[148:151], v[192:195], v[20:23]
	v_mfma_f32_16x16x32_bf16 v[16:19], v[156:159], v[192:195], v[16:19]
	v_mfma_f32_16x16x32_bf16 v[12:15], v[148:151], v[208:211], v[12:15]
	v_mfma_f32_16x16x32_bf16 v[8:11], v[156:159], v[208:211], v[8:11]
	v_mfma_f32_16x16x32_bf16 v[4:7], v[148:151], v[216:219], v[4:7]
	v_mfma_f32_16x16x32_bf16 v[0:3], v[156:159], v[216:219], v[0:3]
	s_setprio 0
	s_barrier
	s_add_i32 s20, 0, 0x18000
	s_add_i32 s21, 0, 0x1c000
	v_add_u32_e32 v140, s20, v203
	v_add_u32_e32 v156, s21, v203
	ds_read_b128 v[120:123], v140
	ds_read_b128 v[124:127], v140 offset:1024
	ds_read_b128 v[132:135], v140 offset:2048
	ds_read_b128 v[140:143], v140 offset:3072
	ds_read_b128 v[144:147], v156
	ds_read_b128 v[148:151], v156 offset:1024
	ds_read_b128 v[152:155], v156 offset:2048
	ds_read_b128 v[156:159], v156 offset:3072
	s_add_u32 s0, s26, 0x28000
	s_addc_u32 s1, s27, 0
	s_mov_b32 m0, s37
	ds_read_b128 v[180:183], v207 offset:32768
	ds_read_b128 v[184:187], v207 offset:33792
	ds_read_b128 v[188:191], v207 offset:34816
	ds_read_b128 v[192:195], v207 offset:35840
	ds_read_b128 v[196:199], v207 offset:36864
	ds_read_b128 v[208:211], v207 offset:37888
	ds_read_b128 v[212:215], v207 offset:38912
	ds_read_b128 v[216:219], v207 offset:39936
	global_load_lds_dwordx4 v160, s[0:1]
	s_mov_b32 m0, s40
	s_nop 0
	global_load_lds_dwordx4 v164, s[0:1]
	s_mov_b32 m0, s35
	s_nop 0
	global_load_lds_dwordx4 v[222:223], off
	s_mov_b32 m0, s36
	s_nop 0
	global_load_lds_dwordx4 v[224:225], off
	s_waitcnt vmcnt(8)
	s_waitcnt lgkmcnt(0)
	s_barrier
	s_setprio 1
	v_mfma_f32_16x16x32_bf16 v[136:139], v[120:123], v[180:183], v[136:139]
	v_mfma_f32_16x16x32_bf16 v[128:131], v[132:135], v[180:183], v[128:131]
	v_mfma_f32_16x16x32_bf16 v[116:119], v[120:123], v[188:191], v[116:119]
	v_mfma_f32_16x16x32_bf16 v[112:115], v[132:135], v[188:191], v[112:115]
	v_mfma_f32_16x16x32_bf16 v[108:111], v[120:123], v[196:199], v[108:111]
	v_mfma_f32_16x16x32_bf16 v[104:107], v[132:135], v[196:199], v[104:107]
	v_mfma_f32_16x16x32_bf16 v[100:103], v[120:123], v[212:215], v[100:103]
	v_mfma_f32_16x16x32_bf16 v[96:99], v[132:135], v[212:215], v[96:99]
	v_mfma_f32_16x16x32_bf16 v[136:139], v[124:127], v[184:187], v[136:139]
	v_mfma_f32_16x16x32_bf16 v[128:131], v[140:143], v[184:187], v[128:131]
	v_mfma_f32_16x16x32_bf16 v[116:119], v[124:127], v[192:195], v[116:119]
	v_mfma_f32_16x16x32_bf16 v[112:115], v[140:143], v[192:195], v[112:115]
	v_mfma_f32_16x16x32_bf16 v[108:111], v[124:127], v[208:211], v[108:111]
	v_mfma_f32_16x16x32_bf16 v[104:107], v[140:143], v[208:211], v[104:107]
	v_mfma_f32_16x16x32_bf16 v[100:103], v[124:127], v[216:219], v[100:103]
	v_mfma_f32_16x16x32_bf16 v[96:99], v[140:143], v[216:219], v[96:99]
	v_mfma_f32_16x16x32_bf16 v[60:63], v[144:147], v[180:183], v[60:63]
	v_mfma_f32_16x16x32_bf16 v[56:59], v[152:155], v[180:183], v[56:59]
	v_mfma_f32_16x16x32_bf16 v[52:55], v[144:147], v[188:191], v[52:55]
	v_mfma_f32_16x16x32_bf16 v[48:51], v[152:155], v[188:191], v[48:51]
	v_mfma_f32_16x16x32_bf16 v[44:47], v[144:147], v[196:199], v[44:47]
	v_mfma_f32_16x16x32_bf16 v[40:43], v[152:155], v[196:199], v[40:43]
	v_mfma_f32_16x16x32_bf16 v[36:39], v[144:147], v[212:215], v[36:39]
	v_mfma_f32_16x16x32_bf16 v[32:35], v[152:155], v[212:215], v[32:35]
	v_mfma_f32_16x16x32_bf16 v[60:63], v[148:151], v[184:187], v[60:63]
	v_mfma_f32_16x16x32_bf16 v[56:59], v[156:159], v[184:187], v[56:59]
	v_mfma_f32_16x16x32_bf16 v[52:55], v[148:151], v[192:195], v[52:55]
	v_mfma_f32_16x16x32_bf16 v[48:51], v[156:159], v[192:195], v[48:51]
	v_mfma_f32_16x16x32_bf16 v[44:47], v[148:151], v[208:211], v[44:47]
	v_mfma_f32_16x16x32_bf16 v[40:43], v[156:159], v[208:211], v[40:43]
	v_mfma_f32_16x16x32_bf16 v[36:39], v[148:151], v[216:219], v[36:39]
	v_mfma_f32_16x16x32_bf16 v[32:35], v[156:159], v[216:219], v[32:35]
	s_setprio 0
	s_barrier
	s_add_i32 s0, s20, s34
	v_lshl_add_u64 v[200:201], v[200:201], 0, s[14:15]
	s_mov_b32 m0, s0
	ds_read_b128 v[180:183], v207 offset:49152
	ds_read_b128 v[184:187], v207 offset:50176
	ds_read_b128 v[188:191], v207 offset:51200
	ds_read_b128 v[192:195], v207 offset:52224
	ds_read_b128 v[196:199], v207 offset:53248
	ds_read_b128 v[208:211], v207 offset:54272
	ds_read_b128 v[212:215], v207 offset:55296
	ds_read_b128 v[216:219], v207 offset:56320
	global_load_lds_dwordx4 v[200:201], off
	s_add_i32 m0, s0, 0x2000
	s_add_u32 s0, s24, 0x28080
	v_lshl_add_u64 v[200:201], v[220:221], 0, s[14:15]
	s_addc_u32 s1, s25, 0
	s_add_i32 s20, s21, s34
	global_load_lds_dwordx4 v[200:201], off
	s_mov_b32 m0, s20
	s_nop 0
	global_load_lds_dwordx4 v162, s[0:1]
	s_add_i32 m0, s20, 0x2000
	s_nop 0
	global_load_lds_dwordx4 v166, s[0:1]
	v_lshl_add_u64 v[200:201], v[222:223], 0, s[14:15]
	s_mov_b32 m0, s42
	s_nop 0
	global_load_lds_dwordx4 v[200:201], off
	v_lshl_add_u64 v[200:201], v[224:225], 0, s[14:15]
	s_mov_b32 m0, s43
	s_nop 0
	global_load_lds_dwordx4 v[200:201], off
	s_waitcnt vmcnt(6)
	s_waitcnt lgkmcnt(0)
	s_barrier
	s_setprio 1
	v_mfma_f32_16x16x32_bf16 v[92:95], v[120:123], v[180:183], v[92:95]
	v_mfma_f32_16x16x32_bf16 v[88:91], v[132:135], v[180:183], v[88:91]
	v_mfma_f32_16x16x32_bf16 v[84:87], v[120:123], v[188:191], v[84:87]
	v_mfma_f32_16x16x32_bf16 v[80:83], v[132:135], v[188:191], v[80:83]
	v_mfma_f32_16x16x32_bf16 v[76:79], v[120:123], v[196:199], v[76:79]
	v_mfma_f32_16x16x32_bf16 v[72:75], v[132:135], v[196:199], v[72:75]
	v_mfma_f32_16x16x32_bf16 v[68:71], v[120:123], v[212:215], v[68:71]
	v_mfma_f32_16x16x32_bf16 v[64:67], v[132:135], v[212:215], v[64:67]
	v_mfma_f32_16x16x32_bf16 v[92:95], v[124:127], v[184:187], v[92:95]
	v_mfma_f32_16x16x32_bf16 v[88:91], v[140:143], v[184:187], v[88:91]
	v_mfma_f32_16x16x32_bf16 v[84:87], v[124:127], v[192:195], v[84:87]
	v_mfma_f32_16x16x32_bf16 v[80:83], v[140:143], v[192:195], v[80:83]
	v_mfma_f32_16x16x32_bf16 v[76:79], v[124:127], v[208:211], v[76:79]
	v_mfma_f32_16x16x32_bf16 v[72:75], v[140:143], v[208:211], v[72:75]
	v_mfma_f32_16x16x32_bf16 v[68:71], v[124:127], v[216:219], v[68:71]
	v_mfma_f32_16x16x32_bf16 v[64:67], v[140:143], v[216:219], v[64:67]
	v_mfma_f32_16x16x32_bf16 v[28:31], v[144:147], v[180:183], v[28:31]
	v_mfma_f32_16x16x32_bf16 v[24:27], v[152:155], v[180:183], v[24:27]
	v_mfma_f32_16x16x32_bf16 v[20:23], v[144:147], v[188:191], v[20:23]
	v_mfma_f32_16x16x32_bf16 v[16:19], v[152:155], v[188:191], v[16:19]
	v_mfma_f32_16x16x32_bf16 v[12:15], v[144:147], v[196:199], v[12:15]
	v_mfma_f32_16x16x32_bf16 v[8:11], v[152:155], v[196:199], v[8:11]
	v_mfma_f32_16x16x32_bf16 v[4:7], v[144:147], v[212:215], v[4:7]
	v_mfma_f32_16x16x32_bf16 v[0:3], v[152:155], v[212:215], v[0:3]
	v_mfma_f32_16x16x32_bf16 v[28:31], v[148:151], v[184:187], v[28:31]
	v_mfma_f32_16x16x32_bf16 v[24:27], v[156:159], v[184:187], v[24:27]
	v_mfma_f32_16x16x32_bf16 v[20:23], v[148:151], v[192:195], v[20:23]
	v_mfma_f32_16x16x32_bf16 v[16:19], v[156:159], v[192:195], v[16:19]
	v_mfma_f32_16x16x32_bf16 v[12:15], v[148:151], v[208:211], v[12:15]
	v_mfma_f32_16x16x32_bf16 v[8:11], v[156:159], v[208:211], v[8:11]
	v_mfma_f32_16x16x32_bf16 v[4:7], v[148:151], v[216:219], v[4:7]
	v_mfma_f32_16x16x32_bf16 v[0:3], v[156:159], v[216:219], v[0:3]
	s_setprio 0
	s_barrier
	s_add_i32 s54, s54, 2
	s_add_u32 s52, s52, 0x100
	s_addc_u32 s53, s53, 0
	s_cmp_gt_u32 s54, 7
	s_mov_b64 s[20:21], s[22:23]
.LBB0_402:
	ds_read_b128 v[120:123], v205
	ds_read_b128 v[124:127], v205 offset:1024
	ds_read_b128 v[132:135], v205 offset:2048
	ds_read_b128 v[140:143], v205 offset:3072
	ds_read_b128 v[144:147], v206
	ds_read_b128 v[148:151], v206 offset:1024
	ds_read_b128 v[152:155], v206 offset:2048
	ds_read_b128 v[156:159], v206 offset:3072
	s_add_u32 s22, s20, 0x100
	s_addc_u32 s23, s21, 0
	s_cmp_eq_u32 s54, 6
	s_cselect_b32 s27, s7, s23
	s_cselect_b32 s26, s6, s22
	s_cselect_b32 s25, s19, s53
	s_cselect_b32 s24, s18, s52
	s_add_i32 m0, s35, 0xc000
	ds_read_b128 v[180:183], v207
	ds_read_b128 v[184:187], v207 offset:1024
	ds_read_b128 v[188:191], v207 offset:2048
	ds_read_b128 v[192:195], v207 offset:3072
	ds_read_b128 v[196:199], v207 offset:4096
	ds_read_b128 v[208:211], v207 offset:5120
	ds_read_b128 v[212:215], v207 offset:6144
	ds_read_b128 v[216:219], v207 offset:7168
	global_load_lds_dwordx4 v172, s[20:21]
	s_add_i32 m0, s35, 0xe000
	s_nop 0
	global_load_lds_dwordx4 v174, s[20:21]
	s_waitcnt vmcnt(8)
	s_waitcnt lgkmcnt(0)
	s_barrier
	s_setprio 1
	v_mfma_f32_16x16x32_bf16 v[136:139], v[120:123], v[180:183], v[136:139]
	v_mfma_f32_16x16x32_bf16 v[128:131], v[132:135], v[180:183], v[128:131]
	v_mfma_f32_16x16x32_bf16 v[116:119], v[120:123], v[188:191], v[116:119]
	v_mfma_f32_16x16x32_bf16 v[112:115], v[132:135], v[188:191], v[112:115]
	v_mfma_f32_16x16x32_bf16 v[108:111], v[120:123], v[196:199], v[108:111]
	v_mfma_f32_16x16x32_bf16 v[104:107], v[132:135], v[196:199], v[104:107]
	v_mfma_f32_16x16x32_bf16 v[100:103], v[120:123], v[212:215], v[100:103]
	v_mfma_f32_16x16x32_bf16 v[96:99], v[132:135], v[212:215], v[96:99]
	v_mfma_f32_16x16x32_bf16 v[136:139], v[124:127], v[184:187], v[136:139]
	v_mfma_f32_16x16x32_bf16 v[128:131], v[140:143], v[184:187], v[128:131]
	v_mfma_f32_16x16x32_bf16 v[116:119], v[124:127], v[192:195], v[116:119]
	v_mfma_f32_16x16x32_bf16 v[112:115], v[140:143], v[192:195], v[112:115]
	v_mfma_f32_16x16x32_bf16 v[108:111], v[124:127], v[208:211], v[108:111]
	v_mfma_f32_16x16x32_bf16 v[104:107], v[140:143], v[208:211], v[104:107]
	v_mfma_f32_16x16x32_bf16 v[100:103], v[124:127], v[216:219], v[100:103]
	v_mfma_f32_16x16x32_bf16 v[96:99], v[140:143], v[216:219], v[96:99]
	v_mfma_f32_16x16x32_bf16 v[60:63], v[144:147], v[180:183], v[60:63]
	v_mfma_f32_16x16x32_bf16 v[56:59], v[152:155], v[180:183], v[56:59]
	v_mfma_f32_16x16x32_bf16 v[52:55], v[144:147], v[188:191], v[52:55]
	v_mfma_f32_16x16x32_bf16 v[48:51], v[152:155], v[188:191], v[48:51]
	v_mfma_f32_16x16x32_bf16 v[44:47], v[144:147], v[196:199], v[44:47]
	v_mfma_f32_16x16x32_bf16 v[40:43], v[152:155], v[196:199], v[40:43]
	v_mfma_f32_16x16x32_bf16 v[36:39], v[144:147], v[212:215], v[36:39]
	v_mfma_f32_16x16x32_bf16 v[32:35], v[152:155], v[212:215], v[32:35]
	v_mfma_f32_16x16x32_bf16 v[60:63], v[148:151], v[184:187], v[60:63]
	v_mfma_f32_16x16x32_bf16 v[56:59], v[156:159], v[184:187], v[56:59]
	v_mfma_f32_16x16x32_bf16 v[52:55], v[148:151], v[192:195], v[52:55]
	v_mfma_f32_16x16x32_bf16 v[48:51], v[156:159], v[192:195], v[48:51]
	v_mfma_f32_16x16x32_bf16 v[44:47], v[148:151], v[208:211], v[44:47]
	v_mfma_f32_16x16x32_bf16 v[40:43], v[156:159], v[208:211], v[40:43]
	v_mfma_f32_16x16x32_bf16 v[36:39], v[148:151], v[216:219], v[36:39]
	v_mfma_f32_16x16x32_bf16 v[32:35], v[156:159], v[216:219], v[32:35]
	s_setprio 0
	s_barrier
	s_add_i32 s0, s46, s34
	v_lshl_add_u64 v[200:201], s[24:25], 0, v[162:163]
	s_mov_b32 m0, s0
	ds_read_b128 v[180:183], v207 offset:16384
	ds_read_b128 v[184:187], v207 offset:17408
	ds_read_b128 v[188:191], v207 offset:18432
	ds_read_b128 v[192:195], v207 offset:19456
	ds_read_b128 v[196:199], v207 offset:20480
	ds_read_b128 v[208:211], v207 offset:21504
	ds_read_b128 v[212:215], v207 offset:22528
	ds_read_b128 v[216:219], v207 offset:23552
	global_load_lds_dwordx4 v[200:201], off
	s_add_i32 m0, s0, 0x2000
	s_add_u32 s0, s24, 0x28000
	v_lshl_add_u64 v[220:221], s[24:25], 0, v[166:167]
	s_addc_u32 s1, s25, 0
	s_add_i32 s20, s47, s34
	global_load_lds_dwordx4 v[220:221], off
	s_mov_b32 m0, s20
	v_lshl_add_u64 v[224:225], s[26:27], 0, v[164:165]
	global_load_lds_dwordx4 v162, s[0:1]
	s_add_i32 m0, s20, 0x2000
	s_nop 0
	global_load_lds_dwordx4 v166, s[0:1]
	v_lshl_add_u64 v[222:223], s[26:27], 0, v[160:161]
	s_waitcnt vmcnt(6)
	s_waitcnt lgkmcnt(0)
	s_barrier
	s_setprio 1
	v_mfma_f32_16x16x32_bf16 v[92:95], v[120:123], v[180:183], v[92:95]
	v_mfma_f32_16x16x32_bf16 v[88:91], v[132:135], v[180:183], v[88:91]
	v_mfma_f32_16x16x32_bf16 v[84:87], v[120:123], v[188:191], v[84:87]
	v_mfma_f32_16x16x32_bf16 v[80:83], v[132:135], v[188:191], v[80:83]
	v_mfma_f32_16x16x32_bf16 v[76:79], v[120:123], v[196:199], v[76:79]
	v_mfma_f32_16x16x32_bf16 v[72:75], v[132:135], v[196:199], v[72:75]
	v_mfma_f32_16x16x32_bf16 v[68:71], v[120:123], v[212:215], v[68:71]
	v_mfma_f32_16x16x32_bf16 v[64:67], v[132:135], v[212:215], v[64:67]
	v_mfma_f32_16x16x32_bf16 v[92:95], v[124:127], v[184:187], v[92:95]
	v_mfma_f32_16x16x32_bf16 v[88:91], v[140:143], v[184:187], v[88:91]
	v_mfma_f32_16x16x32_bf16 v[84:87], v[124:127], v[192:195], v[84:87]
	v_mfma_f32_16x16x32_bf16 v[80:83], v[140:143], v[192:195], v[80:83]
	v_mfma_f32_16x16x32_bf16 v[76:79], v[124:127], v[208:211], v[76:79]
	v_mfma_f32_16x16x32_bf16 v[72:75], v[140:143], v[208:211], v[72:75]
	v_mfma_f32_16x16x32_bf16 v[68:71], v[124:127], v[216:219], v[68:71]
	v_mfma_f32_16x16x32_bf16 v[64:67], v[140:143], v[216:219], v[64:67]
	v_mfma_f32_16x16x32_bf16 v[28:31], v[144:147], v[180:183], v[28:31]
	v_mfma_f32_16x16x32_bf16 v[24:27], v[152:155], v[180:183], v[24:27]
	v_mfma_f32_16x16x32_bf16 v[20:23], v[144:147], v[188:191], v[20:23]
	v_mfma_f32_16x16x32_bf16 v[16:19], v[152:155], v[188:191], v[16:19]
	v_mfma_f32_16x16x32_bf16 v[12:15], v[144:147], v[196:199], v[12:15]
	v_mfma_f32_16x16x32_bf16 v[8:11], v[152:155], v[196:199], v[8:11]
	v_mfma_f32_16x16x32_bf16 v[4:7], v[144:147], v[212:215], v[4:7]
	v_mfma_f32_16x16x32_bf16 v[0:3], v[152:155], v[212:215], v[0:3]
	v_mfma_f32_16x16x32_bf16 v[28:31], v[148:151], v[184:187], v[28:31]
	v_mfma_f32_16x16x32_bf16 v[24:27], v[156:159], v[184:187], v[24:27]
	v_mfma_f32_16x16x32_bf16 v[20:23], v[148:151], v[192:195], v[20:23]
	v_mfma_f32_16x16x32_bf16 v[16:19], v[156:159], v[192:195], v[16:19]
	v_mfma_f32_16x16x32_bf16 v[12:15], v[148:151], v[208:211], v[12:15]
	v_mfma_f32_16x16x32_bf16 v[8:11], v[156:159], v[208:211], v[8:11]
	v_mfma_f32_16x16x32_bf16 v[4:7], v[148:151], v[216:219], v[4:7]
	v_mfma_f32_16x16x32_bf16 v[0:3], v[156:159], v[216:219], v[0:3]
	s_setprio 0
	s_barrier
	s_add_i32 s20, 0, 0x18000
	s_add_i32 s21, 0, 0x1c000
	v_add_u32_e32 v140, s20, v203
	v_add_u32_e32 v156, s21, v203
	ds_read_b128 v[120:123], v140
	ds_read_b128 v[124:127], v140 offset:1024
	ds_read_b128 v[132:135], v140 offset:2048
	ds_read_b128 v[140:143], v140 offset:3072
	ds_read_b128 v[144:147], v156
	ds_read_b128 v[148:151], v156 offset:1024
	ds_read_b128 v[152:155], v156 offset:2048
	ds_read_b128 v[156:159], v156 offset:3072
	s_add_u32 s0, s26, 0x28000
	s_addc_u32 s1, s27, 0
	s_mov_b32 m0, s37
	ds_read_b128 v[180:183], v207 offset:32768
	ds_read_b128 v[184:187], v207 offset:33792
	ds_read_b128 v[188:191], v207 offset:34816
	ds_read_b128 v[192:195], v207 offset:35840
	ds_read_b128 v[196:199], v207 offset:36864
	ds_read_b128 v[208:211], v207 offset:37888
	ds_read_b128 v[212:215], v207 offset:38912
	ds_read_b128 v[216:219], v207 offset:39936
	global_load_lds_dwordx4 v160, s[0:1]
	s_mov_b32 m0, s40
	s_nop 0
	global_load_lds_dwordx4 v164, s[0:1]
	s_mov_b32 m0, s35
	s_nop 0
	global_load_lds_dwordx4 v[222:223], off
	s_mov_b32 m0, s36
	s_nop 0
	global_load_lds_dwordx4 v[224:225], off
	s_waitcnt vmcnt(8)
	s_waitcnt lgkmcnt(0)
	s_barrier
	s_setprio 1
	v_mfma_f32_16x16x32_bf16 v[136:139], v[120:123], v[180:183], v[136:139]
	v_mfma_f32_16x16x32_bf16 v[128:131], v[132:135], v[180:183], v[128:131]
	v_mfma_f32_16x16x32_bf16 v[116:119], v[120:123], v[188:191], v[116:119]
	v_mfma_f32_16x16x32_bf16 v[112:115], v[132:135], v[188:191], v[112:115]
	v_mfma_f32_16x16x32_bf16 v[108:111], v[120:123], v[196:199], v[108:111]
	v_mfma_f32_16x16x32_bf16 v[104:107], v[132:135], v[196:199], v[104:107]
	v_mfma_f32_16x16x32_bf16 v[100:103], v[120:123], v[212:215], v[100:103]
	v_mfma_f32_16x16x32_bf16 v[96:99], v[132:135], v[212:215], v[96:99]
	v_mfma_f32_16x16x32_bf16 v[136:139], v[124:127], v[184:187], v[136:139]
	v_mfma_f32_16x16x32_bf16 v[128:131], v[140:143], v[184:187], v[128:131]
	v_mfma_f32_16x16x32_bf16 v[116:119], v[124:127], v[192:195], v[116:119]
	v_mfma_f32_16x16x32_bf16 v[112:115], v[140:143], v[192:195], v[112:115]
	v_mfma_f32_16x16x32_bf16 v[108:111], v[124:127], v[208:211], v[108:111]
	v_mfma_f32_16x16x32_bf16 v[104:107], v[140:143], v[208:211], v[104:107]
	v_mfma_f32_16x16x32_bf16 v[100:103], v[124:127], v[216:219], v[100:103]
	v_mfma_f32_16x16x32_bf16 v[96:99], v[140:143], v[216:219], v[96:99]
	v_mfma_f32_16x16x32_bf16 v[60:63], v[144:147], v[180:183], v[60:63]
	v_mfma_f32_16x16x32_bf16 v[56:59], v[152:155], v[180:183], v[56:59]
	v_mfma_f32_16x16x32_bf16 v[52:55], v[144:147], v[188:191], v[52:55]
	v_mfma_f32_16x16x32_bf16 v[48:51], v[152:155], v[188:191], v[48:51]
	v_mfma_f32_16x16x32_bf16 v[44:47], v[144:147], v[196:199], v[44:47]
	v_mfma_f32_16x16x32_bf16 v[40:43], v[152:155], v[196:199], v[40:43]
	v_mfma_f32_16x16x32_bf16 v[36:39], v[144:147], v[212:215], v[36:39]
	v_mfma_f32_16x16x32_bf16 v[32:35], v[152:155], v[212:215], v[32:35]
	v_mfma_f32_16x16x32_bf16 v[60:63], v[148:151], v[184:187], v[60:63]
	v_mfma_f32_16x16x32_bf16 v[56:59], v[156:159], v[184:187], v[56:59]
	v_mfma_f32_16x16x32_bf16 v[52:55], v[148:151], v[192:195], v[52:55]
	v_mfma_f32_16x16x32_bf16 v[48:51], v[156:159], v[192:195], v[48:51]
	v_mfma_f32_16x16x32_bf16 v[44:47], v[148:151], v[208:211], v[44:47]
	v_mfma_f32_16x16x32_bf16 v[40:43], v[156:159], v[208:211], v[40:43]
	v_mfma_f32_16x16x32_bf16 v[36:39], v[148:151], v[216:219], v[36:39]
	v_mfma_f32_16x16x32_bf16 v[32:35], v[156:159], v[216:219], v[32:35]
	s_setprio 0
	s_barrier
	s_add_i32 s0, s20, s34
	v_lshl_add_u64 v[200:201], v[200:201], 0, s[14:15]
	s_mov_b32 m0, s0
	ds_read_b128 v[180:183], v207 offset:49152
	ds_read_b128 v[184:187], v207 offset:50176
	ds_read_b128 v[188:191], v207 offset:51200
	ds_read_b128 v[192:195], v207 offset:52224
	ds_read_b128 v[196:199], v207 offset:53248
	ds_read_b128 v[208:211], v207 offset:54272
	ds_read_b128 v[212:215], v207 offset:55296
	ds_read_b128 v[216:219], v207 offset:56320
	global_load_lds_dwordx4 v[200:201], off
	s_add_i32 m0, s0, 0x2000
	s_add_u32 s0, s24, 0x28080
	v_lshl_add_u64 v[200:201], v[220:221], 0, s[14:15]
	s_addc_u32 s1, s25, 0
	s_add_i32 s20, s21, s34
	global_load_lds_dwordx4 v[200:201], off
	s_mov_b32 m0, s20
	s_nop 0
	global_load_lds_dwordx4 v162, s[0:1]
	s_add_i32 m0, s20, 0x2000
	s_nop 0
	global_load_lds_dwordx4 v166, s[0:1]
	v_lshl_add_u64 v[200:201], v[222:223], 0, s[14:15]
	s_mov_b32 m0, s42
	s_nop 0
	global_load_lds_dwordx4 v[200:201], off
	v_lshl_add_u64 v[200:201], v[224:225], 0, s[14:15]
	s_mov_b32 m0, s43
	s_nop 0
	global_load_lds_dwordx4 v[200:201], off
	s_waitcnt vmcnt(6)
	s_waitcnt lgkmcnt(0)
	s_barrier
	s_setprio 1
	v_mfma_f32_16x16x32_bf16 v[92:95], v[120:123], v[180:183], v[92:95]
	v_mfma_f32_16x16x32_bf16 v[88:91], v[132:135], v[180:183], v[88:91]
	v_mfma_f32_16x16x32_bf16 v[84:87], v[120:123], v[188:191], v[84:87]
	v_mfma_f32_16x16x32_bf16 v[80:83], v[132:135], v[188:191], v[80:83]
	v_mfma_f32_16x16x32_bf16 v[76:79], v[120:123], v[196:199], v[76:79]
	v_mfma_f32_16x16x32_bf16 v[72:75], v[132:135], v[196:199], v[72:75]
	v_mfma_f32_16x16x32_bf16 v[68:71], v[120:123], v[212:215], v[68:71]
	v_mfma_f32_16x16x32_bf16 v[64:67], v[132:135], v[212:215], v[64:67]
	v_mfma_f32_16x16x32_bf16 v[92:95], v[124:127], v[184:187], v[92:95]
	v_mfma_f32_16x16x32_bf16 v[88:91], v[140:143], v[184:187], v[88:91]
	v_mfma_f32_16x16x32_bf16 v[84:87], v[124:127], v[192:195], v[84:87]
	v_mfma_f32_16x16x32_bf16 v[80:83], v[140:143], v[192:195], v[80:83]
	v_mfma_f32_16x16x32_bf16 v[76:79], v[124:127], v[208:211], v[76:79]
	v_mfma_f32_16x16x32_bf16 v[72:75], v[140:143], v[208:211], v[72:75]
	v_mfma_f32_16x16x32_bf16 v[68:71], v[124:127], v[216:219], v[68:71]
	v_mfma_f32_16x16x32_bf16 v[64:67], v[140:143], v[216:219], v[64:67]
	v_mfma_f32_16x16x32_bf16 v[28:31], v[144:147], v[180:183], v[28:31]
	v_mfma_f32_16x16x32_bf16 v[24:27], v[152:155], v[180:183], v[24:27]
	v_mfma_f32_16x16x32_bf16 v[20:23], v[144:147], v[188:191], v[20:23]
	v_mfma_f32_16x16x32_bf16 v[16:19], v[152:155], v[188:191], v[16:19]
	v_mfma_f32_16x16x32_bf16 v[12:15], v[144:147], v[196:199], v[12:15]
	v_mfma_f32_16x16x32_bf16 v[8:11], v[152:155], v[196:199], v[8:11]
	v_mfma_f32_16x16x32_bf16 v[4:7], v[144:147], v[212:215], v[4:7]
	v_mfma_f32_16x16x32_bf16 v[0:3], v[152:155], v[212:215], v[0:3]
	v_mfma_f32_16x16x32_bf16 v[28:31], v[148:151], v[184:187], v[28:31]
	v_mfma_f32_16x16x32_bf16 v[24:27], v[156:159], v[184:187], v[24:27]
	v_mfma_f32_16x16x32_bf16 v[20:23], v[148:151], v[192:195], v[20:23]
	v_mfma_f32_16x16x32_bf16 v[16:19], v[156:159], v[192:195], v[16:19]
	v_mfma_f32_16x16x32_bf16 v[12:15], v[148:151], v[208:211], v[12:15]
	v_mfma_f32_16x16x32_bf16 v[8:11], v[156:159], v[208:211], v[8:11]
	v_mfma_f32_16x16x32_bf16 v[4:7], v[148:151], v[216:219], v[4:7]
	v_mfma_f32_16x16x32_bf16 v[0:3], v[156:159], v[216:219], v[0:3]
	s_setprio 0
	s_barrier
	s_add_i32 s54, s54, 2
	s_add_u32 s52, s52, 0x100
	s_addc_u32 s53, s53, 0
	s_cmp_gt_u32 s54, 7
	s_mov_b64 s[20:21], s[22:23]
	s_cbranch_scc0 .LBB0_402
	s_and_b64 vcc, exec, s[16:17]
	s_cbranch_vccz .LBB0_405
	s_barrier

.Lrestag_480:
	ds_read_b128 v[100:103], v210
	ds_read_b128 v[116:119], v210 offset:1024
	ds_read_b128 v[136:139], v210 offset:2048
	ds_read_b128 v[140:143], v210 offset:3072
	ds_read_b128 v[144:147], v211
	ds_read_b128 v[148:151], v211 offset:1024
	ds_read_b128 v[152:155], v211 offset:2048
	ds_read_b128 v[178:181], v211 offset:3072
	s_add_u32 s36, s34, 0x1000000
	s_addc_u32 s37, s35, 0
	s_cmp_eq_u32 s65, 12
	s_cselect_b32 s44, s29, s36
	s_cselect_b32 s45, s23, s37
	s_cselect_b32 s42, s31, s63
	s_cselect_b32 s43, s21, s64
	s_add_u32 s40, s44, 0x800000
	s_addc_u32 s41, s45, 0
	s_add_i32 m0, s52, 0xc000
	ds_read_b128 v[182:185], v212
	ds_read_b128 v[186:189], v212 offset:1024
	ds_read_b128 v[190:193], v212 offset:2048
	ds_read_b128 v[194:197], v212 offset:3072
	ds_read_b128 v[198:201], v212 offset:4096
	ds_read_b128 v[202:205], v212 offset:5120
	ds_read_b128 v[214:217], v212 offset:6144
	ds_read_b128 v[218:221], v212 offset:7168
	global_load_lds_dwordx4 v170, s[34:35]
	s_add_i32 m0, s52, 0xe000
	s_nop 0
	global_load_lds_dwordx4 v172, s[34:35]
	s_nop 0
	s_waitcnt lgkmcnt(0)
	s_barrier
	s_setprio 1
	v_mfma_f32_16x16x32_bf16 v[132:135], v[100:103], v[182:185], 0
	v_mfma_f32_16x16x32_bf16 v[124:127], v[136:139], v[182:185], 0
	v_mfma_f32_16x16x32_bf16 v[112:115], v[100:103], v[190:193], 0
	v_mfma_f32_16x16x32_bf16 v[104:107], v[136:139], v[190:193], 0
	v_mfma_f32_16x16x32_bf16 v[92:95], v[100:103], v[198:201], 0
	v_mfma_f32_16x16x32_bf16 v[84:87], v[136:139], v[198:201], 0
	v_mfma_f32_16x16x32_bf16 v[76:79], v[100:103], v[214:217], 0
	v_mfma_f32_16x16x32_bf16 v[68:71], v[136:139], v[214:217], 0
	v_mfma_f32_16x16x32_bf16 v[132:135], v[116:119], v[186:189], v[132:135]
	v_mfma_f32_16x16x32_bf16 v[124:127], v[140:143], v[186:189], v[124:127]
	v_mfma_f32_16x16x32_bf16 v[112:115], v[116:119], v[194:197], v[112:115]
	v_mfma_f32_16x16x32_bf16 v[104:107], v[140:143], v[194:197], v[104:107]
	v_mfma_f32_16x16x32_bf16 v[92:95], v[116:119], v[202:205], v[92:95]
	v_mfma_f32_16x16x32_bf16 v[84:87], v[140:143], v[202:205], v[84:87]
	v_mfma_f32_16x16x32_bf16 v[76:79], v[116:119], v[218:221], v[76:79]
	v_mfma_f32_16x16x32_bf16 v[68:71], v[140:143], v[218:221], v[68:71]
	v_mfma_f32_16x16x32_bf16 v[128:131], v[144:147], v[182:185], 0
	v_mfma_f32_16x16x32_bf16 v[120:123], v[152:155], v[182:185], 0
	v_mfma_f32_16x16x32_bf16 v[108:111], v[144:147], v[190:193], 0
	v_mfma_f32_16x16x32_bf16 v[96:99], v[152:155], v[190:193], 0
	v_mfma_f32_16x16x32_bf16 v[88:91], v[144:147], v[198:201], 0
	v_mfma_f32_16x16x32_bf16 v[80:83], v[152:155], v[198:201], 0
	v_mfma_f32_16x16x32_bf16 v[72:75], v[144:147], v[214:217], 0
	v_mfma_f32_16x16x32_bf16 v[64:67], v[152:155], v[214:217], 0
	v_mfma_f32_16x16x32_bf16 v[128:131], v[148:151], v[186:189], v[128:131]
	v_mfma_f32_16x16x32_bf16 v[120:123], v[178:181], v[186:189], v[120:123]
	v_mfma_f32_16x16x32_bf16 v[108:111], v[148:151], v[194:197], v[108:111]
	v_mfma_f32_16x16x32_bf16 v[96:99], v[178:181], v[194:197], v[96:99]
	v_mfma_f32_16x16x32_bf16 v[88:91], v[148:151], v[202:205], v[88:91]
	v_mfma_f32_16x16x32_bf16 v[80:83], v[178:181], v[202:205], v[80:83]
	v_mfma_f32_16x16x32_bf16 v[72:75], v[148:151], v[218:221], v[72:75]
	v_mfma_f32_16x16x32_bf16 v[64:67], v[178:181], v[218:221], v[64:67]
	s_setprio 0
	s_barrier
	s_add_i32 s0, s60, s51
	v_lshl_add_u64 v[206:207], s[42:43], 0, v[158:159]
	s_mov_b32 m0, s0
	ds_read_b128 v[182:185], v212 offset:16384
	ds_read_b128 v[186:189], v212 offset:17408
	ds_read_b128 v[190:193], v212 offset:18432
	ds_read_b128 v[194:197], v212 offset:19456
	ds_read_b128 v[198:201], v212 offset:20480
	ds_read_b128 v[202:205], v212 offset:21504
	ds_read_b128 v[214:217], v212 offset:22528
	ds_read_b128 v[218:221], v212 offset:23552
	global_load_lds_dwordx4 v[206:207], off
	s_add_i32 m0, s0, 0x2000
	s_add_u32 s0, s42, 0x40000
	v_lshl_add_u64 v[222:223], s[42:43], 0, v[162:163]
	s_addc_u32 s1, s43, 0
	s_add_i32 s34, s61, s51
	global_load_lds_dwordx4 v[222:223], off
	s_mov_b32 m0, s34
	s_nop 0
	global_load_lds_dwordx4 v158, s[0:1]
	s_add_i32 m0, s34, 0x2000
	s_nop 0
	global_load_lds_dwordx4 v162, s[0:1]
	s_nop 0
	s_waitcnt lgkmcnt(0)
	s_barrier
	s_setprio 1
	v_mfma_f32_16x16x32_bf16 v[60:63], v[100:103], v[182:185], 0
	v_mfma_f32_16x16x32_bf16 v[52:55], v[136:139], v[182:185], 0
	v_mfma_f32_16x16x32_bf16 v[44:47], v[100:103], v[190:193], 0
	v_mfma_f32_16x16x32_bf16 v[36:39], v[136:139], v[190:193], 0
	v_mfma_f32_16x16x32_bf16 v[28:31], v[100:103], v[198:201], 0
	v_mfma_f32_16x16x32_bf16 v[20:23], v[136:139], v[198:201], 0
	v_mfma_f32_16x16x32_bf16 v[12:15], v[100:103], v[214:217], 0
	v_mfma_f32_16x16x32_bf16 v[4:7], v[136:139], v[214:217], 0
	v_mfma_f32_16x16x32_bf16 v[60:63], v[116:119], v[186:189], v[60:63]
	v_mfma_f32_16x16x32_bf16 v[52:55], v[140:143], v[186:189], v[52:55]
	v_mfma_f32_16x16x32_bf16 v[44:47], v[116:119], v[194:197], v[44:47]
	v_mfma_f32_16x16x32_bf16 v[36:39], v[140:143], v[194:197], v[36:39]
	v_mfma_f32_16x16x32_bf16 v[28:31], v[116:119], v[202:205], v[28:31]
	v_mfma_f32_16x16x32_bf16 v[20:23], v[140:143], v[202:205], v[20:23]
	v_mfma_f32_16x16x32_bf16 v[12:15], v[116:119], v[218:221], v[12:15]
	v_mfma_f32_16x16x32_bf16 v[4:7], v[140:143], v[218:221], v[4:7]
	v_mfma_f32_16x16x32_bf16 v[56:59], v[144:147], v[182:185], 0
	v_mfma_f32_16x16x32_bf16 v[48:51], v[152:155], v[182:185], 0
	v_mfma_f32_16x16x32_bf16 v[40:43], v[144:147], v[190:193], 0
	v_mfma_f32_16x16x32_bf16 v[32:35], v[152:155], v[190:193], 0
	v_mfma_f32_16x16x32_bf16 v[24:27], v[144:147], v[198:201], 0
	v_mfma_f32_16x16x32_bf16 v[16:19], v[152:155], v[198:201], 0
	v_mfma_f32_16x16x32_bf16 v[8:11], v[144:147], v[214:217], 0
	v_mfma_f32_16x16x32_bf16 v[0:3], v[152:155], v[214:217], 0
	v_mfma_f32_16x16x32_bf16 v[56:59], v[148:151], v[186:189], v[56:59]
	v_mfma_f32_16x16x32_bf16 v[48:51], v[178:181], v[186:189], v[48:51]
	v_mfma_f32_16x16x32_bf16 v[40:43], v[148:151], v[194:197], v[40:43]
	v_mfma_f32_16x16x32_bf16 v[32:35], v[178:181], v[194:197], v[32:35]
	v_mfma_f32_16x16x32_bf16 v[24:27], v[148:151], v[202:205], v[24:27]
	v_mfma_f32_16x16x32_bf16 v[16:19], v[178:181], v[202:205], v[16:19]
	v_mfma_f32_16x16x32_bf16 v[8:11], v[148:151], v[218:221], v[8:11]
	v_mfma_f32_16x16x32_bf16 v[0:3], v[178:181], v[218:221], v[0:3]
	s_setprio 0
	s_barrier
	s_add_i32 s34, 0, 0x18000
	s_add_i32 s35, 0, 0x1c000
	v_add_u32_e32 v140, s34, v209
	v_add_u32_e32 v178, s35, v209
	ds_read_b128 v[100:103], v140
	ds_read_b128 v[116:119], v140 offset:1024
	ds_read_b128 v[136:139], v140 offset:2048
	ds_read_b128 v[140:143], v140 offset:3072
	ds_read_b128 v[144:147], v178
	ds_read_b128 v[148:151], v178 offset:1024
	ds_read_b128 v[152:155], v178 offset:2048
	ds_read_b128 v[178:181], v178 offset:3072
	s_add_u32 s0, s44, 0x1000
	s_addc_u32 s1, s45, 0
	s_mov_b32 m0, s54
	ds_read_b128 v[182:185], v212 offset:32768
	ds_read_b128 v[186:189], v212 offset:33792
	ds_read_b128 v[190:193], v212 offset:34816
	ds_read_b128 v[194:197], v212 offset:35840
	ds_read_b128 v[198:201], v212 offset:36864
	ds_read_b128 v[202:205], v212 offset:37888
	ds_read_b128 v[214:217], v212 offset:38912
	ds_read_b128 v[218:221], v212 offset:39936
	global_load_lds_dwordx4 v156, s[0:1]
	s_mov_b32 m0, s55
	s_nop 0
	global_load_lds_dwordx4 v160, s[0:1]
	s_mov_b32 m0, s52
	s_nop 0
	global_load_lds_dwordx4 v156, s[44:45]
	s_mov_b32 m0, s53
	s_nop 0
	global_load_lds_dwordx4 v160, s[44:45]
	s_waitcnt vmcnt(8)
	s_waitcnt lgkmcnt(0)
	s_barrier
	s_setprio 1
	v_mfma_f32_16x16x32_bf16 v[132:135], v[100:103], v[182:185], v[132:135]
	v_mfma_f32_16x16x32_bf16 v[124:127], v[136:139], v[182:185], v[124:127]
	v_mfma_f32_16x16x32_bf16 v[112:115], v[100:103], v[190:193], v[112:115]
	v_mfma_f32_16x16x32_bf16 v[104:107], v[136:139], v[190:193], v[104:107]
	v_mfma_f32_16x16x32_bf16 v[92:95], v[100:103], v[198:201], v[92:95]
	v_mfma_f32_16x16x32_bf16 v[84:87], v[136:139], v[198:201], v[84:87]
	v_mfma_f32_16x16x32_bf16 v[76:79], v[100:103], v[214:217], v[76:79]
	v_mfma_f32_16x16x32_bf16 v[68:71], v[136:139], v[214:217], v[68:71]
	v_mfma_f32_16x16x32_bf16 v[132:135], v[116:119], v[186:189], v[132:135]
	v_mfma_f32_16x16x32_bf16 v[124:127], v[140:143], v[186:189], v[124:127]
	v_mfma_f32_16x16x32_bf16 v[112:115], v[116:119], v[194:197], v[112:115]
	v_mfma_f32_16x16x32_bf16 v[104:107], v[140:143], v[194:197], v[104:107]
	v_mfma_f32_16x16x32_bf16 v[92:95], v[116:119], v[202:205], v[92:95]
	v_mfma_f32_16x16x32_bf16 v[84:87], v[140:143], v[202:205], v[84:87]
	v_mfma_f32_16x16x32_bf16 v[76:79], v[116:119], v[218:221], v[76:79]
	v_mfma_f32_16x16x32_bf16 v[68:71], v[140:143], v[218:221], v[68:71]
	v_mfma_f32_16x16x32_bf16 v[128:131], v[144:147], v[182:185], v[128:131]
	v_mfma_f32_16x16x32_bf16 v[120:123], v[152:155], v[182:185], v[120:123]
	v_mfma_f32_16x16x32_bf16 v[108:111], v[144:147], v[190:193], v[108:111]
	v_mfma_f32_16x16x32_bf16 v[96:99], v[152:155], v[190:193], v[96:99]
	v_mfma_f32_16x16x32_bf16 v[88:91], v[144:147], v[198:201], v[88:91]
	v_mfma_f32_16x16x32_bf16 v[80:83], v[152:155], v[198:201], v[80:83]
	v_mfma_f32_16x16x32_bf16 v[72:75], v[144:147], v[214:217], v[72:75]
	v_mfma_f32_16x16x32_bf16 v[64:67], v[152:155], v[214:217], v[64:67]
	v_mfma_f32_16x16x32_bf16 v[128:131], v[148:151], v[186:189], v[128:131]
	v_mfma_f32_16x16x32_bf16 v[120:123], v[178:181], v[186:189], v[120:123]
	v_mfma_f32_16x16x32_bf16 v[108:111], v[148:151], v[194:197], v[108:111]
	v_mfma_f32_16x16x32_bf16 v[96:99], v[178:181], v[194:197], v[96:99]
	v_mfma_f32_16x16x32_bf16 v[88:91], v[148:151], v[202:205], v[88:91]
	v_mfma_f32_16x16x32_bf16 v[80:83], v[178:181], v[202:205], v[80:83]
	v_mfma_f32_16x16x32_bf16 v[72:75], v[148:151], v[218:221], v[72:75]
	v_mfma_f32_16x16x32_bf16 v[64:67], v[178:181], v[218:221], v[64:67]
	s_setprio 0
	s_barrier
	s_add_i32 s0, s34, s51
	v_lshl_add_u64 v[206:207], v[206:207], 0, s[16:17]
	s_mov_b32 m0, s0
	ds_read_b128 v[182:185], v212 offset:49152
	ds_read_b128 v[186:189], v212 offset:50176
	ds_read_b128 v[190:193], v212 offset:51200
	ds_read_b128 v[194:197], v212 offset:52224
	ds_read_b128 v[198:201], v212 offset:53248
	ds_read_b128 v[202:205], v212 offset:54272
	ds_read_b128 v[214:217], v212 offset:55296
	ds_read_b128 v[218:221], v212 offset:56320
	global_load_lds_dwordx4 v[206:207], off
	s_add_i32 m0, s0, 0x2000
	s_add_u32 s0, s42, 0x40080
	v_lshl_add_u64 v[206:207], v[222:223], 0, s[16:17]
	s_addc_u32 s1, s43, 0
	s_add_i32 s34, s35, s51
	global_load_lds_dwordx4 v[206:207], off
	s_mov_b32 m0, s34
	s_nop 0
	global_load_lds_dwordx4 v158, s[0:1]
	s_add_i32 m0, s34, 0x2000
	s_nop 0
	global_load_lds_dwordx4 v162, s[0:1]
	s_mov_b32 m0, s56
	s_nop 0
	global_load_lds_dwordx4 v156, s[40:41]
	s_mov_b32 m0, s57
	s_nop 0
	global_load_lds_dwordx4 v160, s[40:41]
	s_waitcnt vmcnt(6)
	s_waitcnt lgkmcnt(0)
	s_barrier
	s_setprio 1
	v_mfma_f32_16x16x32_bf16 v[60:63], v[100:103], v[182:185], v[60:63]
	v_mfma_f32_16x16x32_bf16 v[52:55], v[136:139], v[182:185], v[52:55]
	v_mfma_f32_16x16x32_bf16 v[44:47], v[100:103], v[190:193], v[44:47]
	v_mfma_f32_16x16x32_bf16 v[36:39], v[136:139], v[190:193], v[36:39]
	v_mfma_f32_16x16x32_bf16 v[28:31], v[100:103], v[198:201], v[28:31]
	v_mfma_f32_16x16x32_bf16 v[20:23], v[136:139], v[198:201], v[20:23]
	v_mfma_f32_16x16x32_bf16 v[12:15], v[100:103], v[214:217], v[12:15]
	v_mfma_f32_16x16x32_bf16 v[4:7], v[136:139], v[214:217], v[4:7]
	v_mfma_f32_16x16x32_bf16 v[60:63], v[116:119], v[186:189], v[60:63]
	v_mfma_f32_16x16x32_bf16 v[52:55], v[140:143], v[186:189], v[52:55]
	v_mfma_f32_16x16x32_bf16 v[44:47], v[116:119], v[194:197], v[44:47]
	v_mfma_f32_16x16x32_bf16 v[36:39], v[140:143], v[194:197], v[36:39]
	v_mfma_f32_16x16x32_bf16 v[28:31], v[116:119], v[202:205], v[28:31]
	v_mfma_f32_16x16x32_bf16 v[20:23], v[140:143], v[202:205], v[20:23]
	v_mfma_f32_16x16x32_bf16 v[12:15], v[116:119], v[218:221], v[12:15]
	v_mfma_f32_16x16x32_bf16 v[4:7], v[140:143], v[218:221], v[4:7]
	v_mfma_f32_16x16x32_bf16 v[56:59], v[144:147], v[182:185], v[56:59]
	v_mfma_f32_16x16x32_bf16 v[48:51], v[152:155], v[182:185], v[48:51]
	v_mfma_f32_16x16x32_bf16 v[40:43], v[144:147], v[190:193], v[40:43]
	v_mfma_f32_16x16x32_bf16 v[32:35], v[152:155], v[190:193], v[32:35]
	v_mfma_f32_16x16x32_bf16 v[24:27], v[144:147], v[198:201], v[24:27]
	v_mfma_f32_16x16x32_bf16 v[16:19], v[152:155], v[198:201], v[16:19]
	v_mfma_f32_16x16x32_bf16 v[8:11], v[144:147], v[214:217], v[8:11]
	v_mfma_f32_16x16x32_bf16 v[0:3], v[152:155], v[214:217], v[0:3]
	v_mfma_f32_16x16x32_bf16 v[56:59], v[148:151], v[186:189], v[56:59]
	v_mfma_f32_16x16x32_bf16 v[48:51], v[178:181], v[186:189], v[48:51]
	v_mfma_f32_16x16x32_bf16 v[40:43], v[148:151], v[194:197], v[40:43]
	v_mfma_f32_16x16x32_bf16 v[32:35], v[178:181], v[194:197], v[32:35]
	v_mfma_f32_16x16x32_bf16 v[24:27], v[148:151], v[202:205], v[24:27]
	v_mfma_f32_16x16x32_bf16 v[16:19], v[178:181], v[202:205], v[16:19]
	v_mfma_f32_16x16x32_bf16 v[8:11], v[148:151], v[218:221], v[8:11]
	v_mfma_f32_16x16x32_bf16 v[0:3], v[178:181], v[218:221], v[0:3]
	s_setprio 0
	s_barrier
	s_add_i32 s65, s65, 2
	s_add_u32 s63, s63, 0x100
	s_addc_u32 s64, s64, 0
	s_cmp_gt_u32 s65, 13
	s_mov_b64 s[34:35], s[36:37]
.LBB0_480:
	ds_read_b128 v[100:103], v210
	ds_read_b128 v[116:119], v210 offset:1024
	ds_read_b128 v[136:139], v210 offset:2048
	ds_read_b128 v[140:143], v210 offset:3072
	ds_read_b128 v[144:147], v211
	ds_read_b128 v[148:151], v211 offset:1024
	ds_read_b128 v[152:155], v211 offset:2048
	ds_read_b128 v[178:181], v211 offset:3072
	s_add_u32 s36, s34, 0x1000000
	s_addc_u32 s37, s35, 0
	s_cmp_eq_u32 s65, 12
	s_cselect_b32 s44, s29, s36
	s_cselect_b32 s45, s23, s37
	s_cselect_b32 s42, s31, s63
	s_cselect_b32 s43, s21, s64
	s_add_u32 s40, s44, 0x800000
	s_addc_u32 s41, s45, 0
	s_add_i32 m0, s52, 0xc000
	ds_read_b128 v[182:185], v212
	ds_read_b128 v[186:189], v212 offset:1024
	ds_read_b128 v[190:193], v212 offset:2048
	ds_read_b128 v[194:197], v212 offset:3072
	ds_read_b128 v[198:201], v212 offset:4096
	ds_read_b128 v[202:205], v212 offset:5120
	ds_read_b128 v[214:217], v212 offset:6144
	ds_read_b128 v[218:221], v212 offset:7168
	global_load_lds_dwordx4 v170, s[34:35]
	s_add_i32 m0, s52, 0xe000
	s_nop 0
	global_load_lds_dwordx4 v172, s[34:35]
	s_waitcnt vmcnt(8)
	s_waitcnt lgkmcnt(0)
	s_barrier
	s_setprio 1
	v_mfma_f32_16x16x32_bf16 v[132:135], v[100:103], v[182:185], v[132:135]
	v_mfma_f32_16x16x32_bf16 v[124:127], v[136:139], v[182:185], v[124:127]
	v_mfma_f32_16x16x32_bf16 v[112:115], v[100:103], v[190:193], v[112:115]
	v_mfma_f32_16x16x32_bf16 v[104:107], v[136:139], v[190:193], v[104:107]
	v_mfma_f32_16x16x32_bf16 v[92:95], v[100:103], v[198:201], v[92:95]
	v_mfma_f32_16x16x32_bf16 v[84:87], v[136:139], v[198:201], v[84:87]
	v_mfma_f32_16x16x32_bf16 v[76:79], v[100:103], v[214:217], v[76:79]
	v_mfma_f32_16x16x32_bf16 v[68:71], v[136:139], v[214:217], v[68:71]
	v_mfma_f32_16x16x32_bf16 v[132:135], v[116:119], v[186:189], v[132:135]
	v_mfma_f32_16x16x32_bf16 v[124:127], v[140:143], v[186:189], v[124:127]
	v_mfma_f32_16x16x32_bf16 v[112:115], v[116:119], v[194:197], v[112:115]
	v_mfma_f32_16x16x32_bf16 v[104:107], v[140:143], v[194:197], v[104:107]
	v_mfma_f32_16x16x32_bf16 v[92:95], v[116:119], v[202:205], v[92:95]
	v_mfma_f32_16x16x32_bf16 v[84:87], v[140:143], v[202:205], v[84:87]
	v_mfma_f32_16x16x32_bf16 v[76:79], v[116:119], v[218:221], v[76:79]
	v_mfma_f32_16x16x32_bf16 v[68:71], v[140:143], v[218:221], v[68:71]
	v_mfma_f32_16x16x32_bf16 v[128:131], v[144:147], v[182:185], v[128:131]
	v_mfma_f32_16x16x32_bf16 v[120:123], v[152:155], v[182:185], v[120:123]
	v_mfma_f32_16x16x32_bf16 v[108:111], v[144:147], v[190:193], v[108:111]
	v_mfma_f32_16x16x32_bf16 v[96:99], v[152:155], v[190:193], v[96:99]
	v_mfma_f32_16x16x32_bf16 v[88:91], v[144:147], v[198:201], v[88:91]
	v_mfma_f32_16x16x32_bf16 v[80:83], v[152:155], v[198:201], v[80:83]
	v_mfma_f32_16x16x32_bf16 v[72:75], v[144:147], v[214:217], v[72:75]
	v_mfma_f32_16x16x32_bf16 v[64:67], v[152:155], v[214:217], v[64:67]
	v_mfma_f32_16x16x32_bf16 v[128:131], v[148:151], v[186:189], v[128:131]
	v_mfma_f32_16x16x32_bf16 v[120:123], v[178:181], v[186:189], v[120:123]
	v_mfma_f32_16x16x32_bf16 v[108:111], v[148:151], v[194:197], v[108:111]
	v_mfma_f32_16x16x32_bf16 v[96:99], v[178:181], v[194:197], v[96:99]
	v_mfma_f32_16x16x32_bf16 v[88:91], v[148:151], v[202:205], v[88:91]
	v_mfma_f32_16x16x32_bf16 v[80:83], v[178:181], v[202:205], v[80:83]
	v_mfma_f32_16x16x32_bf16 v[72:75], v[148:151], v[218:221], v[72:75]
	v_mfma_f32_16x16x32_bf16 v[64:67], v[178:181], v[218:221], v[64:67]
	s_setprio 0
	s_barrier
	s_add_i32 s0, s60, s51
	v_lshl_add_u64 v[206:207], s[42:43], 0, v[158:159]
	s_mov_b32 m0, s0
	ds_read_b128 v[182:185], v212 offset:16384
	ds_read_b128 v[186:189], v212 offset:17408
	ds_read_b128 v[190:193], v212 offset:18432
	ds_read_b128 v[194:197], v212 offset:19456
	ds_read_b128 v[198:201], v212 offset:20480
	ds_read_b128 v[202:205], v212 offset:21504
	ds_read_b128 v[214:217], v212 offset:22528
	ds_read_b128 v[218:221], v212 offset:23552
	global_load_lds_dwordx4 v[206:207], off
	s_add_i32 m0, s0, 0x2000
	s_add_u32 s0, s42, 0x40000
	v_lshl_add_u64 v[222:223], s[42:43], 0, v[162:163]
	s_addc_u32 s1, s43, 0
	s_add_i32 s34, s61, s51
	global_load_lds_dwordx4 v[222:223], off
	s_mov_b32 m0, s34
	s_nop 0
	global_load_lds_dwordx4 v158, s[0:1]
	s_add_i32 m0, s34, 0x2000
	s_nop 0
	global_load_lds_dwordx4 v162, s[0:1]
	s_waitcnt vmcnt(6)
	s_waitcnt lgkmcnt(0)
	s_barrier
	s_setprio 1
	v_mfma_f32_16x16x32_bf16 v[60:63], v[100:103], v[182:185], v[60:63]
	v_mfma_f32_16x16x32_bf16 v[52:55], v[136:139], v[182:185], v[52:55]
	v_mfma_f32_16x16x32_bf16 v[44:47], v[100:103], v[190:193], v[44:47]
	v_mfma_f32_16x16x32_bf16 v[36:39], v[136:139], v[190:193], v[36:39]
	v_mfma_f32_16x16x32_bf16 v[28:31], v[100:103], v[198:201], v[28:31]
	v_mfma_f32_16x16x32_bf16 v[20:23], v[136:139], v[198:201], v[20:23]
	v_mfma_f32_16x16x32_bf16 v[12:15], v[100:103], v[214:217], v[12:15]
	v_mfma_f32_16x16x32_bf16 v[4:7], v[136:139], v[214:217], v[4:7]
	v_mfma_f32_16x16x32_bf16 v[60:63], v[116:119], v[186:189], v[60:63]
	v_mfma_f32_16x16x32_bf16 v[52:55], v[140:143], v[186:189], v[52:55]
	v_mfma_f32_16x16x32_bf16 v[44:47], v[116:119], v[194:197], v[44:47]
	v_mfma_f32_16x16x32_bf16 v[36:39], v[140:143], v[194:197], v[36:39]
	v_mfma_f32_16x16x32_bf16 v[28:31], v[116:119], v[202:205], v[28:31]
	v_mfma_f32_16x16x32_bf16 v[20:23], v[140:143], v[202:205], v[20:23]
	v_mfma_f32_16x16x32_bf16 v[12:15], v[116:119], v[218:221], v[12:15]
	v_mfma_f32_16x16x32_bf16 v[4:7], v[140:143], v[218:221], v[4:7]
	v_mfma_f32_16x16x32_bf16 v[56:59], v[144:147], v[182:185], v[56:59]
	v_mfma_f32_16x16x32_bf16 v[48:51], v[152:155], v[182:185], v[48:51]
	v_mfma_f32_16x16x32_bf16 v[40:43], v[144:147], v[190:193], v[40:43]
	v_mfma_f32_16x16x32_bf16 v[32:35], v[152:155], v[190:193], v[32:35]
	v_mfma_f32_16x16x32_bf16 v[24:27], v[144:147], v[198:201], v[24:27]
	v_mfma_f32_16x16x32_bf16 v[16:19], v[152:155], v[198:201], v[16:19]
	v_mfma_f32_16x16x32_bf16 v[8:11], v[144:147], v[214:217], v[8:11]
	v_mfma_f32_16x16x32_bf16 v[0:3], v[152:155], v[214:217], v[0:3]
	v_mfma_f32_16x16x32_bf16 v[56:59], v[148:151], v[186:189], v[56:59]
	v_mfma_f32_16x16x32_bf16 v[48:51], v[178:181], v[186:189], v[48:51]
	v_mfma_f32_16x16x32_bf16 v[40:43], v[148:151], v[194:197], v[40:43]
	v_mfma_f32_16x16x32_bf16 v[32:35], v[178:181], v[194:197], v[32:35]
	v_mfma_f32_16x16x32_bf16 v[24:27], v[148:151], v[202:205], v[24:27]
	v_mfma_f32_16x16x32_bf16 v[16:19], v[178:181], v[202:205], v[16:19]
	v_mfma_f32_16x16x32_bf16 v[8:11], v[148:151], v[218:221], v[8:11]
	v_mfma_f32_16x16x32_bf16 v[0:3], v[178:181], v[218:221], v[0:3]
	s_setprio 0
	s_barrier
	s_add_i32 s34, 0, 0x18000
	s_add_i32 s35, 0, 0x1c000
	v_add_u32_e32 v140, s34, v209
	v_add_u32_e32 v178, s35, v209
	ds_read_b128 v[100:103], v140
	ds_read_b128 v[116:119], v140 offset:1024
	ds_read_b128 v[136:139], v140 offset:2048
	ds_read_b128 v[140:143], v140 offset:3072
	ds_read_b128 v[144:147], v178
	ds_read_b128 v[148:151], v178 offset:1024
	ds_read_b128 v[152:155], v178 offset:2048
	ds_read_b128 v[178:181], v178 offset:3072
	s_add_u32 s0, s44, 0x1000
	s_addc_u32 s1, s45, 0
	s_mov_b32 m0, s54
	ds_read_b128 v[182:185], v212 offset:32768
	ds_read_b128 v[186:189], v212 offset:33792
	ds_read_b128 v[190:193], v212 offset:34816
	ds_read_b128 v[194:197], v212 offset:35840
	ds_read_b128 v[198:201], v212 offset:36864
	ds_read_b128 v[202:205], v212 offset:37888
	ds_read_b128 v[214:217], v212 offset:38912
	ds_read_b128 v[218:221], v212 offset:39936
	global_load_lds_dwordx4 v156, s[0:1]
	s_mov_b32 m0, s55
	s_nop 0
	global_load_lds_dwordx4 v160, s[0:1]
	s_mov_b32 m0, s52
	s_nop 0
	global_load_lds_dwordx4 v156, s[44:45]
	s_mov_b32 m0, s53
	s_nop 0
	global_load_lds_dwordx4 v160, s[44:45]
	s_waitcnt vmcnt(8)
	s_waitcnt lgkmcnt(0)
	s_barrier
	s_setprio 1
	v_mfma_f32_16x16x32_bf16 v[132:135], v[100:103], v[182:185], v[132:135]
	v_mfma_f32_16x16x32_bf16 v[124:127], v[136:139], v[182:185], v[124:127]
	v_mfma_f32_16x16x32_bf16 v[112:115], v[100:103], v[190:193], v[112:115]
	v_mfma_f32_16x16x32_bf16 v[104:107], v[136:139], v[190:193], v[104:107]
	v_mfma_f32_16x16x32_bf16 v[92:95], v[100:103], v[198:201], v[92:95]
	v_mfma_f32_16x16x32_bf16 v[84:87], v[136:139], v[198:201], v[84:87]
	v_mfma_f32_16x16x32_bf16 v[76:79], v[100:103], v[214:217], v[76:79]
	v_mfma_f32_16x16x32_bf16 v[68:71], v[136:139], v[214:217], v[68:71]
	v_mfma_f32_16x16x32_bf16 v[132:135], v[116:119], v[186:189], v[132:135]
	v_mfma_f32_16x16x32_bf16 v[124:127], v[140:143], v[186:189], v[124:127]
	v_mfma_f32_16x16x32_bf16 v[112:115], v[116:119], v[194:197], v[112:115]
	v_mfma_f32_16x16x32_bf16 v[104:107], v[140:143], v[194:197], v[104:107]
	v_mfma_f32_16x16x32_bf16 v[92:95], v[116:119], v[202:205], v[92:95]
	v_mfma_f32_16x16x32_bf16 v[84:87], v[140:143], v[202:205], v[84:87]
	v_mfma_f32_16x16x32_bf16 v[76:79], v[116:119], v[218:221], v[76:79]
	v_mfma_f32_16x16x32_bf16 v[68:71], v[140:143], v[218:221], v[68:71]
	v_mfma_f32_16x16x32_bf16 v[128:131], v[144:147], v[182:185], v[128:131]
	v_mfma_f32_16x16x32_bf16 v[120:123], v[152:155], v[182:185], v[120:123]
	v_mfma_f32_16x16x32_bf16 v[108:111], v[144:147], v[190:193], v[108:111]
	v_mfma_f32_16x16x32_bf16 v[96:99], v[152:155], v[190:193], v[96:99]
	v_mfma_f32_16x16x32_bf16 v[88:91], v[144:147], v[198:201], v[88:91]
	v_mfma_f32_16x16x32_bf16 v[80:83], v[152:155], v[198:201], v[80:83]
	v_mfma_f32_16x16x32_bf16 v[72:75], v[144:147], v[214:217], v[72:75]
	v_mfma_f32_16x16x32_bf16 v[64:67], v[152:155], v[214:217], v[64:67]
	v_mfma_f32_16x16x32_bf16 v[128:131], v[148:151], v[186:189], v[128:131]
	v_mfma_f32_16x16x32_bf16 v[120:123], v[178:181], v[186:189], v[120:123]
	v_mfma_f32_16x16x32_bf16 v[108:111], v[148:151], v[194:197], v[108:111]
	v_mfma_f32_16x16x32_bf16 v[96:99], v[178:181], v[194:197], v[96:99]
	v_mfma_f32_16x16x32_bf16 v[88:91], v[148:151], v[202:205], v[88:91]
	v_mfma_f32_16x16x32_bf16 v[80:83], v[178:181], v[202:205], v[80:83]
	v_mfma_f32_16x16x32_bf16 v[72:75], v[148:151], v[218:221], v[72:75]
	v_mfma_f32_16x16x32_bf16 v[64:67], v[178:181], v[218:221], v[64:67]
	s_setprio 0
	s_barrier
	s_add_i32 s0, s34, s51
	v_lshl_add_u64 v[206:207], v[206:207], 0, s[16:17]
	s_mov_b32 m0, s0
	ds_read_b128 v[182:185], v212 offset:49152
	ds_read_b128 v[186:189], v212 offset:50176
	ds_read_b128 v[190:193], v212 offset:51200
	ds_read_b128 v[194:197], v212 offset:52224
	ds_read_b128 v[198:201], v212 offset:53248
	ds_read_b128 v[202:205], v212 offset:54272
	ds_read_b128 v[214:217], v212 offset:55296
	ds_read_b128 v[218:221], v212 offset:56320
	global_load_lds_dwordx4 v[206:207], off
	s_add_i32 m0, s0, 0x2000
	s_add_u32 s0, s42, 0x40080
	v_lshl_add_u64 v[206:207], v[222:223], 0, s[16:17]
	s_addc_u32 s1, s43, 0
	s_add_i32 s34, s35, s51
	global_load_lds_dwordx4 v[206:207], off
	s_mov_b32 m0, s34
	s_nop 0
	global_load_lds_dwordx4 v158, s[0:1]
	s_add_i32 m0, s34, 0x2000
	s_nop 0
	global_load_lds_dwordx4 v162, s[0:1]
	s_mov_b32 m0, s56
	s_nop 0
	global_load_lds_dwordx4 v156, s[40:41]
	s_mov_b32 m0, s57
	s_nop 0
	global_load_lds_dwordx4 v160, s[40:41]
	s_waitcnt vmcnt(6)
	s_waitcnt lgkmcnt(0)
	s_barrier
	s_setprio 1
	v_mfma_f32_16x16x32_bf16 v[60:63], v[100:103], v[182:185], v[60:63]
	v_mfma_f32_16x16x32_bf16 v[52:55], v[136:139], v[182:185], v[52:55]
	v_mfma_f32_16x16x32_bf16 v[44:47], v[100:103], v[190:193], v[44:47]
	v_mfma_f32_16x16x32_bf16 v[36:39], v[136:139], v[190:193], v[36:39]
	v_mfma_f32_16x16x32_bf16 v[28:31], v[100:103], v[198:201], v[28:31]
	v_mfma_f32_16x16x32_bf16 v[20:23], v[136:139], v[198:201], v[20:23]
	v_mfma_f32_16x16x32_bf16 v[12:15], v[100:103], v[214:217], v[12:15]
	v_mfma_f32_16x16x32_bf16 v[4:7], v[136:139], v[214:217], v[4:7]
	v_mfma_f32_16x16x32_bf16 v[60:63], v[116:119], v[186:189], v[60:63]
	v_mfma_f32_16x16x32_bf16 v[52:55], v[140:143], v[186:189], v[52:55]
	v_mfma_f32_16x16x32_bf16 v[44:47], v[116:119], v[194:197], v[44:47]
	v_mfma_f32_16x16x32_bf16 v[36:39], v[140:143], v[194:197], v[36:39]
	v_mfma_f32_16x16x32_bf16 v[28:31], v[116:119], v[202:205], v[28:31]
	v_mfma_f32_16x16x32_bf16 v[20:23], v[140:143], v[202:205], v[20:23]
	v_mfma_f32_16x16x32_bf16 v[12:15], v[116:119], v[218:221], v[12:15]
	v_mfma_f32_16x16x32_bf16 v[4:7], v[140:143], v[218:221], v[4:7]
	v_mfma_f32_16x16x32_bf16 v[56:59], v[144:147], v[182:185], v[56:59]
	v_mfma_f32_16x16x32_bf16 v[48:51], v[152:155], v[182:185], v[48:51]
	v_mfma_f32_16x16x32_bf16 v[40:43], v[144:147], v[190:193], v[40:43]
	v_mfma_f32_16x16x32_bf16 v[32:35], v[152:155], v[190:193], v[32:35]
	v_mfma_f32_16x16x32_bf16 v[24:27], v[144:147], v[198:201], v[24:27]
	v_mfma_f32_16x16x32_bf16 v[16:19], v[152:155], v[198:201], v[16:19]
	v_mfma_f32_16x16x32_bf16 v[8:11], v[144:147], v[214:217], v[8:11]
	v_mfma_f32_16x16x32_bf16 v[0:3], v[152:155], v[214:217], v[0:3]
	v_mfma_f32_16x16x32_bf16 v[56:59], v[148:151], v[186:189], v[56:59]
	v_mfma_f32_16x16x32_bf16 v[48:51], v[178:181], v[186:189], v[48:51]
	v_mfma_f32_16x16x32_bf16 v[40:43], v[148:151], v[194:197], v[40:43]
	v_mfma_f32_16x16x32_bf16 v[32:35], v[178:181], v[194:197], v[32:35]
	v_mfma_f32_16x16x32_bf16 v[24:27], v[148:151], v[202:205], v[24:27]
	v_mfma_f32_16x16x32_bf16 v[16:19], v[178:181], v[202:205], v[16:19]
	v_mfma_f32_16x16x32_bf16 v[8:11], v[148:151], v[218:221], v[8:11]
	v_mfma_f32_16x16x32_bf16 v[0:3], v[178:181], v[218:221], v[0:3]
	s_setprio 0
	s_barrier
	s_add_i32 s65, s65, 2
	s_add_u32 s63, s63, 0x100
	s_addc_u32 s64, s64, 0
	s_cmp_gt_u32 s65, 13
	s_mov_b64 s[34:35], s[36:37]
	s_cbranch_scc0 .LBB0_480
	s_and_b64 vcc, exec, s[18:19]
	s_cbranch_vccz .LBB0_483
	s_barrier

.Lrestag_577:
	s_add_u32 s52, s50, 0x100
	s_addc_u32 s53, s51, 0
	s_add_i32 s0, 0, 0x10000
	s_cmp_eq_u32 s76, 12
	s_cselect_b32 s57, s43, s53
	s_cselect_b32 s56, s67, s52
	s_cselect_b32 s55, s41, s75
	s_cselect_b32 s54, s68, s69
	s_add_i32 s12, 0, 0x14000
	v_add_u32_e32 v154, s0, v188
	v_add_u32_e32 v166, s12, v188
	ds_read_b128 v[142:145], v154
	ds_read_b128 v[146:149], v154 offset:1024
	ds_read_b128 v[150:153], v154 offset:2048
	ds_read_b128 v[154:157], v154 offset:3072
	ds_read_b128 v[158:161], v166
	ds_read_b128 v[162:165], v166 offset:1024
	ds_read_b128 v[184:187], v166 offset:2048
	ds_read_b128 v[190:193], v166 offset:3072
	s_add_i32 m0, s49, 0xc000
	ds_read_b128 v[194:197], v189
	ds_read_b128 v[198:201], v189 offset:1024
	ds_read_b128 v[202:205], v189 offset:2048
	ds_read_b128 v[206:209], v189 offset:3072
	ds_read_b128 v[210:213], v189 offset:4096
	ds_read_b128 v[214:217], v189 offset:5120
	ds_read_b128 v[228:231], v189 offset:6144
	ds_read_b128 v[232:235], v189 offset:7168
	global_load_lds_dwordx4 v138, s[50:51]
	s_add_i32 m0, s49, 0xe000
	s_nop 0
	global_load_lds_dwordx4 v140, s[50:51]
	s_nop 0
	s_waitcnt lgkmcnt(0)
	s_barrier
	s_setprio 1
	v_mfma_f32_16x16x32_bf16 v[124:127], v[142:145], v[194:197], 0
	v_mfma_f32_16x16x32_bf16 v[120:123], v[150:153], v[194:197], 0
	v_mfma_f32_16x16x32_bf16 v[108:111], v[142:145], v[202:205], 0
	v_mfma_f32_16x16x32_bf16 v[104:107], v[150:153], v[202:205], 0
	v_mfma_f32_16x16x32_bf16 v[92:95], v[142:145], v[210:213], 0
	v_mfma_f32_16x16x32_bf16 v[88:91], v[150:153], v[210:213], 0
	v_mfma_f32_16x16x32_bf16 v[76:79], v[142:145], v[228:231], 0
	v_mfma_f32_16x16x32_bf16 v[72:75], v[150:153], v[228:231], 0
	v_mfma_f32_16x16x32_bf16 v[124:127], v[146:149], v[198:201], v[124:127]
	v_mfma_f32_16x16x32_bf16 v[120:123], v[154:157], v[198:201], v[120:123]
	v_mfma_f32_16x16x32_bf16 v[108:111], v[146:149], v[206:209], v[108:111]
	v_mfma_f32_16x16x32_bf16 v[104:107], v[154:157], v[206:209], v[104:107]
	v_mfma_f32_16x16x32_bf16 v[92:95], v[146:149], v[214:217], v[92:95]
	v_mfma_f32_16x16x32_bf16 v[88:91], v[154:157], v[214:217], v[88:91]
	v_mfma_f32_16x16x32_bf16 v[76:79], v[146:149], v[232:235], v[76:79]
	v_mfma_f32_16x16x32_bf16 v[72:75], v[154:157], v[232:235], v[72:75]
	v_mfma_f32_16x16x32_bf16 v[116:119], v[158:161], v[194:197], 0
	v_mfma_f32_16x16x32_bf16 v[112:115], v[184:187], v[194:197], 0
	v_mfma_f32_16x16x32_bf16 v[100:103], v[158:161], v[202:205], 0
	v_mfma_f32_16x16x32_bf16 v[96:99], v[184:187], v[202:205], 0
	v_mfma_f32_16x16x32_bf16 v[84:87], v[158:161], v[210:213], 0
	v_mfma_f32_16x16x32_bf16 v[80:83], v[184:187], v[210:213], 0
	v_mfma_f32_16x16x32_bf16 v[68:71], v[158:161], v[228:231], 0
	v_mfma_f32_16x16x32_bf16 v[64:67], v[184:187], v[228:231], 0
	v_mfma_f32_16x16x32_bf16 v[116:119], v[162:165], v[198:201], v[116:119]
	v_mfma_f32_16x16x32_bf16 v[112:115], v[190:193], v[198:201], v[112:115]
	v_mfma_f32_16x16x32_bf16 v[100:103], v[162:165], v[206:209], v[100:103]
	v_mfma_f32_16x16x32_bf16 v[96:99], v[190:193], v[206:209], v[96:99]
	v_mfma_f32_16x16x32_bf16 v[84:87], v[162:165], v[214:217], v[84:87]
	v_mfma_f32_16x16x32_bf16 v[80:83], v[190:193], v[214:217], v[80:83]
	v_mfma_f32_16x16x32_bf16 v[68:71], v[162:165], v[232:235], v[68:71]
	v_mfma_f32_16x16x32_bf16 v[64:67], v[190:193], v[232:235], v[64:67]
	s_setprio 0
	s_barrier
	s_add_i32 s0, s0, s59
	v_lshl_add_u64 v[166:167], s[54:55], 0, v[130:131]
	s_mov_b32 m0, s0
	ds_read_b128 v[194:197], v189 offset:16384
	ds_read_b128 v[198:201], v189 offset:17408
	ds_read_b128 v[202:205], v189 offset:18432
	ds_read_b128 v[206:209], v189 offset:19456
	ds_read_b128 v[210:213], v189 offset:20480
	ds_read_b128 v[214:217], v189 offset:21504
	ds_read_b128 v[228:231], v189 offset:22528
	ds_read_b128 v[232:235], v189 offset:23552
	global_load_lds_dwordx4 v[166:167], off
	s_add_i32 m0, s0, 0x2000
	s_add_u32 s0, s54, 0x40000
	v_lshl_add_u64 v[218:219], s[54:55], 0, v[134:135]
	s_addc_u32 s1, s55, 0
	s_add_i32 s12, s12, s59
	global_load_lds_dwordx4 v[218:219], off
	s_mov_b32 m0, s12
	v_lshl_add_u64 v[238:239], s[56:57], 0, v[132:133]
	global_load_lds_dwordx4 v130, s[0:1]
	s_add_i32 m0, s12, 0x2000
	s_nop 0
	global_load_lds_dwordx4 v134, s[0:1]
	v_lshl_add_u64 v[236:237], s[56:57], 0, v[128:129]
	s_nop 0
	s_waitcnt lgkmcnt(0)
	s_barrier
	s_setprio 1
	v_mfma_f32_16x16x32_bf16 v[60:63], v[142:145], v[194:197], 0
	v_mfma_f32_16x16x32_bf16 v[56:59], v[150:153], v[194:197], 0
	v_mfma_f32_16x16x32_bf16 v[44:47], v[142:145], v[202:205], 0
	v_mfma_f32_16x16x32_bf16 v[40:43], v[150:153], v[202:205], 0
	v_mfma_f32_16x16x32_bf16 v[28:31], v[142:145], v[210:213], 0
	v_mfma_f32_16x16x32_bf16 v[24:27], v[150:153], v[210:213], 0
	v_mfma_f32_16x16x32_bf16 v[12:15], v[142:145], v[228:231], 0
	v_mfma_f32_16x16x32_bf16 v[8:11], v[150:153], v[228:231], 0
	v_mfma_f32_16x16x32_bf16 v[60:63], v[146:149], v[198:201], v[60:63]
	v_mfma_f32_16x16x32_bf16 v[56:59], v[154:157], v[198:201], v[56:59]
	v_mfma_f32_16x16x32_bf16 v[44:47], v[146:149], v[206:209], v[44:47]
	v_mfma_f32_16x16x32_bf16 v[40:43], v[154:157], v[206:209], v[40:43]
	v_mfma_f32_16x16x32_bf16 v[28:31], v[146:149], v[214:217], v[28:31]
	v_mfma_f32_16x16x32_bf16 v[24:27], v[154:157], v[214:217], v[24:27]
	v_mfma_f32_16x16x32_bf16 v[12:15], v[146:149], v[232:235], v[12:15]
	v_mfma_f32_16x16x32_bf16 v[8:11], v[154:157], v[232:235], v[8:11]
	v_mfma_f32_16x16x32_bf16 v[52:55], v[158:161], v[194:197], 0
	v_mfma_f32_16x16x32_bf16 v[48:51], v[184:187], v[194:197], 0
	v_mfma_f32_16x16x32_bf16 v[36:39], v[158:161], v[202:205], 0
	v_mfma_f32_16x16x32_bf16 v[32:35], v[184:187], v[202:205], 0
	v_mfma_f32_16x16x32_bf16 v[20:23], v[158:161], v[210:213], 0
	v_mfma_f32_16x16x32_bf16 v[16:19], v[184:187], v[210:213], 0
	v_mfma_f32_16x16x32_bf16 v[4:7], v[158:161], v[228:231], 0
	v_mfma_f32_16x16x32_bf16 v[0:3], v[184:187], v[228:231], 0
	v_mfma_f32_16x16x32_bf16 v[52:55], v[162:165], v[198:201], v[52:55]
	v_mfma_f32_16x16x32_bf16 v[48:51], v[190:193], v[198:201], v[48:51]
	v_mfma_f32_16x16x32_bf16 v[36:39], v[162:165], v[206:209], v[36:39]
	v_mfma_f32_16x16x32_bf16 v[32:35], v[190:193], v[206:209], v[32:35]
	v_mfma_f32_16x16x32_bf16 v[20:23], v[162:165], v[214:217], v[20:23]
	v_mfma_f32_16x16x32_bf16 v[16:19], v[190:193], v[214:217], v[16:19]
	v_mfma_f32_16x16x32_bf16 v[4:7], v[162:165], v[232:235], v[4:7]
	v_mfma_f32_16x16x32_bf16 v[0:3], v[190:193], v[232:235], v[0:3]
	s_setprio 0
	s_barrier
	s_add_i32 s12, 0, 0x18000
	s_add_i32 s13, 0, 0x1c000
	v_add_u32_e32 v154, s12, v188
	v_add_u32_e32 v170, s13, v188
	ds_read_b128 v[142:145], v154
	ds_read_b128 v[146:149], v154 offset:1024
	ds_read_b128 v[150:153], v154 offset:2048
	ds_read_b128 v[154:157], v154 offset:3072
	ds_read_b128 v[158:161], v170
	ds_read_b128 v[162:165], v170 offset:1024
	ds_read_b128 v[184:187], v170 offset:2048
	ds_read_b128 v[190:193], v170 offset:3072
	s_add_u32 s0, s56, 0x40000
	s_addc_u32 s1, s57, 0
	s_mov_b32 m0, s61
	ds_read_b128 v[194:197], v189 offset:32768
	ds_read_b128 v[198:201], v189 offset:33792
	ds_read_b128 v[202:205], v189 offset:34816
	ds_read_b128 v[206:209], v189 offset:35840
	ds_read_b128 v[210:213], v189 offset:36864
	ds_read_b128 v[214:217], v189 offset:37888
	ds_read_b128 v[228:231], v189 offset:38912
	ds_read_b128 v[232:235], v189 offset:39936
	global_load_lds_dwordx4 v128, s[0:1]
	s_mov_b32 m0, s62
	s_nop 0
	global_load_lds_dwordx4 v132, s[0:1]
	s_mov_b32 m0, s49
	s_nop 0
	global_load_lds_dwordx4 v[236:237], off
	s_mov_b32 m0, s60
	s_nop 0
	global_load_lds_dwordx4 v[238:239], off
	s_waitcnt vmcnt(8)
	s_waitcnt lgkmcnt(0)
	s_barrier
	s_setprio 1
	v_mfma_f32_16x16x32_bf16 v[124:127], v[142:145], v[194:197], v[124:127]
	v_mfma_f32_16x16x32_bf16 v[120:123], v[150:153], v[194:197], v[120:123]
	v_mfma_f32_16x16x32_bf16 v[108:111], v[142:145], v[202:205], v[108:111]
	v_mfma_f32_16x16x32_bf16 v[104:107], v[150:153], v[202:205], v[104:107]
	v_mfma_f32_16x16x32_bf16 v[92:95], v[142:145], v[210:213], v[92:95]
	v_mfma_f32_16x16x32_bf16 v[88:91], v[150:153], v[210:213], v[88:91]
	v_mfma_f32_16x16x32_bf16 v[76:79], v[142:145], v[228:231], v[76:79]
	v_mfma_f32_16x16x32_bf16 v[72:75], v[150:153], v[228:231], v[72:75]
	v_mfma_f32_16x16x32_bf16 v[124:127], v[146:149], v[198:201], v[124:127]
	v_mfma_f32_16x16x32_bf16 v[120:123], v[154:157], v[198:201], v[120:123]
	v_mfma_f32_16x16x32_bf16 v[108:111], v[146:149], v[206:209], v[108:111]
	v_mfma_f32_16x16x32_bf16 v[104:107], v[154:157], v[206:209], v[104:107]
	v_mfma_f32_16x16x32_bf16 v[92:95], v[146:149], v[214:217], v[92:95]
	v_mfma_f32_16x16x32_bf16 v[88:91], v[154:157], v[214:217], v[88:91]
	v_mfma_f32_16x16x32_bf16 v[76:79], v[146:149], v[232:235], v[76:79]
	v_mfma_f32_16x16x32_bf16 v[72:75], v[154:157], v[232:235], v[72:75]
	v_mfma_f32_16x16x32_bf16 v[116:119], v[158:161], v[194:197], v[116:119]
	v_mfma_f32_16x16x32_bf16 v[112:115], v[184:187], v[194:197], v[112:115]
	v_mfma_f32_16x16x32_bf16 v[100:103], v[158:161], v[202:205], v[100:103]
	v_mfma_f32_16x16x32_bf16 v[96:99], v[184:187], v[202:205], v[96:99]
	v_mfma_f32_16x16x32_bf16 v[84:87], v[158:161], v[210:213], v[84:87]
	v_mfma_f32_16x16x32_bf16 v[80:83], v[184:187], v[210:213], v[80:83]
	v_mfma_f32_16x16x32_bf16 v[68:71], v[158:161], v[228:231], v[68:71]
	v_mfma_f32_16x16x32_bf16 v[64:67], v[184:187], v[228:231], v[64:67]
	v_mfma_f32_16x16x32_bf16 v[116:119], v[162:165], v[198:201], v[116:119]
	v_mfma_f32_16x16x32_bf16 v[112:115], v[190:193], v[198:201], v[112:115]
	v_mfma_f32_16x16x32_bf16 v[100:103], v[162:165], v[206:209], v[100:103]
	v_mfma_f32_16x16x32_bf16 v[96:99], v[190:193], v[206:209], v[96:99]
	v_mfma_f32_16x16x32_bf16 v[84:87], v[162:165], v[214:217], v[84:87]
	v_mfma_f32_16x16x32_bf16 v[80:83], v[190:193], v[214:217], v[80:83]
	v_mfma_f32_16x16x32_bf16 v[68:71], v[162:165], v[232:235], v[68:71]
	v_mfma_f32_16x16x32_bf16 v[64:67], v[190:193], v[232:235], v[64:67]
	s_setprio 0
	s_barrier
	s_add_i32 s0, s12, s59
	v_lshl_add_u64 v[166:167], v[166:167], 0, s[16:17]
	s_mov_b32 m0, s0
	ds_read_b128 v[194:197], v189 offset:49152
	ds_read_b128 v[198:201], v189 offset:50176
	ds_read_b128 v[202:205], v189 offset:51200
	ds_read_b128 v[206:209], v189 offset:52224
	ds_read_b128 v[210:213], v189 offset:53248
	ds_read_b128 v[214:217], v189 offset:54272
	ds_read_b128 v[228:231], v189 offset:55296
	ds_read_b128 v[232:235], v189 offset:56320
	global_load_lds_dwordx4 v[166:167], off
	s_add_i32 m0, s0, 0x2000
	s_add_u32 s0, s54, 0x40080
	v_lshl_add_u64 v[166:167], v[218:219], 0, s[16:17]
	s_addc_u32 s1, s55, 0
	s_add_i32 s12, s13, s59
	global_load_lds_dwordx4 v[166:167], off
	s_mov_b32 m0, s12
	s_nop 0
	global_load_lds_dwordx4 v130, s[0:1]
	s_add_i32 m0, s12, 0x2000
	s_nop 0
	global_load_lds_dwordx4 v134, s[0:1]
	v_lshl_add_u64 v[166:167], v[236:237], 0, s[16:17]
	s_mov_b32 m0, s64
	s_nop 0
	global_load_lds_dwordx4 v[166:167], off
	v_lshl_add_u64 v[166:167], v[238:239], 0, s[16:17]
	s_mov_b32 m0, s65
	s_nop 0
	global_load_lds_dwordx4 v[166:167], off
	s_waitcnt vmcnt(6)
	s_waitcnt lgkmcnt(0)
	s_barrier
	s_setprio 1
	v_mfma_f32_16x16x32_bf16 v[60:63], v[142:145], v[194:197], v[60:63]
	v_mfma_f32_16x16x32_bf16 v[56:59], v[150:153], v[194:197], v[56:59]
	v_mfma_f32_16x16x32_bf16 v[44:47], v[142:145], v[202:205], v[44:47]
	v_mfma_f32_16x16x32_bf16 v[40:43], v[150:153], v[202:205], v[40:43]
	v_mfma_f32_16x16x32_bf16 v[28:31], v[142:145], v[210:213], v[28:31]
	v_mfma_f32_16x16x32_bf16 v[24:27], v[150:153], v[210:213], v[24:27]
	v_mfma_f32_16x16x32_bf16 v[12:15], v[142:145], v[228:231], v[12:15]
	v_mfma_f32_16x16x32_bf16 v[8:11], v[150:153], v[228:231], v[8:11]
	v_mfma_f32_16x16x32_bf16 v[60:63], v[146:149], v[198:201], v[60:63]
	v_mfma_f32_16x16x32_bf16 v[56:59], v[154:157], v[198:201], v[56:59]
	v_mfma_f32_16x16x32_bf16 v[44:47], v[146:149], v[206:209], v[44:47]
	v_mfma_f32_16x16x32_bf16 v[40:43], v[154:157], v[206:209], v[40:43]
	v_mfma_f32_16x16x32_bf16 v[28:31], v[146:149], v[214:217], v[28:31]
	v_mfma_f32_16x16x32_bf16 v[24:27], v[154:157], v[214:217], v[24:27]
	v_mfma_f32_16x16x32_bf16 v[12:15], v[146:149], v[232:235], v[12:15]
	v_mfma_f32_16x16x32_bf16 v[8:11], v[154:157], v[232:235], v[8:11]
	v_mfma_f32_16x16x32_bf16 v[52:55], v[158:161], v[194:197], v[52:55]
	v_mfma_f32_16x16x32_bf16 v[48:51], v[184:187], v[194:197], v[48:51]
	v_mfma_f32_16x16x32_bf16 v[36:39], v[158:161], v[202:205], v[36:39]
	v_mfma_f32_16x16x32_bf16 v[32:35], v[184:187], v[202:205], v[32:35]
	v_mfma_f32_16x16x32_bf16 v[20:23], v[158:161], v[210:213], v[20:23]
	v_mfma_f32_16x16x32_bf16 v[16:19], v[184:187], v[210:213], v[16:19]
	v_mfma_f32_16x16x32_bf16 v[4:7], v[158:161], v[228:231], v[4:7]
	v_mfma_f32_16x16x32_bf16 v[0:3], v[184:187], v[228:231], v[0:3]
	v_mfma_f32_16x16x32_bf16 v[52:55], v[162:165], v[198:201], v[52:55]
	v_mfma_f32_16x16x32_bf16 v[48:51], v[190:193], v[198:201], v[48:51]
	v_mfma_f32_16x16x32_bf16 v[36:39], v[162:165], v[206:209], v[36:39]
	v_mfma_f32_16x16x32_bf16 v[32:35], v[190:193], v[206:209], v[32:35]
	v_mfma_f32_16x16x32_bf16 v[20:23], v[162:165], v[214:217], v[20:23]
	v_mfma_f32_16x16x32_bf16 v[16:19], v[190:193], v[214:217], v[16:19]
	v_mfma_f32_16x16x32_bf16 v[4:7], v[162:165], v[232:235], v[4:7]
	v_mfma_f32_16x16x32_bf16 v[0:3], v[190:193], v[232:235], v[0:3]
	s_setprio 0
	s_barrier
	s_add_i32 s76, s76, 2
	s_add_u32 s69, s69, 0x100
	s_addc_u32 s75, s75, 0
	s_cmp_gt_u32 s76, 13
	s_mov_b64 s[50:51], s[52:53]
.LBB0_577:
	s_add_u32 s52, s50, 0x100
	s_addc_u32 s53, s51, 0
	s_add_i32 s0, 0, 0x10000
	s_cmp_eq_u32 s76, 12
	s_cselect_b32 s57, s43, s53
	s_cselect_b32 s56, s67, s52
	s_cselect_b32 s55, s41, s75
	s_cselect_b32 s54, s68, s69
	s_add_i32 s12, 0, 0x14000
	v_add_u32_e32 v154, s0, v188
	v_add_u32_e32 v166, s12, v188
	ds_read_b128 v[142:145], v154
	ds_read_b128 v[146:149], v154 offset:1024
	ds_read_b128 v[150:153], v154 offset:2048
	ds_read_b128 v[154:157], v154 offset:3072
	ds_read_b128 v[158:161], v166
	ds_read_b128 v[162:165], v166 offset:1024
	ds_read_b128 v[184:187], v166 offset:2048
	ds_read_b128 v[190:193], v166 offset:3072
	s_add_i32 m0, s49, 0xc000
	ds_read_b128 v[194:197], v189
	ds_read_b128 v[198:201], v189 offset:1024
	ds_read_b128 v[202:205], v189 offset:2048
	ds_read_b128 v[206:209], v189 offset:3072
	ds_read_b128 v[210:213], v189 offset:4096
	ds_read_b128 v[214:217], v189 offset:5120
	ds_read_b128 v[228:231], v189 offset:6144
	ds_read_b128 v[232:235], v189 offset:7168
	global_load_lds_dwordx4 v138, s[50:51]
	s_add_i32 m0, s49, 0xe000
	s_nop 0
	global_load_lds_dwordx4 v140, s[50:51]
	s_waitcnt vmcnt(8)
	s_waitcnt lgkmcnt(0)
	s_barrier
	s_setprio 1
	v_mfma_f32_16x16x32_bf16 v[124:127], v[142:145], v[194:197], v[124:127]
	v_mfma_f32_16x16x32_bf16 v[120:123], v[150:153], v[194:197], v[120:123]
	v_mfma_f32_16x16x32_bf16 v[108:111], v[142:145], v[202:205], v[108:111]
	v_mfma_f32_16x16x32_bf16 v[104:107], v[150:153], v[202:205], v[104:107]
	v_mfma_f32_16x16x32_bf16 v[92:95], v[142:145], v[210:213], v[92:95]
	v_mfma_f32_16x16x32_bf16 v[88:91], v[150:153], v[210:213], v[88:91]
	v_mfma_f32_16x16x32_bf16 v[76:79], v[142:145], v[228:231], v[76:79]
	v_mfma_f32_16x16x32_bf16 v[72:75], v[150:153], v[228:231], v[72:75]
	v_mfma_f32_16x16x32_bf16 v[124:127], v[146:149], v[198:201], v[124:127]
	v_mfma_f32_16x16x32_bf16 v[120:123], v[154:157], v[198:201], v[120:123]
	v_mfma_f32_16x16x32_bf16 v[108:111], v[146:149], v[206:209], v[108:111]
	v_mfma_f32_16x16x32_bf16 v[104:107], v[154:157], v[206:209], v[104:107]
	v_mfma_f32_16x16x32_bf16 v[92:95], v[146:149], v[214:217], v[92:95]
	v_mfma_f32_16x16x32_bf16 v[88:91], v[154:157], v[214:217], v[88:91]
	v_mfma_f32_16x16x32_bf16 v[76:79], v[146:149], v[232:235], v[76:79]
	v_mfma_f32_16x16x32_bf16 v[72:75], v[154:157], v[232:235], v[72:75]
	v_mfma_f32_16x16x32_bf16 v[116:119], v[158:161], v[194:197], v[116:119]
	v_mfma_f32_16x16x32_bf16 v[112:115], v[184:187], v[194:197], v[112:115]
	v_mfma_f32_16x16x32_bf16 v[100:103], v[158:161], v[202:205], v[100:103]
	v_mfma_f32_16x16x32_bf16 v[96:99], v[184:187], v[202:205], v[96:99]
	v_mfma_f32_16x16x32_bf16 v[84:87], v[158:161], v[210:213], v[84:87]
	v_mfma_f32_16x16x32_bf16 v[80:83], v[184:187], v[210:213], v[80:83]
	v_mfma_f32_16x16x32_bf16 v[68:71], v[158:161], v[228:231], v[68:71]
	v_mfma_f32_16x16x32_bf16 v[64:67], v[184:187], v[228:231], v[64:67]
	v_mfma_f32_16x16x32_bf16 v[116:119], v[162:165], v[198:201], v[116:119]
	v_mfma_f32_16x16x32_bf16 v[112:115], v[190:193], v[198:201], v[112:115]
	v_mfma_f32_16x16x32_bf16 v[100:103], v[162:165], v[206:209], v[100:103]
	v_mfma_f32_16x16x32_bf16 v[96:99], v[190:193], v[206:209], v[96:99]
	v_mfma_f32_16x16x32_bf16 v[84:87], v[162:165], v[214:217], v[84:87]
	v_mfma_f32_16x16x32_bf16 v[80:83], v[190:193], v[214:217], v[80:83]
	v_mfma_f32_16x16x32_bf16 v[68:71], v[162:165], v[232:235], v[68:71]
	v_mfma_f32_16x16x32_bf16 v[64:67], v[190:193], v[232:235], v[64:67]
	s_setprio 0
	s_barrier
	s_add_i32 s0, s0, s59
	v_lshl_add_u64 v[166:167], s[54:55], 0, v[130:131]
	s_mov_b32 m0, s0
	ds_read_b128 v[194:197], v189 offset:16384
	ds_read_b128 v[198:201], v189 offset:17408
	ds_read_b128 v[202:205], v189 offset:18432
	ds_read_b128 v[206:209], v189 offset:19456
	ds_read_b128 v[210:213], v189 offset:20480
	ds_read_b128 v[214:217], v189 offset:21504
	ds_read_b128 v[228:231], v189 offset:22528
	ds_read_b128 v[232:235], v189 offset:23552
	global_load_lds_dwordx4 v[166:167], off
	s_add_i32 m0, s0, 0x2000
	s_add_u32 s0, s54, 0x40000
	v_lshl_add_u64 v[218:219], s[54:55], 0, v[134:135]
	s_addc_u32 s1, s55, 0
	s_add_i32 s12, s12, s59
	global_load_lds_dwordx4 v[218:219], off
	s_mov_b32 m0, s12
	v_lshl_add_u64 v[238:239], s[56:57], 0, v[132:133]
	global_load_lds_dwordx4 v130, s[0:1]
	s_add_i32 m0, s12, 0x2000
	s_nop 0
	global_load_lds_dwordx4 v134, s[0:1]
	v_lshl_add_u64 v[236:237], s[56:57], 0, v[128:129]
	s_waitcnt vmcnt(6)
	s_waitcnt lgkmcnt(0)
	s_barrier
	s_setprio 1
	v_mfma_f32_16x16x32_bf16 v[60:63], v[142:145], v[194:197], v[60:63]
	v_mfma_f32_16x16x32_bf16 v[56:59], v[150:153], v[194:197], v[56:59]
	v_mfma_f32_16x16x32_bf16 v[44:47], v[142:145], v[202:205], v[44:47]
	v_mfma_f32_16x16x32_bf16 v[40:43], v[150:153], v[202:205], v[40:43]
	v_mfma_f32_16x16x32_bf16 v[28:31], v[142:145], v[210:213], v[28:31]
	v_mfma_f32_16x16x32_bf16 v[24:27], v[150:153], v[210:213], v[24:27]
	v_mfma_f32_16x16x32_bf16 v[12:15], v[142:145], v[228:231], v[12:15]
	v_mfma_f32_16x16x32_bf16 v[8:11], v[150:153], v[228:231], v[8:11]
	v_mfma_f32_16x16x32_bf16 v[60:63], v[146:149], v[198:201], v[60:63]
	v_mfma_f32_16x16x32_bf16 v[56:59], v[154:157], v[198:201], v[56:59]
	v_mfma_f32_16x16x32_bf16 v[44:47], v[146:149], v[206:209], v[44:47]
	v_mfma_f32_16x16x32_bf16 v[40:43], v[154:157], v[206:209], v[40:43]
	v_mfma_f32_16x16x32_bf16 v[28:31], v[146:149], v[214:217], v[28:31]
	v_mfma_f32_16x16x32_bf16 v[24:27], v[154:157], v[214:217], v[24:27]
	v_mfma_f32_16x16x32_bf16 v[12:15], v[146:149], v[232:235], v[12:15]
	v_mfma_f32_16x16x32_bf16 v[8:11], v[154:157], v[232:235], v[8:11]
	v_mfma_f32_16x16x32_bf16 v[52:55], v[158:161], v[194:197], v[52:55]
	v_mfma_f32_16x16x32_bf16 v[48:51], v[184:187], v[194:197], v[48:51]
	v_mfma_f32_16x16x32_bf16 v[36:39], v[158:161], v[202:205], v[36:39]
	v_mfma_f32_16x16x32_bf16 v[32:35], v[184:187], v[202:205], v[32:35]
	v_mfma_f32_16x16x32_bf16 v[20:23], v[158:161], v[210:213], v[20:23]
	v_mfma_f32_16x16x32_bf16 v[16:19], v[184:187], v[210:213], v[16:19]
	v_mfma_f32_16x16x32_bf16 v[4:7], v[158:161], v[228:231], v[4:7]
	v_mfma_f32_16x16x32_bf16 v[0:3], v[184:187], v[228:231], v[0:3]
	v_mfma_f32_16x16x32_bf16 v[52:55], v[162:165], v[198:201], v[52:55]
	v_mfma_f32_16x16x32_bf16 v[48:51], v[190:193], v[198:201], v[48:51]
	v_mfma_f32_16x16x32_bf16 v[36:39], v[162:165], v[206:209], v[36:39]
	v_mfma_f32_16x16x32_bf16 v[32:35], v[190:193], v[206:209], v[32:35]
	v_mfma_f32_16x16x32_bf16 v[20:23], v[162:165], v[214:217], v[20:23]
	v_mfma_f32_16x16x32_bf16 v[16:19], v[190:193], v[214:217], v[16:19]
	v_mfma_f32_16x16x32_bf16 v[4:7], v[162:165], v[232:235], v[4:7]
	v_mfma_f32_16x16x32_bf16 v[0:3], v[190:193], v[232:235], v[0:3]
	s_setprio 0
	s_barrier
	s_add_i32 s12, 0, 0x18000
	s_add_i32 s13, 0, 0x1c000
	v_add_u32_e32 v154, s12, v188
	v_add_u32_e32 v170, s13, v188
	ds_read_b128 v[142:145], v154
	ds_read_b128 v[146:149], v154 offset:1024
	ds_read_b128 v[150:153], v154 offset:2048
	ds_read_b128 v[154:157], v154 offset:3072
	ds_read_b128 v[158:161], v170
	ds_read_b128 v[162:165], v170 offset:1024
	ds_read_b128 v[184:187], v170 offset:2048
	ds_read_b128 v[190:193], v170 offset:3072
	s_add_u32 s0, s56, 0x40000
	s_addc_u32 s1, s57, 0
	s_mov_b32 m0, s61
	ds_read_b128 v[194:197], v189 offset:32768
	ds_read_b128 v[198:201], v189 offset:33792
	ds_read_b128 v[202:205], v189 offset:34816
	ds_read_b128 v[206:209], v189 offset:35840
	ds_read_b128 v[210:213], v189 offset:36864
	ds_read_b128 v[214:217], v189 offset:37888
	ds_read_b128 v[228:231], v189 offset:38912
	ds_read_b128 v[232:235], v189 offset:39936
	global_load_lds_dwordx4 v128, s[0:1]
	s_mov_b32 m0, s62
	s_nop 0
	global_load_lds_dwordx4 v132, s[0:1]
	s_mov_b32 m0, s49
	s_nop 0
	global_load_lds_dwordx4 v[236:237], off
	s_mov_b32 m0, s60
	s_nop 0
	global_load_lds_dwordx4 v[238:239], off
	s_waitcnt vmcnt(8)
	s_waitcnt lgkmcnt(0)
	s_barrier
	s_setprio 1
	v_mfma_f32_16x16x32_bf16 v[124:127], v[142:145], v[194:197], v[124:127]
	v_mfma_f32_16x16x32_bf16 v[120:123], v[150:153], v[194:197], v[120:123]
	v_mfma_f32_16x16x32_bf16 v[108:111], v[142:145], v[202:205], v[108:111]
	v_mfma_f32_16x16x32_bf16 v[104:107], v[150:153], v[202:205], v[104:107]
	v_mfma_f32_16x16x32_bf16 v[92:95], v[142:145], v[210:213], v[92:95]
	v_mfma_f32_16x16x32_bf16 v[88:91], v[150:153], v[210:213], v[88:91]
	v_mfma_f32_16x16x32_bf16 v[76:79], v[142:145], v[228:231], v[76:79]
	v_mfma_f32_16x16x32_bf16 v[72:75], v[150:153], v[228:231], v[72:75]
	v_mfma_f32_16x16x32_bf16 v[124:127], v[146:149], v[198:201], v[124:127]
	v_mfma_f32_16x16x32_bf16 v[120:123], v[154:157], v[198:201], v[120:123]
	v_mfma_f32_16x16x32_bf16 v[108:111], v[146:149], v[206:209], v[108:111]
	v_mfma_f32_16x16x32_bf16 v[104:107], v[154:157], v[206:209], v[104:107]
	v_mfma_f32_16x16x32_bf16 v[92:95], v[146:149], v[214:217], v[92:95]
	v_mfma_f32_16x16x32_bf16 v[88:91], v[154:157], v[214:217], v[88:91]
	v_mfma_f32_16x16x32_bf16 v[76:79], v[146:149], v[232:235], v[76:79]
	v_mfma_f32_16x16x32_bf16 v[72:75], v[154:157], v[232:235], v[72:75]
	v_mfma_f32_16x16x32_bf16 v[116:119], v[158:161], v[194:197], v[116:119]
	v_mfma_f32_16x16x32_bf16 v[112:115], v[184:187], v[194:197], v[112:115]
	v_mfma_f32_16x16x32_bf16 v[100:103], v[158:161], v[202:205], v[100:103]
	v_mfma_f32_16x16x32_bf16 v[96:99], v[184:187], v[202:205], v[96:99]
	v_mfma_f32_16x16x32_bf16 v[84:87], v[158:161], v[210:213], v[84:87]
	v_mfma_f32_16x16x32_bf16 v[80:83], v[184:187], v[210:213], v[80:83]
	v_mfma_f32_16x16x32_bf16 v[68:71], v[158:161], v[228:231], v[68:71]
	v_mfma_f32_16x16x32_bf16 v[64:67], v[184:187], v[228:231], v[64:67]
	v_mfma_f32_16x16x32_bf16 v[116:119], v[162:165], v[198:201], v[116:119]
	v_mfma_f32_16x16x32_bf16 v[112:115], v[190:193], v[198:201], v[112:115]
	v_mfma_f32_16x16x32_bf16 v[100:103], v[162:165], v[206:209], v[100:103]
	v_mfma_f32_16x16x32_bf16 v[96:99], v[190:193], v[206:209], v[96:99]
	v_mfma_f32_16x16x32_bf16 v[84:87], v[162:165], v[214:217], v[84:87]
	v_mfma_f32_16x16x32_bf16 v[80:83], v[190:193], v[214:217], v[80:83]
	v_mfma_f32_16x16x32_bf16 v[68:71], v[162:165], v[232:235], v[68:71]
	v_mfma_f32_16x16x32_bf16 v[64:67], v[190:193], v[232:235], v[64:67]
	s_setprio 0
	s_barrier
	s_add_i32 s0, s12, s59
	v_lshl_add_u64 v[166:167], v[166:167], 0, s[16:17]
	s_mov_b32 m0, s0
	ds_read_b128 v[194:197], v189 offset:49152
	ds_read_b128 v[198:201], v189 offset:50176
	ds_read_b128 v[202:205], v189 offset:51200
	ds_read_b128 v[206:209], v189 offset:52224
	ds_read_b128 v[210:213], v189 offset:53248
	ds_read_b128 v[214:217], v189 offset:54272
	ds_read_b128 v[228:231], v189 offset:55296
	ds_read_b128 v[232:235], v189 offset:56320
	global_load_lds_dwordx4 v[166:167], off
	s_add_i32 m0, s0, 0x2000
	s_add_u32 s0, s54, 0x40080
	v_lshl_add_u64 v[166:167], v[218:219], 0, s[16:17]
	s_addc_u32 s1, s55, 0
	s_add_i32 s12, s13, s59
	global_load_lds_dwordx4 v[166:167], off
	s_mov_b32 m0, s12
	s_nop 0
	global_load_lds_dwordx4 v130, s[0:1]
	s_add_i32 m0, s12, 0x2000
	s_nop 0
	global_load_lds_dwordx4 v134, s[0:1]
	v_lshl_add_u64 v[166:167], v[236:237], 0, s[16:17]
	s_mov_b32 m0, s64
	s_nop 0
	global_load_lds_dwordx4 v[166:167], off
	v_lshl_add_u64 v[166:167], v[238:239], 0, s[16:17]
	s_mov_b32 m0, s65
	s_nop 0
	global_load_lds_dwordx4 v[166:167], off
	s_waitcnt vmcnt(6)
	s_waitcnt lgkmcnt(0)
	s_barrier
	s_setprio 1
	v_mfma_f32_16x16x32_bf16 v[60:63], v[142:145], v[194:197], v[60:63]
	v_mfma_f32_16x16x32_bf16 v[56:59], v[150:153], v[194:197], v[56:59]
	v_mfma_f32_16x16x32_bf16 v[44:47], v[142:145], v[202:205], v[44:47]
	v_mfma_f32_16x16x32_bf16 v[40:43], v[150:153], v[202:205], v[40:43]
	v_mfma_f32_16x16x32_bf16 v[28:31], v[142:145], v[210:213], v[28:31]
	v_mfma_f32_16x16x32_bf16 v[24:27], v[150:153], v[210:213], v[24:27]
	v_mfma_f32_16x16x32_bf16 v[12:15], v[142:145], v[228:231], v[12:15]
	v_mfma_f32_16x16x32_bf16 v[8:11], v[150:153], v[228:231], v[8:11]
	v_mfma_f32_16x16x32_bf16 v[60:63], v[146:149], v[198:201], v[60:63]
	v_mfma_f32_16x16x32_bf16 v[56:59], v[154:157], v[198:201], v[56:59]
	v_mfma_f32_16x16x32_bf16 v[44:47], v[146:149], v[206:209], v[44:47]
	v_mfma_f32_16x16x32_bf16 v[40:43], v[154:157], v[206:209], v[40:43]
	v_mfma_f32_16x16x32_bf16 v[28:31], v[146:149], v[214:217], v[28:31]
	v_mfma_f32_16x16x32_bf16 v[24:27], v[154:157], v[214:217], v[24:27]
	v_mfma_f32_16x16x32_bf16 v[12:15], v[146:149], v[232:235], v[12:15]
	v_mfma_f32_16x16x32_bf16 v[8:11], v[154:157], v[232:235], v[8:11]
	v_mfma_f32_16x16x32_bf16 v[52:55], v[158:161], v[194:197], v[52:55]
	v_mfma_f32_16x16x32_bf16 v[48:51], v[184:187], v[194:197], v[48:51]
	v_mfma_f32_16x16x32_bf16 v[36:39], v[158:161], v[202:205], v[36:39]
	v_mfma_f32_16x16x32_bf16 v[32:35], v[184:187], v[202:205], v[32:35]
	v_mfma_f32_16x16x32_bf16 v[20:23], v[158:161], v[210:213], v[20:23]
	v_mfma_f32_16x16x32_bf16 v[16:19], v[184:187], v[210:213], v[16:19]
	v_mfma_f32_16x16x32_bf16 v[4:7], v[158:161], v[228:231], v[4:7]
	v_mfma_f32_16x16x32_bf16 v[0:3], v[184:187], v[228:231], v[0:3]
	v_mfma_f32_16x16x32_bf16 v[52:55], v[162:165], v[198:201], v[52:55]
	v_mfma_f32_16x16x32_bf16 v[48:51], v[190:193], v[198:201], v[48:51]
	v_mfma_f32_16x16x32_bf16 v[36:39], v[162:165], v[206:209], v[36:39]
	v_mfma_f32_16x16x32_bf16 v[32:35], v[190:193], v[206:209], v[32:35]
	v_mfma_f32_16x16x32_bf16 v[20:23], v[162:165], v[214:217], v[20:23]
	v_mfma_f32_16x16x32_bf16 v[16:19], v[190:193], v[214:217], v[16:19]
	v_mfma_f32_16x16x32_bf16 v[4:7], v[162:165], v[232:235], v[4:7]
	v_mfma_f32_16x16x32_bf16 v[0:3], v[190:193], v[232:235], v[0:3]
	s_setprio 0
	s_barrier
	s_add_i32 s76, s76, 2
	s_add_u32 s69, s69, 0x100
	s_addc_u32 s75, s75, 0
	s_cmp_gt_u32 s76, 13
	s_mov_b64 s[50:51], s[52:53]
	s_cbranch_scc0 .LBB0_577
	s_and_b64 vcc, exec, s[36:37]
	s_cbranch_vccz .LBB0_580
	s_barrier

.Lrestag_601:
	s_add_u32 s48, s46, 0x100
	s_addc_u32 s49, s47, 0
	s_add_i32 s0, 0, 0x10000
	s_cmp_eq_u32 s66, 12
	s_cselect_b32 s53, s37, s49
	s_cselect_b32 s52, s62, s48
	v_add_u32_e32 v146, s0, v149
	s_cselect_b32 s51, s35, s65
	s_cselect_b32 s50, s63, s64
	s_add_i32 s12, 0, 0x14000
	ds_read_b128 v[128:131], v146
	ds_read_b128 v[132:135], v146 offset:1024
	ds_read_b128 v[152:155], v146 offset:2048
	ds_read_b128 v[156:159], v146 offset:3072
	v_add_u32_e32 v146, s12, v149
	ds_read_b128 v[160:163], v146
	ds_read_b128 v[164:167], v146 offset:1024
	ds_read_b128 v[184:187], v146 offset:2048
	ds_read_b128 v[188:191], v146 offset:3072
	s_add_i32 m0, s45, 0xc000
	ds_read_b128 v[192:195], v151
	ds_read_b128 v[196:199], v151 offset:1024
	ds_read_b128 v[200:203], v151 offset:2048
	ds_read_b128 v[204:207], v151 offset:3072
	ds_read_b128 v[208:211], v151 offset:4096
	ds_read_b128 v[212:215], v151 offset:5120
	ds_read_b128 v[216:219], v151 offset:6144
	ds_read_b128 v[228:231], v151 offset:7168
	global_load_lds_dwordx4 v142, s[46:47]
	s_add_i32 m0, s45, 0xe000
	s_nop 0
	global_load_lds_dwordx4 v144, s[46:47]
	s_nop 0
	s_waitcnt lgkmcnt(0)
	s_barrier
	s_setprio 1
	v_mfma_f32_16x16x32_bf16 v[124:127], v[128:131], v[192:195], 0
	v_mfma_f32_16x16x32_bf16 v[120:123], v[152:155], v[192:195], 0
	v_mfma_f32_16x16x32_bf16 v[116:119], v[128:131], v[200:203], 0
	v_mfma_f32_16x16x32_bf16 v[112:115], v[152:155], v[200:203], 0
	v_mfma_f32_16x16x32_bf16 v[108:111], v[128:131], v[208:211], 0
	v_mfma_f32_16x16x32_bf16 v[104:107], v[152:155], v[208:211], 0
	v_mfma_f32_16x16x32_bf16 v[100:103], v[128:131], v[216:219], 0
	v_mfma_f32_16x16x32_bf16 v[96:99], v[152:155], v[216:219], 0
	v_mfma_f32_16x16x32_bf16 v[124:127], v[132:135], v[196:199], v[124:127]
	v_mfma_f32_16x16x32_bf16 v[120:123], v[156:159], v[196:199], v[120:123]
	v_mfma_f32_16x16x32_bf16 v[116:119], v[132:135], v[204:207], v[116:119]
	v_mfma_f32_16x16x32_bf16 v[112:115], v[156:159], v[204:207], v[112:115]
	v_mfma_f32_16x16x32_bf16 v[108:111], v[132:135], v[212:215], v[108:111]
	v_mfma_f32_16x16x32_bf16 v[104:107], v[156:159], v[212:215], v[104:107]
	v_mfma_f32_16x16x32_bf16 v[100:103], v[132:135], v[228:231], v[100:103]
	v_mfma_f32_16x16x32_bf16 v[96:99], v[156:159], v[228:231], v[96:99]
	v_mfma_f32_16x16x32_bf16 v[68:71], v[160:163], v[192:195], 0
	v_mfma_f32_16x16x32_bf16 v[60:63], v[184:187], v[192:195], 0
	v_mfma_f32_16x16x32_bf16 v[52:55], v[160:163], v[200:203], 0
	v_mfma_f32_16x16x32_bf16 v[48:51], v[184:187], v[200:203], 0
	v_mfma_f32_16x16x32_bf16 v[44:47], v[160:163], v[208:211], 0
	v_mfma_f32_16x16x32_bf16 v[40:43], v[184:187], v[208:211], 0
	v_mfma_f32_16x16x32_bf16 v[36:39], v[160:163], v[216:219], 0
	v_mfma_f32_16x16x32_bf16 v[32:35], v[184:187], v[216:219], 0
	v_mfma_f32_16x16x32_bf16 v[68:71], v[164:167], v[196:199], v[68:71]
	v_mfma_f32_16x16x32_bf16 v[60:63], v[188:191], v[196:199], v[60:63]
	v_mfma_f32_16x16x32_bf16 v[52:55], v[164:167], v[204:207], v[52:55]
	v_mfma_f32_16x16x32_bf16 v[48:51], v[188:191], v[204:207], v[48:51]
	v_mfma_f32_16x16x32_bf16 v[44:47], v[164:167], v[212:215], v[44:47]
	v_mfma_f32_16x16x32_bf16 v[40:43], v[188:191], v[212:215], v[40:43]
	v_mfma_f32_16x16x32_bf16 v[36:39], v[164:167], v[228:231], v[36:39]
	v_mfma_f32_16x16x32_bf16 v[32:35], v[188:191], v[228:231], v[32:35]
	s_setprio 0
	s_barrier
	s_add_i32 s0, s0, s55
	v_lshl_add_u64 v[146:147], s[50:51], 0, v[170:171]
	s_mov_b32 m0, s0
	ds_read_b128 v[192:195], v151 offset:16384
	ds_read_b128 v[196:199], v151 offset:17408
	ds_read_b128 v[200:203], v151 offset:18432
	ds_read_b128 v[204:207], v151 offset:19456
	ds_read_b128 v[208:211], v151 offset:20480
	ds_read_b128 v[212:215], v151 offset:21504
	ds_read_b128 v[216:219], v151 offset:22528
	ds_read_b128 v[228:231], v151 offset:23552
	global_load_lds_dwordx4 v[146:147], off
	s_add_i32 m0, s0, 0x2000
	s_add_u32 s0, s50, 0x40000
	v_lshl_add_u64 v[232:233], s[50:51], 0, v[140:141]
	s_addc_u32 s1, s51, 0
	s_add_i32 s12, s12, s55
	global_load_lds_dwordx4 v[232:233], off
	s_mov_b32 m0, s12
	v_lshl_add_u64 v[236:237], s[52:53], 0, v[138:139]
	global_load_lds_dwordx4 v170, s[0:1]
	s_add_i32 m0, s12, 0x2000
	s_nop 0
	global_load_lds_dwordx4 v140, s[0:1]
	v_lshl_add_u64 v[234:235], s[52:53], 0, v[136:137]
	s_nop 0
	s_waitcnt lgkmcnt(0)
	s_barrier
	s_setprio 1
	v_mfma_f32_16x16x32_bf16 v[92:95], v[128:131], v[192:195], 0
	v_mfma_f32_16x16x32_bf16 v[88:91], v[152:155], v[192:195], 0
	v_mfma_f32_16x16x32_bf16 v[84:87], v[128:131], v[200:203], 0
	v_mfma_f32_16x16x32_bf16 v[80:83], v[152:155], v[200:203], 0
	v_mfma_f32_16x16x32_bf16 v[76:79], v[128:131], v[208:211], 0
	v_mfma_f32_16x16x32_bf16 v[72:75], v[152:155], v[208:211], 0
	v_mfma_f32_16x16x32_bf16 v[64:67], v[128:131], v[216:219], 0
	v_mfma_f32_16x16x32_bf16 v[56:59], v[152:155], v[216:219], 0
	v_mfma_f32_16x16x32_bf16 v[92:95], v[132:135], v[196:199], v[92:95]
	v_mfma_f32_16x16x32_bf16 v[88:91], v[156:159], v[196:199], v[88:91]
	v_mfma_f32_16x16x32_bf16 v[84:87], v[132:135], v[204:207], v[84:87]
	v_mfma_f32_16x16x32_bf16 v[80:83], v[156:159], v[204:207], v[80:83]
	v_mfma_f32_16x16x32_bf16 v[76:79], v[132:135], v[212:215], v[76:79]
	v_mfma_f32_16x16x32_bf16 v[72:75], v[156:159], v[212:215], v[72:75]
	v_mfma_f32_16x16x32_bf16 v[64:67], v[132:135], v[228:231], v[64:67]
	v_mfma_f32_16x16x32_bf16 v[56:59], v[156:159], v[228:231], v[56:59]
	v_mfma_f32_16x16x32_bf16 v[28:31], v[160:163], v[192:195], 0
	v_mfma_f32_16x16x32_bf16 v[24:27], v[184:187], v[192:195], 0
	v_mfma_f32_16x16x32_bf16 v[20:23], v[160:163], v[200:203], 0
	v_mfma_f32_16x16x32_bf16 v[16:19], v[184:187], v[200:203], 0
	v_mfma_f32_16x16x32_bf16 v[12:15], v[160:163], v[208:211], 0
	v_mfma_f32_16x16x32_bf16 v[8:11], v[184:187], v[208:211], 0
	v_mfma_f32_16x16x32_bf16 v[4:7], v[160:163], v[216:219], 0
	v_mfma_f32_16x16x32_bf16 v[0:3], v[184:187], v[216:219], 0
	v_mfma_f32_16x16x32_bf16 v[28:31], v[164:167], v[196:199], v[28:31]
	v_mfma_f32_16x16x32_bf16 v[24:27], v[188:191], v[196:199], v[24:27]
	v_mfma_f32_16x16x32_bf16 v[20:23], v[164:167], v[204:207], v[20:23]
	v_mfma_f32_16x16x32_bf16 v[16:19], v[188:191], v[204:207], v[16:19]
	v_mfma_f32_16x16x32_bf16 v[12:15], v[164:167], v[212:215], v[12:15]
	v_mfma_f32_16x16x32_bf16 v[8:11], v[188:191], v[212:215], v[8:11]
	v_mfma_f32_16x16x32_bf16 v[4:7], v[164:167], v[228:231], v[4:7]
	v_mfma_f32_16x16x32_bf16 v[0:3], v[188:191], v[228:231], v[0:3]
	s_setprio 0
	s_barrier
	s_add_i32 s12, 0, 0x18000
	s_add_i32 s13, 0, 0x1c000
	v_add_u32_e32 v156, s12, v149
	v_add_u32_e32 v188, s13, v149
	ds_read_b128 v[128:131], v156
	ds_read_b128 v[132:135], v156 offset:1024
	ds_read_b128 v[152:155], v156 offset:2048
	ds_read_b128 v[156:159], v156 offset:3072
	ds_read_b128 v[160:163], v188
	ds_read_b128 v[164:167], v188 offset:1024
	ds_read_b128 v[184:187], v188 offset:2048
	ds_read_b128 v[188:191], v188 offset:3072
	s_add_u32 s0, s52, 0x40000
	s_addc_u32 s1, s53, 0
	s_mov_b32 m0, s57
	ds_read_b128 v[192:195], v151 offset:32768
	ds_read_b128 v[196:199], v151 offset:33792
	ds_read_b128 v[200:203], v151 offset:34816
	ds_read_b128 v[204:207], v151 offset:35840
	ds_read_b128 v[208:211], v151 offset:36864
	ds_read_b128 v[212:215], v151 offset:37888
	ds_read_b128 v[216:219], v151 offset:38912
	ds_read_b128 v[228:231], v151 offset:39936
	global_load_lds_dwordx4 v136, s[0:1]
	s_mov_b32 m0, s58
	s_nop 0
	global_load_lds_dwordx4 v138, s[0:1]
	s_mov_b32 m0, s45
	s_nop 0
	global_load_lds_dwordx4 v[234:235], off
	s_mov_b32 m0, s56
	s_nop 0
	global_load_lds_dwordx4 v[236:237], off
	s_waitcnt vmcnt(8)
	s_waitcnt lgkmcnt(0)
	s_barrier
	s_setprio 1
	v_mfma_f32_16x16x32_bf16 v[124:127], v[128:131], v[192:195], v[124:127]
	v_mfma_f32_16x16x32_bf16 v[120:123], v[152:155], v[192:195], v[120:123]
	v_mfma_f32_16x16x32_bf16 v[116:119], v[128:131], v[200:203], v[116:119]
	v_mfma_f32_16x16x32_bf16 v[112:115], v[152:155], v[200:203], v[112:115]
	v_mfma_f32_16x16x32_bf16 v[108:111], v[128:131], v[208:211], v[108:111]
	v_mfma_f32_16x16x32_bf16 v[104:107], v[152:155], v[208:211], v[104:107]
	v_mfma_f32_16x16x32_bf16 v[100:103], v[128:131], v[216:219], v[100:103]
	v_mfma_f32_16x16x32_bf16 v[96:99], v[152:155], v[216:219], v[96:99]
	v_mfma_f32_16x16x32_bf16 v[124:127], v[132:135], v[196:199], v[124:127]
	v_mfma_f32_16x16x32_bf16 v[120:123], v[156:159], v[196:199], v[120:123]
	v_mfma_f32_16x16x32_bf16 v[116:119], v[132:135], v[204:207], v[116:119]
	v_mfma_f32_16x16x32_bf16 v[112:115], v[156:159], v[204:207], v[112:115]
	v_mfma_f32_16x16x32_bf16 v[108:111], v[132:135], v[212:215], v[108:111]
	v_mfma_f32_16x16x32_bf16 v[104:107], v[156:159], v[212:215], v[104:107]
	v_mfma_f32_16x16x32_bf16 v[100:103], v[132:135], v[228:231], v[100:103]
	v_mfma_f32_16x16x32_bf16 v[96:99], v[156:159], v[228:231], v[96:99]
	v_mfma_f32_16x16x32_bf16 v[68:71], v[160:163], v[192:195], v[68:71]
	v_mfma_f32_16x16x32_bf16 v[60:63], v[184:187], v[192:195], v[60:63]
	v_mfma_f32_16x16x32_bf16 v[52:55], v[160:163], v[200:203], v[52:55]
	v_mfma_f32_16x16x32_bf16 v[48:51], v[184:187], v[200:203], v[48:51]
	v_mfma_f32_16x16x32_bf16 v[44:47], v[160:163], v[208:211], v[44:47]
	v_mfma_f32_16x16x32_bf16 v[40:43], v[184:187], v[208:211], v[40:43]
	v_mfma_f32_16x16x32_bf16 v[36:39], v[160:163], v[216:219], v[36:39]
	v_mfma_f32_16x16x32_bf16 v[32:35], v[184:187], v[216:219], v[32:35]
	v_mfma_f32_16x16x32_bf16 v[68:71], v[164:167], v[196:199], v[68:71]
	v_mfma_f32_16x16x32_bf16 v[60:63], v[188:191], v[196:199], v[60:63]
	v_mfma_f32_16x16x32_bf16 v[52:55], v[164:167], v[204:207], v[52:55]
	v_mfma_f32_16x16x32_bf16 v[48:51], v[188:191], v[204:207], v[48:51]
	v_mfma_f32_16x16x32_bf16 v[44:47], v[164:167], v[212:215], v[44:47]
	v_mfma_f32_16x16x32_bf16 v[40:43], v[188:191], v[212:215], v[40:43]
	v_mfma_f32_16x16x32_bf16 v[36:39], v[164:167], v[228:231], v[36:39]
	v_mfma_f32_16x16x32_bf16 v[32:35], v[188:191], v[228:231], v[32:35]
	s_setprio 0
	s_barrier
	s_add_i32 s0, s12, s55
	v_lshl_add_u64 v[146:147], v[146:147], 0, s[16:17]
	s_mov_b32 m0, s0
	ds_read_b128 v[192:195], v151 offset:49152
	ds_read_b128 v[196:199], v151 offset:50176
	ds_read_b128 v[200:203], v151 offset:51200
	ds_read_b128 v[204:207], v151 offset:52224
	ds_read_b128 v[208:211], v151 offset:53248
	ds_read_b128 v[212:215], v151 offset:54272
	ds_read_b128 v[216:219], v151 offset:55296
	ds_read_b128 v[228:231], v151 offset:56320
	global_load_lds_dwordx4 v[146:147], off
	s_add_i32 m0, s0, 0x2000
	s_add_u32 s0, s50, 0x40080
	v_lshl_add_u64 v[146:147], v[232:233], 0, s[16:17]
	s_addc_u32 s1, s51, 0
	s_add_i32 s12, s13, s55
	global_load_lds_dwordx4 v[146:147], off
	s_mov_b32 m0, s12
	s_nop 0
	global_load_lds_dwordx4 v170, s[0:1]
	s_add_i32 m0, s12, 0x2000
	s_nop 0
	global_load_lds_dwordx4 v140, s[0:1]
	v_lshl_add_u64 v[146:147], v[234:235], 0, s[16:17]
	s_mov_b32 m0, s59
	s_nop 0
	global_load_lds_dwordx4 v[146:147], off
	v_lshl_add_u64 v[146:147], v[236:237], 0, s[16:17]
	s_mov_b32 m0, s60
	s_nop 0
	global_load_lds_dwordx4 v[146:147], off
	s_waitcnt vmcnt(6)
	s_waitcnt lgkmcnt(0)
	s_barrier
	s_setprio 1
	v_mfma_f32_16x16x32_bf16 v[92:95], v[128:131], v[192:195], v[92:95]
	v_mfma_f32_16x16x32_bf16 v[88:91], v[152:155], v[192:195], v[88:91]
	v_mfma_f32_16x16x32_bf16 v[84:87], v[128:131], v[200:203], v[84:87]
	v_mfma_f32_16x16x32_bf16 v[80:83], v[152:155], v[200:203], v[80:83]
	v_mfma_f32_16x16x32_bf16 v[76:79], v[128:131], v[208:211], v[76:79]
	v_mfma_f32_16x16x32_bf16 v[72:75], v[152:155], v[208:211], v[72:75]
	v_mfma_f32_16x16x32_bf16 v[64:67], v[128:131], v[216:219], v[64:67]
	v_mfma_f32_16x16x32_bf16 v[56:59], v[152:155], v[216:219], v[56:59]
	v_mfma_f32_16x16x32_bf16 v[92:95], v[132:135], v[196:199], v[92:95]
	v_mfma_f32_16x16x32_bf16 v[88:91], v[156:159], v[196:199], v[88:91]
	v_mfma_f32_16x16x32_bf16 v[84:87], v[132:135], v[204:207], v[84:87]
	v_mfma_f32_16x16x32_bf16 v[80:83], v[156:159], v[204:207], v[80:83]
	v_mfma_f32_16x16x32_bf16 v[76:79], v[132:135], v[212:215], v[76:79]
	v_mfma_f32_16x16x32_bf16 v[72:75], v[156:159], v[212:215], v[72:75]
	v_mfma_f32_16x16x32_bf16 v[64:67], v[132:135], v[228:231], v[64:67]
	v_mfma_f32_16x16x32_bf16 v[56:59], v[156:159], v[228:231], v[56:59]
	v_mfma_f32_16x16x32_bf16 v[28:31], v[160:163], v[192:195], v[28:31]
	v_mfma_f32_16x16x32_bf16 v[24:27], v[184:187], v[192:195], v[24:27]
	v_mfma_f32_16x16x32_bf16 v[20:23], v[160:163], v[200:203], v[20:23]
	v_mfma_f32_16x16x32_bf16 v[16:19], v[184:187], v[200:203], v[16:19]
	v_mfma_f32_16x16x32_bf16 v[12:15], v[160:163], v[208:211], v[12:15]
	v_mfma_f32_16x16x32_bf16 v[8:11], v[184:187], v[208:211], v[8:11]
	v_mfma_f32_16x16x32_bf16 v[4:7], v[160:163], v[216:219], v[4:7]
	v_mfma_f32_16x16x32_bf16 v[0:3], v[184:187], v[216:219], v[0:3]
	v_mfma_f32_16x16x32_bf16 v[28:31], v[164:167], v[196:199], v[28:31]
	v_mfma_f32_16x16x32_bf16 v[24:27], v[188:191], v[196:199], v[24:27]
	v_mfma_f32_16x16x32_bf16 v[20:23], v[164:167], v[204:207], v[20:23]
	v_mfma_f32_16x16x32_bf16 v[16:19], v[188:191], v[204:207], v[16:19]
	v_mfma_f32_16x16x32_bf16 v[12:15], v[164:167], v[212:215], v[12:15]
	v_mfma_f32_16x16x32_bf16 v[8:11], v[188:191], v[212:215], v[8:11]
	v_mfma_f32_16x16x32_bf16 v[4:7], v[164:167], v[228:231], v[4:7]
	v_mfma_f32_16x16x32_bf16 v[0:3], v[188:191], v[228:231], v[0:3]
	s_setprio 0
	s_barrier
	s_add_i32 s66, s66, 2
	s_add_u32 s64, s64, 0x100
	s_addc_u32 s65, s65, 0
	s_cmp_gt_u32 s66, 13
	s_mov_b64 s[46:47], s[48:49]
.LBB0_601:
	s_add_u32 s48, s46, 0x100
	s_addc_u32 s49, s47, 0
	s_add_i32 s0, 0, 0x10000
	s_cmp_eq_u32 s66, 12
	s_cselect_b32 s53, s37, s49
	s_cselect_b32 s52, s62, s48
	v_add_u32_e32 v146, s0, v149
	s_cselect_b32 s51, s35, s65
	s_cselect_b32 s50, s63, s64
	s_add_i32 s12, 0, 0x14000
	ds_read_b128 v[128:131], v146
	ds_read_b128 v[132:135], v146 offset:1024
	ds_read_b128 v[152:155], v146 offset:2048
	ds_read_b128 v[156:159], v146 offset:3072
	v_add_u32_e32 v146, s12, v149
	ds_read_b128 v[160:163], v146
	ds_read_b128 v[164:167], v146 offset:1024
	ds_read_b128 v[184:187], v146 offset:2048
	ds_read_b128 v[188:191], v146 offset:3072
	s_add_i32 m0, s45, 0xc000
	ds_read_b128 v[192:195], v151
	ds_read_b128 v[196:199], v151 offset:1024
	ds_read_b128 v[200:203], v151 offset:2048
	ds_read_b128 v[204:207], v151 offset:3072
	ds_read_b128 v[208:211], v151 offset:4096
	ds_read_b128 v[212:215], v151 offset:5120
	ds_read_b128 v[216:219], v151 offset:6144
	ds_read_b128 v[228:231], v151 offset:7168
	global_load_lds_dwordx4 v142, s[46:47]
	s_add_i32 m0, s45, 0xe000
	s_nop 0
	global_load_lds_dwordx4 v144, s[46:47]
	s_waitcnt vmcnt(8)
	s_waitcnt lgkmcnt(0)
	s_barrier
	s_setprio 1
	v_mfma_f32_16x16x32_bf16 v[124:127], v[128:131], v[192:195], v[124:127]
	v_mfma_f32_16x16x32_bf16 v[120:123], v[152:155], v[192:195], v[120:123]
	v_mfma_f32_16x16x32_bf16 v[116:119], v[128:131], v[200:203], v[116:119]
	v_mfma_f32_16x16x32_bf16 v[112:115], v[152:155], v[200:203], v[112:115]
	v_mfma_f32_16x16x32_bf16 v[108:111], v[128:131], v[208:211], v[108:111]
	v_mfma_f32_16x16x32_bf16 v[104:107], v[152:155], v[208:211], v[104:107]
	v_mfma_f32_16x16x32_bf16 v[100:103], v[128:131], v[216:219], v[100:103]
	v_mfma_f32_16x16x32_bf16 v[96:99], v[152:155], v[216:219], v[96:99]
	v_mfma_f32_16x16x32_bf16 v[124:127], v[132:135], v[196:199], v[124:127]
	v_mfma_f32_16x16x32_bf16 v[120:123], v[156:159], v[196:199], v[120:123]
	v_mfma_f32_16x16x32_bf16 v[116:119], v[132:135], v[204:207], v[116:119]
	v_mfma_f32_16x16x32_bf16 v[112:115], v[156:159], v[204:207], v[112:115]
	v_mfma_f32_16x16x32_bf16 v[108:111], v[132:135], v[212:215], v[108:111]
	v_mfma_f32_16x16x32_bf16 v[104:107], v[156:159], v[212:215], v[104:107]
	v_mfma_f32_16x16x32_bf16 v[100:103], v[132:135], v[228:231], v[100:103]
	v_mfma_f32_16x16x32_bf16 v[96:99], v[156:159], v[228:231], v[96:99]
	v_mfma_f32_16x16x32_bf16 v[68:71], v[160:163], v[192:195], v[68:71]
	v_mfma_f32_16x16x32_bf16 v[60:63], v[184:187], v[192:195], v[60:63]
	v_mfma_f32_16x16x32_bf16 v[52:55], v[160:163], v[200:203], v[52:55]
	v_mfma_f32_16x16x32_bf16 v[48:51], v[184:187], v[200:203], v[48:51]
	v_mfma_f32_16x16x32_bf16 v[44:47], v[160:163], v[208:211], v[44:47]
	v_mfma_f32_16x16x32_bf16 v[40:43], v[184:187], v[208:211], v[40:43]
	v_mfma_f32_16x16x32_bf16 v[36:39], v[160:163], v[216:219], v[36:39]
	v_mfma_f32_16x16x32_bf16 v[32:35], v[184:187], v[216:219], v[32:35]
	v_mfma_f32_16x16x32_bf16 v[68:71], v[164:167], v[196:199], v[68:71]
	v_mfma_f32_16x16x32_bf16 v[60:63], v[188:191], v[196:199], v[60:63]
	v_mfma_f32_16x16x32_bf16 v[52:55], v[164:167], v[204:207], v[52:55]
	v_mfma_f32_16x16x32_bf16 v[48:51], v[188:191], v[204:207], v[48:51]
	v_mfma_f32_16x16x32_bf16 v[44:47], v[164:167], v[212:215], v[44:47]
	v_mfma_f32_16x16x32_bf16 v[40:43], v[188:191], v[212:215], v[40:43]
	v_mfma_f32_16x16x32_bf16 v[36:39], v[164:167], v[228:231], v[36:39]
	v_mfma_f32_16x16x32_bf16 v[32:35], v[188:191], v[228:231], v[32:35]
	s_setprio 0
	s_barrier
	s_add_i32 s0, s0, s55
	v_lshl_add_u64 v[146:147], s[50:51], 0, v[170:171]
	s_mov_b32 m0, s0
	ds_read_b128 v[192:195], v151 offset:16384
	ds_read_b128 v[196:199], v151 offset:17408
	ds_read_b128 v[200:203], v151 offset:18432
	ds_read_b128 v[204:207], v151 offset:19456
	ds_read_b128 v[208:211], v151 offset:20480
	ds_read_b128 v[212:215], v151 offset:21504
	ds_read_b128 v[216:219], v151 offset:22528
	ds_read_b128 v[228:231], v151 offset:23552
	global_load_lds_dwordx4 v[146:147], off
	s_add_i32 m0, s0, 0x2000
	s_add_u32 s0, s50, 0x40000
	v_lshl_add_u64 v[232:233], s[50:51], 0, v[140:141]
	s_addc_u32 s1, s51, 0
	s_add_i32 s12, s12, s55
	global_load_lds_dwordx4 v[232:233], off
	s_mov_b32 m0, s12
	v_lshl_add_u64 v[236:237], s[52:53], 0, v[138:139]
	global_load_lds_dwordx4 v170, s[0:1]
	s_add_i32 m0, s12, 0x2000
	s_nop 0
	global_load_lds_dwordx4 v140, s[0:1]
	v_lshl_add_u64 v[234:235], s[52:53], 0, v[136:137]
	s_waitcnt vmcnt(6)
	s_waitcnt lgkmcnt(0)
	s_barrier
	s_setprio 1
	v_mfma_f32_16x16x32_bf16 v[92:95], v[128:131], v[192:195], v[92:95]
	v_mfma_f32_16x16x32_bf16 v[88:91], v[152:155], v[192:195], v[88:91]
	v_mfma_f32_16x16x32_bf16 v[84:87], v[128:131], v[200:203], v[84:87]
	v_mfma_f32_16x16x32_bf16 v[80:83], v[152:155], v[200:203], v[80:83]
	v_mfma_f32_16x16x32_bf16 v[76:79], v[128:131], v[208:211], v[76:79]
	v_mfma_f32_16x16x32_bf16 v[72:75], v[152:155], v[208:211], v[72:75]
	v_mfma_f32_16x16x32_bf16 v[64:67], v[128:131], v[216:219], v[64:67]
	v_mfma_f32_16x16x32_bf16 v[56:59], v[152:155], v[216:219], v[56:59]
	v_mfma_f32_16x16x32_bf16 v[92:95], v[132:135], v[196:199], v[92:95]
	v_mfma_f32_16x16x32_bf16 v[88:91], v[156:159], v[196:199], v[88:91]
	v_mfma_f32_16x16x32_bf16 v[84:87], v[132:135], v[204:207], v[84:87]
	v_mfma_f32_16x16x32_bf16 v[80:83], v[156:159], v[204:207], v[80:83]
	v_mfma_f32_16x16x32_bf16 v[76:79], v[132:135], v[212:215], v[76:79]
	v_mfma_f32_16x16x32_bf16 v[72:75], v[156:159], v[212:215], v[72:75]
	v_mfma_f32_16x16x32_bf16 v[64:67], v[132:135], v[228:231], v[64:67]
	v_mfma_f32_16x16x32_bf16 v[56:59], v[156:159], v[228:231], v[56:59]
	v_mfma_f32_16x16x32_bf16 v[28:31], v[160:163], v[192:195], v[28:31]
	v_mfma_f32_16x16x32_bf16 v[24:27], v[184:187], v[192:195], v[24:27]
	v_mfma_f32_16x16x32_bf16 v[20:23], v[160:163], v[200:203], v[20:23]
	v_mfma_f32_16x16x32_bf16 v[16:19], v[184:187], v[200:203], v[16:19]
	v_mfma_f32_16x16x32_bf16 v[12:15], v[160:163], v[208:211], v[12:15]
	v_mfma_f32_16x16x32_bf16 v[8:11], v[184:187], v[208:211], v[8:11]
	v_mfma_f32_16x16x32_bf16 v[4:7], v[160:163], v[216:219], v[4:7]
	v_mfma_f32_16x16x32_bf16 v[0:3], v[184:187], v[216:219], v[0:3]
	v_mfma_f32_16x16x32_bf16 v[28:31], v[164:167], v[196:199], v[28:31]
	v_mfma_f32_16x16x32_bf16 v[24:27], v[188:191], v[196:199], v[24:27]
	v_mfma_f32_16x16x32_bf16 v[20:23], v[164:167], v[204:207], v[20:23]
	v_mfma_f32_16x16x32_bf16 v[16:19], v[188:191], v[204:207], v[16:19]
	v_mfma_f32_16x16x32_bf16 v[12:15], v[164:167], v[212:215], v[12:15]
	v_mfma_f32_16x16x32_bf16 v[8:11], v[188:191], v[212:215], v[8:11]
	v_mfma_f32_16x16x32_bf16 v[4:7], v[164:167], v[228:231], v[4:7]
	v_mfma_f32_16x16x32_bf16 v[0:3], v[188:191], v[228:231], v[0:3]
	s_setprio 0
	s_barrier
	s_add_i32 s12, 0, 0x18000
	s_add_i32 s13, 0, 0x1c000
	v_add_u32_e32 v156, s12, v149
	v_add_u32_e32 v188, s13, v149
	ds_read_b128 v[128:131], v156
	ds_read_b128 v[132:135], v156 offset:1024
	ds_read_b128 v[152:155], v156 offset:2048
	ds_read_b128 v[156:159], v156 offset:3072
	ds_read_b128 v[160:163], v188
	ds_read_b128 v[164:167], v188 offset:1024
	ds_read_b128 v[184:187], v188 offset:2048
	ds_read_b128 v[188:191], v188 offset:3072
	s_add_u32 s0, s52, 0x40000
	s_addc_u32 s1, s53, 0
	s_mov_b32 m0, s57
	ds_read_b128 v[192:195], v151 offset:32768
	ds_read_b128 v[196:199], v151 offset:33792
	ds_read_b128 v[200:203], v151 offset:34816
	ds_read_b128 v[204:207], v151 offset:35840
	ds_read_b128 v[208:211], v151 offset:36864
	ds_read_b128 v[212:215], v151 offset:37888
	ds_read_b128 v[216:219], v151 offset:38912
	ds_read_b128 v[228:231], v151 offset:39936
	global_load_lds_dwordx4 v136, s[0:1]
	s_mov_b32 m0, s58
	s_nop 0
	global_load_lds_dwordx4 v138, s[0:1]
	s_mov_b32 m0, s45
	s_nop 0
	global_load_lds_dwordx4 v[234:235], off
	s_mov_b32 m0, s56
	s_nop 0
	global_load_lds_dwordx4 v[236:237], off
	s_waitcnt vmcnt(8)
	s_waitcnt lgkmcnt(0)
	s_barrier
	s_setprio 1
	v_mfma_f32_16x16x32_bf16 v[124:127], v[128:131], v[192:195], v[124:127]
	v_mfma_f32_16x16x32_bf16 v[120:123], v[152:155], v[192:195], v[120:123]
	v_mfma_f32_16x16x32_bf16 v[116:119], v[128:131], v[200:203], v[116:119]
	v_mfma_f32_16x16x32_bf16 v[112:115], v[152:155], v[200:203], v[112:115]
	v_mfma_f32_16x16x32_bf16 v[108:111], v[128:131], v[208:211], v[108:111]
	v_mfma_f32_16x16x32_bf16 v[104:107], v[152:155], v[208:211], v[104:107]
	v_mfma_f32_16x16x32_bf16 v[100:103], v[128:131], v[216:219], v[100:103]
	v_mfma_f32_16x16x32_bf16 v[96:99], v[152:155], v[216:219], v[96:99]
	v_mfma_f32_16x16x32_bf16 v[124:127], v[132:135], v[196:199], v[124:127]
	v_mfma_f32_16x16x32_bf16 v[120:123], v[156:159], v[196:199], v[120:123]
	v_mfma_f32_16x16x32_bf16 v[116:119], v[132:135], v[204:207], v[116:119]
	v_mfma_f32_16x16x32_bf16 v[112:115], v[156:159], v[204:207], v[112:115]
	v_mfma_f32_16x16x32_bf16 v[108:111], v[132:135], v[212:215], v[108:111]
	v_mfma_f32_16x16x32_bf16 v[104:107], v[156:159], v[212:215], v[104:107]
	v_mfma_f32_16x16x32_bf16 v[100:103], v[132:135], v[228:231], v[100:103]
	v_mfma_f32_16x16x32_bf16 v[96:99], v[156:159], v[228:231], v[96:99]
	v_mfma_f32_16x16x32_bf16 v[68:71], v[160:163], v[192:195], v[68:71]
	v_mfma_f32_16x16x32_bf16 v[60:63], v[184:187], v[192:195], v[60:63]
	v_mfma_f32_16x16x32_bf16 v[52:55], v[160:163], v[200:203], v[52:55]
	v_mfma_f32_16x16x32_bf16 v[48:51], v[184:187], v[200:203], v[48:51]
	v_mfma_f32_16x16x32_bf16 v[44:47], v[160:163], v[208:211], v[44:47]
	v_mfma_f32_16x16x32_bf16 v[40:43], v[184:187], v[208:211], v[40:43]
	v_mfma_f32_16x16x32_bf16 v[36:39], v[160:163], v[216:219], v[36:39]
	v_mfma_f32_16x16x32_bf16 v[32:35], v[184:187], v[216:219], v[32:35]
	v_mfma_f32_16x16x32_bf16 v[68:71], v[164:167], v[196:199], v[68:71]
	v_mfma_f32_16x16x32_bf16 v[60:63], v[188:191], v[196:199], v[60:63]
	v_mfma_f32_16x16x32_bf16 v[52:55], v[164:167], v[204:207], v[52:55]
	v_mfma_f32_16x16x32_bf16 v[48:51], v[188:191], v[204:207], v[48:51]
	v_mfma_f32_16x16x32_bf16 v[44:47], v[164:167], v[212:215], v[44:47]
	v_mfma_f32_16x16x32_bf16 v[40:43], v[188:191], v[212:215], v[40:43]
	v_mfma_f32_16x16x32_bf16 v[36:39], v[164:167], v[228:231], v[36:39]
	v_mfma_f32_16x16x32_bf16 v[32:35], v[188:191], v[228:231], v[32:35]
	s_setprio 0
	s_barrier
	s_add_i32 s0, s12, s55
	v_lshl_add_u64 v[146:147], v[146:147], 0, s[16:17]
	s_mov_b32 m0, s0
	ds_read_b128 v[192:195], v151 offset:49152
	ds_read_b128 v[196:199], v151 offset:50176
	ds_read_b128 v[200:203], v151 offset:51200
	ds_read_b128 v[204:207], v151 offset:52224
	ds_read_b128 v[208:211], v151 offset:53248
	ds_read_b128 v[212:215], v151 offset:54272
	ds_read_b128 v[216:219], v151 offset:55296
	ds_read_b128 v[228:231], v151 offset:56320
	global_load_lds_dwordx4 v[146:147], off
	s_add_i32 m0, s0, 0x2000
	s_add_u32 s0, s50, 0x40080
	v_lshl_add_u64 v[146:147], v[232:233], 0, s[16:17]
	s_addc_u32 s1, s51, 0
	s_add_i32 s12, s13, s55
	global_load_lds_dwordx4 v[146:147], off
	s_mov_b32 m0, s12
	s_nop 0
	global_load_lds_dwordx4 v170, s[0:1]
	s_add_i32 m0, s12, 0x2000
	s_nop 0
	global_load_lds_dwordx4 v140, s[0:1]
	v_lshl_add_u64 v[146:147], v[234:235], 0, s[16:17]
	s_mov_b32 m0, s59
	s_nop 0
	global_load_lds_dwordx4 v[146:147], off
	v_lshl_add_u64 v[146:147], v[236:237], 0, s[16:17]
	s_mov_b32 m0, s60
	s_nop 0
	global_load_lds_dwordx4 v[146:147], off
	s_waitcnt vmcnt(6)
	s_waitcnt lgkmcnt(0)
	s_barrier
	s_setprio 1
	v_mfma_f32_16x16x32_bf16 v[92:95], v[128:131], v[192:195], v[92:95]
	v_mfma_f32_16x16x32_bf16 v[88:91], v[152:155], v[192:195], v[88:91]
	v_mfma_f32_16x16x32_bf16 v[84:87], v[128:131], v[200:203], v[84:87]
	v_mfma_f32_16x16x32_bf16 v[80:83], v[152:155], v[200:203], v[80:83]
	v_mfma_f32_16x16x32_bf16 v[76:79], v[128:131], v[208:211], v[76:79]
	v_mfma_f32_16x16x32_bf16 v[72:75], v[152:155], v[208:211], v[72:75]
	v_mfma_f32_16x16x32_bf16 v[64:67], v[128:131], v[216:219], v[64:67]
	v_mfma_f32_16x16x32_bf16 v[56:59], v[152:155], v[216:219], v[56:59]
	v_mfma_f32_16x16x32_bf16 v[92:95], v[132:135], v[196:199], v[92:95]
	v_mfma_f32_16x16x32_bf16 v[88:91], v[156:159], v[196:199], v[88:91]
	v_mfma_f32_16x16x32_bf16 v[84:87], v[132:135], v[204:207], v[84:87]
	v_mfma_f32_16x16x32_bf16 v[80:83], v[156:159], v[204:207], v[80:83]
	v_mfma_f32_16x16x32_bf16 v[76:79], v[132:135], v[212:215], v[76:79]
	v_mfma_f32_16x16x32_bf16 v[72:75], v[156:159], v[212:215], v[72:75]
	v_mfma_f32_16x16x32_bf16 v[64:67], v[132:135], v[228:231], v[64:67]
	v_mfma_f32_16x16x32_bf16 v[56:59], v[156:159], v[228:231], v[56:59]
	v_mfma_f32_16x16x32_bf16 v[28:31], v[160:163], v[192:195], v[28:31]
	v_mfma_f32_16x16x32_bf16 v[24:27], v[184:187], v[192:195], v[24:27]
	v_mfma_f32_16x16x32_bf16 v[20:23], v[160:163], v[200:203], v[20:23]
	v_mfma_f32_16x16x32_bf16 v[16:19], v[184:187], v[200:203], v[16:19]
	v_mfma_f32_16x16x32_bf16 v[12:15], v[160:163], v[208:211], v[12:15]
	v_mfma_f32_16x16x32_bf16 v[8:11], v[184:187], v[208:211], v[8:11]
	v_mfma_f32_16x16x32_bf16 v[4:7], v[160:163], v[216:219], v[4:7]
	v_mfma_f32_16x16x32_bf16 v[0:3], v[184:187], v[216:219], v[0:3]
	v_mfma_f32_16x16x32_bf16 v[28:31], v[164:167], v[196:199], v[28:31]
	v_mfma_f32_16x16x32_bf16 v[24:27], v[188:191], v[196:199], v[24:27]
	v_mfma_f32_16x16x32_bf16 v[20:23], v[164:167], v[204:207], v[20:23]
	v_mfma_f32_16x16x32_bf16 v[16:19], v[188:191], v[204:207], v[16:19]
	v_mfma_f32_16x16x32_bf16 v[12:15], v[164:167], v[212:215], v[12:15]
	v_mfma_f32_16x16x32_bf16 v[8:11], v[188:191], v[212:215], v[8:11]
	v_mfma_f32_16x16x32_bf16 v[4:7], v[164:167], v[228:231], v[4:7]
	v_mfma_f32_16x16x32_bf16 v[0:3], v[188:191], v[228:231], v[0:3]
	s_setprio 0
	s_barrier
	s_add_i32 s66, s66, 2
	s_add_u32 s64, s64, 0x100
	s_addc_u32 s65, s65, 0
	s_cmp_gt_u32 s66, 13
	s_mov_b64 s[46:47], s[48:49]
	s_cbranch_scc0 .LBB0_601
	s_and_b64 vcc, exec, s[30:31]
	s_cbranch_vccz .LBB0_604
	s_barrier

.Lrestag_776:
	s_add_u32 s50, s48, 0x100
	s_addc_u32 s51, s49, 0
	s_add_i32 s0, 0, 0x10000
	s_cmp_eq_u32 s66, 12
	s_cselect_b32 s55, s37, s51
	s_cselect_b32 s54, s45, s50
	s_cselect_b32 s53, s35, s65
	s_cselect_b32 s52, s63, s64
	s_add_i32 s12, 0, 0x14000
	v_add_u32_e32 v140, s0, v197
	v_add_u32_e32 v184, s12, v197
	ds_read_b128 v[128:131], v140
	ds_read_b128 v[132:135], v140 offset:1024
	ds_read_b128 v[136:139], v140 offset:2048
	ds_read_b128 v[140:143], v140 offset:3072
	ds_read_b128 v[144:147], v184
	ds_read_b128 v[148:151], v184 offset:1024
	ds_read_b128 v[164:167], v184 offset:2048
	ds_read_b128 v[184:187], v184 offset:3072
	s_add_i32 m0, s47, 0xc000
	ds_read_b128 v[188:191], v198
	ds_read_b128 v[192:195], v198 offset:1024
	ds_read_b128 v[200:203], v198 offset:2048
	ds_read_b128 v[204:207], v198 offset:3072
	ds_read_b128 v[208:211], v198 offset:4096
	ds_read_b128 v[212:215], v198 offset:5120
	ds_read_b128 v[216:219], v198 offset:6144
	ds_read_b128 v[228:231], v198 offset:7168
	global_load_lds_dwordx4 v160, s[48:49]
	s_add_i32 m0, s47, 0xe000
	s_nop 0
	global_load_lds_dwordx4 v162, s[48:49]
	s_nop 0
	s_waitcnt lgkmcnt(0)
	s_barrier
	s_setprio 1
	v_mfma_f32_16x16x32_bf16 v[124:127], v[128:131], v[188:191], 0
	v_mfma_f32_16x16x32_bf16 v[120:123], v[136:139], v[188:191], 0
	v_mfma_f32_16x16x32_bf16 v[108:111], v[128:131], v[200:203], 0
	v_mfma_f32_16x16x32_bf16 v[104:107], v[136:139], v[200:203], 0
	v_mfma_f32_16x16x32_bf16 v[92:95], v[128:131], v[208:211], 0
	v_mfma_f32_16x16x32_bf16 v[88:91], v[136:139], v[208:211], 0
	v_mfma_f32_16x16x32_bf16 v[76:79], v[128:131], v[216:219], 0
	v_mfma_f32_16x16x32_bf16 v[72:75], v[136:139], v[216:219], 0
	v_mfma_f32_16x16x32_bf16 v[124:127], v[132:135], v[192:195], v[124:127]
	v_mfma_f32_16x16x32_bf16 v[120:123], v[140:143], v[192:195], v[120:123]
	v_mfma_f32_16x16x32_bf16 v[108:111], v[132:135], v[204:207], v[108:111]
	v_mfma_f32_16x16x32_bf16 v[104:107], v[140:143], v[204:207], v[104:107]
	v_mfma_f32_16x16x32_bf16 v[92:95], v[132:135], v[212:215], v[92:95]
	v_mfma_f32_16x16x32_bf16 v[88:91], v[140:143], v[212:215], v[88:91]
	v_mfma_f32_16x16x32_bf16 v[76:79], v[132:135], v[228:231], v[76:79]
	v_mfma_f32_16x16x32_bf16 v[72:75], v[140:143], v[228:231], v[72:75]
	v_mfma_f32_16x16x32_bf16 v[116:119], v[144:147], v[188:191], 0
	v_mfma_f32_16x16x32_bf16 v[112:115], v[164:167], v[188:191], 0
	v_mfma_f32_16x16x32_bf16 v[100:103], v[144:147], v[200:203], 0
	v_mfma_f32_16x16x32_bf16 v[96:99], v[164:167], v[200:203], 0
	v_mfma_f32_16x16x32_bf16 v[84:87], v[144:147], v[208:211], 0
	v_mfma_f32_16x16x32_bf16 v[80:83], v[164:167], v[208:211], 0
	v_mfma_f32_16x16x32_bf16 v[68:71], v[144:147], v[216:219], 0
	v_mfma_f32_16x16x32_bf16 v[64:67], v[164:167], v[216:219], 0
	v_mfma_f32_16x16x32_bf16 v[116:119], v[148:151], v[192:195], v[116:119]
	v_mfma_f32_16x16x32_bf16 v[112:115], v[184:187], v[192:195], v[112:115]
	v_mfma_f32_16x16x32_bf16 v[100:103], v[148:151], v[204:207], v[100:103]
	v_mfma_f32_16x16x32_bf16 v[96:99], v[184:187], v[204:207], v[96:99]
	v_mfma_f32_16x16x32_bf16 v[84:87], v[148:151], v[212:215], v[84:87]
	v_mfma_f32_16x16x32_bf16 v[80:83], v[184:187], v[212:215], v[80:83]
	v_mfma_f32_16x16x32_bf16 v[68:71], v[148:151], v[228:231], v[68:71]
	v_mfma_f32_16x16x32_bf16 v[64:67], v[184:187], v[228:231], v[64:67]
	s_setprio 0
	s_barrier
	s_add_i32 s0, s0, s56
	v_lshl_add_u64 v[232:233], s[52:53], 0, v[170:171]
	s_mov_b32 m0, s0
	ds_read_b128 v[188:191], v198 offset:16384
	ds_read_b128 v[192:195], v198 offset:17408
	ds_read_b128 v[200:203], v198 offset:18432
	ds_read_b128 v[204:207], v198 offset:19456
	ds_read_b128 v[208:211], v198 offset:20480
	ds_read_b128 v[212:215], v198 offset:21504
	ds_read_b128 v[216:219], v198 offset:22528
	ds_read_b128 v[228:231], v198 offset:23552
	global_load_lds_dwordx4 v[232:233], off
	s_add_i32 m0, s0, 0x2000
	s_add_u32 s0, s52, 0x40000
	v_lshl_add_u64 v[234:235], s[52:53], 0, v[156:157]
	s_addc_u32 s1, s53, 0
	s_add_i32 s12, s12, s56
	global_load_lds_dwordx4 v[234:235], off
	s_mov_b32 m0, s12
	v_lshl_add_u64 v[238:239], s[54:55], 0, v[154:155]
	global_load_lds_dwordx4 v170, s[0:1]
	s_add_i32 m0, s12, 0x2000
	s_nop 0
	global_load_lds_dwordx4 v156, s[0:1]
	v_lshl_add_u64 v[236:237], s[54:55], 0, v[152:153]
	s_nop 0
	s_waitcnt lgkmcnt(0)
	s_barrier
	s_setprio 1
	v_mfma_f32_16x16x32_bf16 v[60:63], v[128:131], v[188:191], 0
	v_mfma_f32_16x16x32_bf16 v[56:59], v[136:139], v[188:191], 0
	v_mfma_f32_16x16x32_bf16 v[44:47], v[128:131], v[200:203], 0
	v_mfma_f32_16x16x32_bf16 v[40:43], v[136:139], v[200:203], 0
	v_mfma_f32_16x16x32_bf16 v[28:31], v[128:131], v[208:211], 0
	v_mfma_f32_16x16x32_bf16 v[24:27], v[136:139], v[208:211], 0
	v_mfma_f32_16x16x32_bf16 v[12:15], v[128:131], v[216:219], 0
	v_mfma_f32_16x16x32_bf16 v[8:11], v[136:139], v[216:219], 0
	v_mfma_f32_16x16x32_bf16 v[60:63], v[132:135], v[192:195], v[60:63]
	v_mfma_f32_16x16x32_bf16 v[56:59], v[140:143], v[192:195], v[56:59]
	v_mfma_f32_16x16x32_bf16 v[44:47], v[132:135], v[204:207], v[44:47]
	v_mfma_f32_16x16x32_bf16 v[40:43], v[140:143], v[204:207], v[40:43]
	v_mfma_f32_16x16x32_bf16 v[28:31], v[132:135], v[212:215], v[28:31]
	v_mfma_f32_16x16x32_bf16 v[24:27], v[140:143], v[212:215], v[24:27]
	v_mfma_f32_16x16x32_bf16 v[12:15], v[132:135], v[228:231], v[12:15]
	v_mfma_f32_16x16x32_bf16 v[8:11], v[140:143], v[228:231], v[8:11]
	v_mfma_f32_16x16x32_bf16 v[52:55], v[144:147], v[188:191], 0
	v_mfma_f32_16x16x32_bf16 v[48:51], v[164:167], v[188:191], 0
	v_mfma_f32_16x16x32_bf16 v[36:39], v[144:147], v[200:203], 0
	v_mfma_f32_16x16x32_bf16 v[32:35], v[164:167], v[200:203], 0
	v_mfma_f32_16x16x32_bf16 v[20:23], v[144:147], v[208:211], 0
	v_mfma_f32_16x16x32_bf16 v[16:19], v[164:167], v[208:211], 0
	v_mfma_f32_16x16x32_bf16 v[4:7], v[144:147], v[216:219], 0
	v_mfma_f32_16x16x32_bf16 v[0:3], v[164:167], v[216:219], 0
	v_mfma_f32_16x16x32_bf16 v[52:55], v[148:151], v[192:195], v[52:55]
	v_mfma_f32_16x16x32_bf16 v[48:51], v[184:187], v[192:195], v[48:51]
	v_mfma_f32_16x16x32_bf16 v[36:39], v[148:151], v[204:207], v[36:39]
	v_mfma_f32_16x16x32_bf16 v[32:35], v[184:187], v[204:207], v[32:35]
	v_mfma_f32_16x16x32_bf16 v[20:23], v[148:151], v[212:215], v[20:23]
	v_mfma_f32_16x16x32_bf16 v[16:19], v[184:187], v[212:215], v[16:19]
	v_mfma_f32_16x16x32_bf16 v[4:7], v[148:151], v[228:231], v[4:7]
	v_mfma_f32_16x16x32_bf16 v[0:3], v[184:187], v[228:231], v[0:3]
	s_setprio 0
	s_barrier
	s_add_i32 s12, 0, 0x18000
	s_add_i32 s13, 0, 0x1c000
	v_add_u32_e32 v140, s12, v197
	v_add_u32_e32 v184, s13, v197
	ds_read_b128 v[128:131], v140
	ds_read_b128 v[132:135], v140 offset:1024
	ds_read_b128 v[136:139], v140 offset:2048
	ds_read_b128 v[140:143], v140 offset:3072
	ds_read_b128 v[144:147], v184
	ds_read_b128 v[148:151], v184 offset:1024
	ds_read_b128 v[164:167], v184 offset:2048
	ds_read_b128 v[184:187], v184 offset:3072
	s_add_u32 s0, s54, 0x40000
	s_addc_u32 s1, s55, 0
	s_mov_b32 m0, s58
	ds_read_b128 v[188:191], v198 offset:32768
	ds_read_b128 v[192:195], v198 offset:33792
	ds_read_b128 v[200:203], v198 offset:34816
	ds_read_b128 v[204:207], v198 offset:35840
	ds_read_b128 v[208:211], v198 offset:36864
	ds_read_b128 v[212:215], v198 offset:37888
	ds_read_b128 v[216:219], v198 offset:38912
	ds_read_b128 v[228:231], v198 offset:39936
	global_load_lds_dwordx4 v152, s[0:1]
	s_mov_b32 m0, s59
	s_nop 0
	global_load_lds_dwordx4 v154, s[0:1]
	s_mov_b32 m0, s47
	s_nop 0
	global_load_lds_dwordx4 v[236:237], off
	s_mov_b32 m0, s57
	s_nop 0
	global_load_lds_dwordx4 v[238:239], off
	s_waitcnt vmcnt(8)
	s_waitcnt lgkmcnt(0)
	s_barrier
	s_setprio 1
	v_mfma_f32_16x16x32_bf16 v[124:127], v[128:131], v[188:191], v[124:127]
	v_mfma_f32_16x16x32_bf16 v[120:123], v[136:139], v[188:191], v[120:123]
	v_mfma_f32_16x16x32_bf16 v[108:111], v[128:131], v[200:203], v[108:111]
	v_mfma_f32_16x16x32_bf16 v[104:107], v[136:139], v[200:203], v[104:107]
	v_mfma_f32_16x16x32_bf16 v[92:95], v[128:131], v[208:211], v[92:95]
	v_mfma_f32_16x16x32_bf16 v[88:91], v[136:139], v[208:211], v[88:91]
	v_mfma_f32_16x16x32_bf16 v[76:79], v[128:131], v[216:219], v[76:79]
	v_mfma_f32_16x16x32_bf16 v[72:75], v[136:139], v[216:219], v[72:75]
	v_mfma_f32_16x16x32_bf16 v[124:127], v[132:135], v[192:195], v[124:127]
	v_mfma_f32_16x16x32_bf16 v[120:123], v[140:143], v[192:195], v[120:123]
	v_mfma_f32_16x16x32_bf16 v[108:111], v[132:135], v[204:207], v[108:111]
	v_mfma_f32_16x16x32_bf16 v[104:107], v[140:143], v[204:207], v[104:107]
	v_mfma_f32_16x16x32_bf16 v[92:95], v[132:135], v[212:215], v[92:95]
	v_mfma_f32_16x16x32_bf16 v[88:91], v[140:143], v[212:215], v[88:91]
	v_mfma_f32_16x16x32_bf16 v[76:79], v[132:135], v[228:231], v[76:79]
	v_mfma_f32_16x16x32_bf16 v[72:75], v[140:143], v[228:231], v[72:75]
	v_mfma_f32_16x16x32_bf16 v[116:119], v[144:147], v[188:191], v[116:119]
	v_mfma_f32_16x16x32_bf16 v[112:115], v[164:167], v[188:191], v[112:115]
	v_mfma_f32_16x16x32_bf16 v[100:103], v[144:147], v[200:203], v[100:103]
	v_mfma_f32_16x16x32_bf16 v[96:99], v[164:167], v[200:203], v[96:99]
	v_mfma_f32_16x16x32_bf16 v[84:87], v[144:147], v[208:211], v[84:87]
	v_mfma_f32_16x16x32_bf16 v[80:83], v[164:167], v[208:211], v[80:83]
	v_mfma_f32_16x16x32_bf16 v[68:71], v[144:147], v[216:219], v[68:71]
	v_mfma_f32_16x16x32_bf16 v[64:67], v[164:167], v[216:219], v[64:67]
	v_mfma_f32_16x16x32_bf16 v[116:119], v[148:151], v[192:195], v[116:119]
	v_mfma_f32_16x16x32_bf16 v[112:115], v[184:187], v[192:195], v[112:115]
	v_mfma_f32_16x16x32_bf16 v[100:103], v[148:151], v[204:207], v[100:103]
	v_mfma_f32_16x16x32_bf16 v[96:99], v[184:187], v[204:207], v[96:99]
	v_mfma_f32_16x16x32_bf16 v[84:87], v[148:151], v[212:215], v[84:87]
	v_mfma_f32_16x16x32_bf16 v[80:83], v[184:187], v[212:215], v[80:83]
	v_mfma_f32_16x16x32_bf16 v[68:71], v[148:151], v[228:231], v[68:71]
	v_mfma_f32_16x16x32_bf16 v[64:67], v[184:187], v[228:231], v[64:67]
	s_setprio 0
	s_barrier
	s_add_i32 s0, s12, s56
	v_lshl_add_u64 v[232:233], v[232:233], 0, s[16:17]
	s_mov_b32 m0, s0
	ds_read_b128 v[188:191], v198 offset:49152
	ds_read_b128 v[192:195], v198 offset:50176
	ds_read_b128 v[200:203], v198 offset:51200
	ds_read_b128 v[204:207], v198 offset:52224
	ds_read_b128 v[208:211], v198 offset:53248
	ds_read_b128 v[212:215], v198 offset:54272
	ds_read_b128 v[216:219], v198 offset:55296
	ds_read_b128 v[228:231], v198 offset:56320
	global_load_lds_dwordx4 v[232:233], off
	s_add_i32 m0, s0, 0x2000
	s_add_u32 s0, s52, 0x40080
	v_lshl_add_u64 v[232:233], v[234:235], 0, s[16:17]
	s_addc_u32 s1, s53, 0
	s_add_i32 s12, s13, s56
	global_load_lds_dwordx4 v[232:233], off
	s_mov_b32 m0, s12
	s_nop 0
	global_load_lds_dwordx4 v170, s[0:1]
	s_add_i32 m0, s12, 0x2000
	s_nop 0
	global_load_lds_dwordx4 v156, s[0:1]
	v_lshl_add_u64 v[232:233], v[236:237], 0, s[16:17]
	s_mov_b32 m0, s60
	s_nop 0
	global_load_lds_dwordx4 v[232:233], off
	v_lshl_add_u64 v[232:233], v[238:239], 0, s[16:17]
	s_mov_b32 m0, s61
	s_nop 0
	global_load_lds_dwordx4 v[232:233], off
	s_waitcnt vmcnt(6)
	s_waitcnt lgkmcnt(0)
	s_barrier
	s_setprio 1
	v_mfma_f32_16x16x32_bf16 v[60:63], v[128:131], v[188:191], v[60:63]
	v_mfma_f32_16x16x32_bf16 v[56:59], v[136:139], v[188:191], v[56:59]
	v_mfma_f32_16x16x32_bf16 v[44:47], v[128:131], v[200:203], v[44:47]
	v_mfma_f32_16x16x32_bf16 v[40:43], v[136:139], v[200:203], v[40:43]
	v_mfma_f32_16x16x32_bf16 v[28:31], v[128:131], v[208:211], v[28:31]
	v_mfma_f32_16x16x32_bf16 v[24:27], v[136:139], v[208:211], v[24:27]
	v_mfma_f32_16x16x32_bf16 v[12:15], v[128:131], v[216:219], v[12:15]
	v_mfma_f32_16x16x32_bf16 v[8:11], v[136:139], v[216:219], v[8:11]
	v_mfma_f32_16x16x32_bf16 v[60:63], v[132:135], v[192:195], v[60:63]
	v_mfma_f32_16x16x32_bf16 v[56:59], v[140:143], v[192:195], v[56:59]
	v_mfma_f32_16x16x32_bf16 v[44:47], v[132:135], v[204:207], v[44:47]
	v_mfma_f32_16x16x32_bf16 v[40:43], v[140:143], v[204:207], v[40:43]
	v_mfma_f32_16x16x32_bf16 v[28:31], v[132:135], v[212:215], v[28:31]
	v_mfma_f32_16x16x32_bf16 v[24:27], v[140:143], v[212:215], v[24:27]
	v_mfma_f32_16x16x32_bf16 v[12:15], v[132:135], v[228:231], v[12:15]
	v_mfma_f32_16x16x32_bf16 v[8:11], v[140:143], v[228:231], v[8:11]
	v_mfma_f32_16x16x32_bf16 v[52:55], v[144:147], v[188:191], v[52:55]
	v_mfma_f32_16x16x32_bf16 v[48:51], v[164:167], v[188:191], v[48:51]
	v_mfma_f32_16x16x32_bf16 v[36:39], v[144:147], v[200:203], v[36:39]
	v_mfma_f32_16x16x32_bf16 v[32:35], v[164:167], v[200:203], v[32:35]
	v_mfma_f32_16x16x32_bf16 v[20:23], v[144:147], v[208:211], v[20:23]
	v_mfma_f32_16x16x32_bf16 v[16:19], v[164:167], v[208:211], v[16:19]
	v_mfma_f32_16x16x32_bf16 v[4:7], v[144:147], v[216:219], v[4:7]
	v_mfma_f32_16x16x32_bf16 v[0:3], v[164:167], v[216:219], v[0:3]
	v_mfma_f32_16x16x32_bf16 v[52:55], v[148:151], v[192:195], v[52:55]
	v_mfma_f32_16x16x32_bf16 v[48:51], v[184:187], v[192:195], v[48:51]
	v_mfma_f32_16x16x32_bf16 v[36:39], v[148:151], v[204:207], v[36:39]
	v_mfma_f32_16x16x32_bf16 v[32:35], v[184:187], v[204:207], v[32:35]
	v_mfma_f32_16x16x32_bf16 v[20:23], v[148:151], v[212:215], v[20:23]
	v_mfma_f32_16x16x32_bf16 v[16:19], v[184:187], v[212:215], v[16:19]
	v_mfma_f32_16x16x32_bf16 v[4:7], v[148:151], v[228:231], v[4:7]
	v_mfma_f32_16x16x32_bf16 v[0:3], v[184:187], v[228:231], v[0:3]
	s_setprio 0
	s_barrier
	s_add_i32 s66, s66, 2
	s_add_u32 s64, s64, 0x100
	s_addc_u32 s65, s65, 0
	s_cmp_gt_u32 s66, 13
	s_mov_b64 s[48:49], s[50:51]
.LBB0_776:
	s_add_u32 s50, s48, 0x100
	s_addc_u32 s51, s49, 0
	s_add_i32 s0, 0, 0x10000
	s_cmp_eq_u32 s66, 12
	s_cselect_b32 s55, s37, s51
	s_cselect_b32 s54, s45, s50
	s_cselect_b32 s53, s35, s65
	s_cselect_b32 s52, s63, s64
	s_add_i32 s12, 0, 0x14000
	v_add_u32_e32 v140, s0, v197
	v_add_u32_e32 v184, s12, v197
	ds_read_b128 v[128:131], v140
	ds_read_b128 v[132:135], v140 offset:1024
	ds_read_b128 v[136:139], v140 offset:2048
	ds_read_b128 v[140:143], v140 offset:3072
	ds_read_b128 v[144:147], v184
	ds_read_b128 v[148:151], v184 offset:1024
	ds_read_b128 v[164:167], v184 offset:2048
	ds_read_b128 v[184:187], v184 offset:3072
	s_add_i32 m0, s47, 0xc000
	ds_read_b128 v[188:191], v198
	ds_read_b128 v[192:195], v198 offset:1024
	ds_read_b128 v[200:203], v198 offset:2048
	ds_read_b128 v[204:207], v198 offset:3072
	ds_read_b128 v[208:211], v198 offset:4096
	ds_read_b128 v[212:215], v198 offset:5120
	ds_read_b128 v[216:219], v198 offset:6144
	ds_read_b128 v[228:231], v198 offset:7168
	global_load_lds_dwordx4 v160, s[48:49]
	s_add_i32 m0, s47, 0xe000
	s_nop 0
	global_load_lds_dwordx4 v162, s[48:49]
	s_waitcnt vmcnt(8)
	s_waitcnt lgkmcnt(0)
	s_barrier
	s_setprio 1
	v_mfma_f32_16x16x32_bf16 v[124:127], v[128:131], v[188:191], v[124:127]
	v_mfma_f32_16x16x32_bf16 v[120:123], v[136:139], v[188:191], v[120:123]
	v_mfma_f32_16x16x32_bf16 v[108:111], v[128:131], v[200:203], v[108:111]
	v_mfma_f32_16x16x32_bf16 v[104:107], v[136:139], v[200:203], v[104:107]
	v_mfma_f32_16x16x32_bf16 v[92:95], v[128:131], v[208:211], v[92:95]
	v_mfma_f32_16x16x32_bf16 v[88:91], v[136:139], v[208:211], v[88:91]
	v_mfma_f32_16x16x32_bf16 v[76:79], v[128:131], v[216:219], v[76:79]
	v_mfma_f32_16x16x32_bf16 v[72:75], v[136:139], v[216:219], v[72:75]
	v_mfma_f32_16x16x32_bf16 v[124:127], v[132:135], v[192:195], v[124:127]
	v_mfma_f32_16x16x32_bf16 v[120:123], v[140:143], v[192:195], v[120:123]
	v_mfma_f32_16x16x32_bf16 v[108:111], v[132:135], v[204:207], v[108:111]
	v_mfma_f32_16x16x32_bf16 v[104:107], v[140:143], v[204:207], v[104:107]
	v_mfma_f32_16x16x32_bf16 v[92:95], v[132:135], v[212:215], v[92:95]
	v_mfma_f32_16x16x32_bf16 v[88:91], v[140:143], v[212:215], v[88:91]
	v_mfma_f32_16x16x32_bf16 v[76:79], v[132:135], v[228:231], v[76:79]
	v_mfma_f32_16x16x32_bf16 v[72:75], v[140:143], v[228:231], v[72:75]
	v_mfma_f32_16x16x32_bf16 v[116:119], v[144:147], v[188:191], v[116:119]
	v_mfma_f32_16x16x32_bf16 v[112:115], v[164:167], v[188:191], v[112:115]
	v_mfma_f32_16x16x32_bf16 v[100:103], v[144:147], v[200:203], v[100:103]
	v_mfma_f32_16x16x32_bf16 v[96:99], v[164:167], v[200:203], v[96:99]
	v_mfma_f32_16x16x32_bf16 v[84:87], v[144:147], v[208:211], v[84:87]
	v_mfma_f32_16x16x32_bf16 v[80:83], v[164:167], v[208:211], v[80:83]
	v_mfma_f32_16x16x32_bf16 v[68:71], v[144:147], v[216:219], v[68:71]
	v_mfma_f32_16x16x32_bf16 v[64:67], v[164:167], v[216:219], v[64:67]
	v_mfma_f32_16x16x32_bf16 v[116:119], v[148:151], v[192:195], v[116:119]
	v_mfma_f32_16x16x32_bf16 v[112:115], v[184:187], v[192:195], v[112:115]
	v_mfma_f32_16x16x32_bf16 v[100:103], v[148:151], v[204:207], v[100:103]
	v_mfma_f32_16x16x32_bf16 v[96:99], v[184:187], v[204:207], v[96:99]
	v_mfma_f32_16x16x32_bf16 v[84:87], v[148:151], v[212:215], v[84:87]
	v_mfma_f32_16x16x32_bf16 v[80:83], v[184:187], v[212:215], v[80:83]
	v_mfma_f32_16x16x32_bf16 v[68:71], v[148:151], v[228:231], v[68:71]
	v_mfma_f32_16x16x32_bf16 v[64:67], v[184:187], v[228:231], v[64:67]
	s_setprio 0
	s_barrier
	s_add_i32 s0, s0, s56
	v_lshl_add_u64 v[232:233], s[52:53], 0, v[170:171]
	s_mov_b32 m0, s0
	ds_read_b128 v[188:191], v198 offset:16384
	ds_read_b128 v[192:195], v198 offset:17408
	ds_read_b128 v[200:203], v198 offset:18432
	ds_read_b128 v[204:207], v198 offset:19456
	ds_read_b128 v[208:211], v198 offset:20480
	ds_read_b128 v[212:215], v198 offset:21504
	ds_read_b128 v[216:219], v198 offset:22528
	ds_read_b128 v[228:231], v198 offset:23552
	global_load_lds_dwordx4 v[232:233], off
	s_add_i32 m0, s0, 0x2000
	s_add_u32 s0, s52, 0x40000
	v_lshl_add_u64 v[234:235], s[52:53], 0, v[156:157]
	s_addc_u32 s1, s53, 0
	s_add_i32 s12, s12, s56
	global_load_lds_dwordx4 v[234:235], off
	s_mov_b32 m0, s12
	v_lshl_add_u64 v[238:239], s[54:55], 0, v[154:155]
	global_load_lds_dwordx4 v170, s[0:1]
	s_add_i32 m0, s12, 0x2000
	s_nop 0
	global_load_lds_dwordx4 v156, s[0:1]
	v_lshl_add_u64 v[236:237], s[54:55], 0, v[152:153]
	s_waitcnt vmcnt(6)
	s_waitcnt lgkmcnt(0)
	s_barrier
	s_setprio 1
	v_mfma_f32_16x16x32_bf16 v[60:63], v[128:131], v[188:191], v[60:63]
	v_mfma_f32_16x16x32_bf16 v[56:59], v[136:139], v[188:191], v[56:59]
	v_mfma_f32_16x16x32_bf16 v[44:47], v[128:131], v[200:203], v[44:47]
	v_mfma_f32_16x16x32_bf16 v[40:43], v[136:139], v[200:203], v[40:43]
	v_mfma_f32_16x16x32_bf16 v[28:31], v[128:131], v[208:211], v[28:31]
	v_mfma_f32_16x16x32_bf16 v[24:27], v[136:139], v[208:211], v[24:27]
	v_mfma_f32_16x16x32_bf16 v[12:15], v[128:131], v[216:219], v[12:15]
	v_mfma_f32_16x16x32_bf16 v[8:11], v[136:139], v[216:219], v[8:11]
	v_mfma_f32_16x16x32_bf16 v[60:63], v[132:135], v[192:195], v[60:63]
	v_mfma_f32_16x16x32_bf16 v[56:59], v[140:143], v[192:195], v[56:59]
	v_mfma_f32_16x16x32_bf16 v[44:47], v[132:135], v[204:207], v[44:47]
	v_mfma_f32_16x16x32_bf16 v[40:43], v[140:143], v[204:207], v[40:43]
	v_mfma_f32_16x16x32_bf16 v[28:31], v[132:135], v[212:215], v[28:31]
	v_mfma_f32_16x16x32_bf16 v[24:27], v[140:143], v[212:215], v[24:27]
	v_mfma_f32_16x16x32_bf16 v[12:15], v[132:135], v[228:231], v[12:15]
	v_mfma_f32_16x16x32_bf16 v[8:11], v[140:143], v[228:231], v[8:11]
	v_mfma_f32_16x16x32_bf16 v[52:55], v[144:147], v[188:191], v[52:55]
	v_mfma_f32_16x16x32_bf16 v[48:51], v[164:167], v[188:191], v[48:51]
	v_mfma_f32_16x16x32_bf16 v[36:39], v[144:147], v[200:203], v[36:39]
	v_mfma_f32_16x16x32_bf16 v[32:35], v[164:167], v[200:203], v[32:35]
	v_mfma_f32_16x16x32_bf16 v[20:23], v[144:147], v[208:211], v[20:23]
	v_mfma_f32_16x16x32_bf16 v[16:19], v[164:167], v[208:211], v[16:19]
	v_mfma_f32_16x16x32_bf16 v[4:7], v[144:147], v[216:219], v[4:7]
	v_mfma_f32_16x16x32_bf16 v[0:3], v[164:167], v[216:219], v[0:3]
	v_mfma_f32_16x16x32_bf16 v[52:55], v[148:151], v[192:195], v[52:55]
	v_mfma_f32_16x16x32_bf16 v[48:51], v[184:187], v[192:195], v[48:51]
	v_mfma_f32_16x16x32_bf16 v[36:39], v[148:151], v[204:207], v[36:39]
	v_mfma_f32_16x16x32_bf16 v[32:35], v[184:187], v[204:207], v[32:35]
	v_mfma_f32_16x16x32_bf16 v[20:23], v[148:151], v[212:215], v[20:23]
	v_mfma_f32_16x16x32_bf16 v[16:19], v[184:187], v[212:215], v[16:19]
	v_mfma_f32_16x16x32_bf16 v[4:7], v[148:151], v[228:231], v[4:7]
	v_mfma_f32_16x16x32_bf16 v[0:3], v[184:187], v[228:231], v[0:3]
	s_setprio 0
	s_barrier
	s_add_i32 s12, 0, 0x18000
	s_add_i32 s13, 0, 0x1c000
	v_add_u32_e32 v140, s12, v197
	v_add_u32_e32 v184, s13, v197
	ds_read_b128 v[128:131], v140
	ds_read_b128 v[132:135], v140 offset:1024
	ds_read_b128 v[136:139], v140 offset:2048
	ds_read_b128 v[140:143], v140 offset:3072
	ds_read_b128 v[144:147], v184
	ds_read_b128 v[148:151], v184 offset:1024
	ds_read_b128 v[164:167], v184 offset:2048
	ds_read_b128 v[184:187], v184 offset:3072
	s_add_u32 s0, s54, 0x40000
	s_addc_u32 s1, s55, 0
	s_mov_b32 m0, s58
	ds_read_b128 v[188:191], v198 offset:32768
	ds_read_b128 v[192:195], v198 offset:33792
	ds_read_b128 v[200:203], v198 offset:34816
	ds_read_b128 v[204:207], v198 offset:35840
	ds_read_b128 v[208:211], v198 offset:36864
	ds_read_b128 v[212:215], v198 offset:37888
	ds_read_b128 v[216:219], v198 offset:38912
	ds_read_b128 v[228:231], v198 offset:39936
	global_load_lds_dwordx4 v152, s[0:1]
	s_mov_b32 m0, s59
	s_nop 0
	global_load_lds_dwordx4 v154, s[0:1]
	s_mov_b32 m0, s47
	s_nop 0
	global_load_lds_dwordx4 v[236:237], off
	s_mov_b32 m0, s57
	s_nop 0
	global_load_lds_dwordx4 v[238:239], off
	s_waitcnt vmcnt(8)
	s_waitcnt lgkmcnt(0)
	s_barrier
	s_setprio 1
	v_mfma_f32_16x16x32_bf16 v[124:127], v[128:131], v[188:191], v[124:127]
	v_mfma_f32_16x16x32_bf16 v[120:123], v[136:139], v[188:191], v[120:123]
	v_mfma_f32_16x16x32_bf16 v[108:111], v[128:131], v[200:203], v[108:111]
	v_mfma_f32_16x16x32_bf16 v[104:107], v[136:139], v[200:203], v[104:107]
	v_mfma_f32_16x16x32_bf16 v[92:95], v[128:131], v[208:211], v[92:95]
	v_mfma_f32_16x16x32_bf16 v[88:91], v[136:139], v[208:211], v[88:91]
	v_mfma_f32_16x16x32_bf16 v[76:79], v[128:131], v[216:219], v[76:79]
	v_mfma_f32_16x16x32_bf16 v[72:75], v[136:139], v[216:219], v[72:75]
	v_mfma_f32_16x16x32_bf16 v[124:127], v[132:135], v[192:195], v[124:127]
	v_mfma_f32_16x16x32_bf16 v[120:123], v[140:143], v[192:195], v[120:123]
	v_mfma_f32_16x16x32_bf16 v[108:111], v[132:135], v[204:207], v[108:111]
	v_mfma_f32_16x16x32_bf16 v[104:107], v[140:143], v[204:207], v[104:107]
	v_mfma_f32_16x16x32_bf16 v[92:95], v[132:135], v[212:215], v[92:95]
	v_mfma_f32_16x16x32_bf16 v[88:91], v[140:143], v[212:215], v[88:91]
	v_mfma_f32_16x16x32_bf16 v[76:79], v[132:135], v[228:231], v[76:79]
	v_mfma_f32_16x16x32_bf16 v[72:75], v[140:143], v[228:231], v[72:75]
	v_mfma_f32_16x16x32_bf16 v[116:119], v[144:147], v[188:191], v[116:119]
	v_mfma_f32_16x16x32_bf16 v[112:115], v[164:167], v[188:191], v[112:115]
	v_mfma_f32_16x16x32_bf16 v[100:103], v[144:147], v[200:203], v[100:103]
	v_mfma_f32_16x16x32_bf16 v[96:99], v[164:167], v[200:203], v[96:99]
	v_mfma_f32_16x16x32_bf16 v[84:87], v[144:147], v[208:211], v[84:87]
	v_mfma_f32_16x16x32_bf16 v[80:83], v[164:167], v[208:211], v[80:83]
	v_mfma_f32_16x16x32_bf16 v[68:71], v[144:147], v[216:219], v[68:71]
	v_mfma_f32_16x16x32_bf16 v[64:67], v[164:167], v[216:219], v[64:67]
	v_mfma_f32_16x16x32_bf16 v[116:119], v[148:151], v[192:195], v[116:119]
	v_mfma_f32_16x16x32_bf16 v[112:115], v[184:187], v[192:195], v[112:115]
	v_mfma_f32_16x16x32_bf16 v[100:103], v[148:151], v[204:207], v[100:103]
	v_mfma_f32_16x16x32_bf16 v[96:99], v[184:187], v[204:207], v[96:99]
	v_mfma_f32_16x16x32_bf16 v[84:87], v[148:151], v[212:215], v[84:87]
	v_mfma_f32_16x16x32_bf16 v[80:83], v[184:187], v[212:215], v[80:83]
	v_mfma_f32_16x16x32_bf16 v[68:71], v[148:151], v[228:231], v[68:71]
	v_mfma_f32_16x16x32_bf16 v[64:67], v[184:187], v[228:231], v[64:67]
	s_setprio 0
	s_barrier
	s_add_i32 s0, s12, s56
	v_lshl_add_u64 v[232:233], v[232:233], 0, s[16:17]
	s_mov_b32 m0, s0
	ds_read_b128 v[188:191], v198 offset:49152
	ds_read_b128 v[192:195], v198 offset:50176
	ds_read_b128 v[200:203], v198 offset:51200
	ds_read_b128 v[204:207], v198 offset:52224
	ds_read_b128 v[208:211], v198 offset:53248
	ds_read_b128 v[212:215], v198 offset:54272
	ds_read_b128 v[216:219], v198 offset:55296
	ds_read_b128 v[228:231], v198 offset:56320
	global_load_lds_dwordx4 v[232:233], off
	s_add_i32 m0, s0, 0x2000
	s_add_u32 s0, s52, 0x40080
	v_lshl_add_u64 v[232:233], v[234:235], 0, s[16:17]
	s_addc_u32 s1, s53, 0
	s_add_i32 s12, s13, s56
	global_load_lds_dwordx4 v[232:233], off
	s_mov_b32 m0, s12
	s_nop 0
	global_load_lds_dwordx4 v170, s[0:1]
	s_add_i32 m0, s12, 0x2000
	s_nop 0
	global_load_lds_dwordx4 v156, s[0:1]
	v_lshl_add_u64 v[232:233], v[236:237], 0, s[16:17]
	s_mov_b32 m0, s60
	s_nop 0
	global_load_lds_dwordx4 v[232:233], off
	v_lshl_add_u64 v[232:233], v[238:239], 0, s[16:17]
	s_mov_b32 m0, s61
	s_nop 0
	global_load_lds_dwordx4 v[232:233], off
	s_waitcnt vmcnt(6)
	s_waitcnt lgkmcnt(0)
	s_barrier
	s_setprio 1
	v_mfma_f32_16x16x32_bf16 v[60:63], v[128:131], v[188:191], v[60:63]
	v_mfma_f32_16x16x32_bf16 v[56:59], v[136:139], v[188:191], v[56:59]
	v_mfma_f32_16x16x32_bf16 v[44:47], v[128:131], v[200:203], v[44:47]
	v_mfma_f32_16x16x32_bf16 v[40:43], v[136:139], v[200:203], v[40:43]
	v_mfma_f32_16x16x32_bf16 v[28:31], v[128:131], v[208:211], v[28:31]
	v_mfma_f32_16x16x32_bf16 v[24:27], v[136:139], v[208:211], v[24:27]
	v_mfma_f32_16x16x32_bf16 v[12:15], v[128:131], v[216:219], v[12:15]
	v_mfma_f32_16x16x32_bf16 v[8:11], v[136:139], v[216:219], v[8:11]
	v_mfma_f32_16x16x32_bf16 v[60:63], v[132:135], v[192:195], v[60:63]
	v_mfma_f32_16x16x32_bf16 v[56:59], v[140:143], v[192:195], v[56:59]
	v_mfma_f32_16x16x32_bf16 v[44:47], v[132:135], v[204:207], v[44:47]
	v_mfma_f32_16x16x32_bf16 v[40:43], v[140:143], v[204:207], v[40:43]
	v_mfma_f32_16x16x32_bf16 v[28:31], v[132:135], v[212:215], v[28:31]
	v_mfma_f32_16x16x32_bf16 v[24:27], v[140:143], v[212:215], v[24:27]
	v_mfma_f32_16x16x32_bf16 v[12:15], v[132:135], v[228:231], v[12:15]
	v_mfma_f32_16x16x32_bf16 v[8:11], v[140:143], v[228:231], v[8:11]
	v_mfma_f32_16x16x32_bf16 v[52:55], v[144:147], v[188:191], v[52:55]
	v_mfma_f32_16x16x32_bf16 v[48:51], v[164:167], v[188:191], v[48:51]
	v_mfma_f32_16x16x32_bf16 v[36:39], v[144:147], v[200:203], v[36:39]
	v_mfma_f32_16x16x32_bf16 v[32:35], v[164:167], v[200:203], v[32:35]
	v_mfma_f32_16x16x32_bf16 v[20:23], v[144:147], v[208:211], v[20:23]
	v_mfma_f32_16x16x32_bf16 v[16:19], v[164:167], v[208:211], v[16:19]
	v_mfma_f32_16x16x32_bf16 v[4:7], v[144:147], v[216:219], v[4:7]
	v_mfma_f32_16x16x32_bf16 v[0:3], v[164:167], v[216:219], v[0:3]
	v_mfma_f32_16x16x32_bf16 v[52:55], v[148:151], v[192:195], v[52:55]
	v_mfma_f32_16x16x32_bf16 v[48:51], v[184:187], v[192:195], v[48:51]
	v_mfma_f32_16x16x32_bf16 v[36:39], v[148:151], v[204:207], v[36:39]
	v_mfma_f32_16x16x32_bf16 v[32:35], v[184:187], v[204:207], v[32:35]
	v_mfma_f32_16x16x32_bf16 v[20:23], v[148:151], v[212:215], v[20:23]
	v_mfma_f32_16x16x32_bf16 v[16:19], v[184:187], v[212:215], v[16:19]
	v_mfma_f32_16x16x32_bf16 v[4:7], v[148:151], v[228:231], v[4:7]
	v_mfma_f32_16x16x32_bf16 v[0:3], v[184:187], v[228:231], v[0:3]
	s_setprio 0
	s_barrier
	s_add_i32 s66, s66, 2
	s_add_u32 s64, s64, 0x100
	s_addc_u32 s65, s65, 0
	s_cmp_gt_u32 s66, 13
	s_mov_b64 s[48:49], s[50:51]
	s_cbranch_scc0 .LBB0_776
	s_and_b64 vcc, exec, s[30:31]
	s_cbranch_vccz .LBB0_779
	s_barrier

.Lrestag_863:
	s_add_u32 s62, s60, 0x100
	s_addc_u32 s63, s61, 0
	s_add_i32 s0, 0, 0x10000
	s_cmp_eq_u32 s12, 12
	s_cselect_b32 s67, s23, s63
	s_cselect_b32 s66, s51, s62
	s_cselect_b32 s65, s49, vcc_hi
	s_cselect_b32 s64, s57, vcc_lo
	s_add_i32 s13, 0, 0x14000
	v_add_u32_e32 v64, s0, v228
	v_add_u32_e32 v92, s13, v228
	ds_read_b128 v[48:51], v64
	ds_read_b128 v[52:55], v64 offset:1024
	ds_read_b128 v[60:63], v64 offset:2048
	ds_read_b128 v[64:67], v64 offset:3072
	ds_read_b128 v[72:75], v92
	ds_read_b128 v[80:83], v92 offset:1024
	ds_read_b128 v[84:87], v92 offset:2048
	ds_read_b128 v[92:95], v92 offset:3072
	s_add_i32 m0, s59, 0xc000
	ds_read_b128 v[112:115], v230
	ds_read_b128 v[164:167], v230 offset:1024
	ds_read_b128 v[194:197], v230 offset:2048
	ds_read_b128 v[198:201], v230 offset:3072
	ds_read_b128 v[202:205], v230 offset:4096
	ds_read_b128 v[206:209], v230 offset:5120
	ds_read_b128 v[210:213], v230 offset:6144
	ds_read_b128 v[214:217], v230 offset:7168
	global_load_lds_dwordx4 v190, s[60:61]
	s_add_i32 m0, s59, 0xe000
	s_nop 0
	global_load_lds_dwordx4 v192, s[60:61]
	s_nop 0
	s_waitcnt lgkmcnt(0)
	s_barrier
	s_setprio 1
	v_mfma_f32_16x16x32_bf16 v[160:163], v[48:51], v[112:115], 0
	v_mfma_f32_16x16x32_bf16 v[156:159], v[60:63], v[112:115], 0
	v_mfma_f32_16x16x32_bf16 v[128:131], v[48:51], v[194:197], 0
	v_mfma_f32_16x16x32_bf16 v[124:127], v[60:63], v[194:197], 0
	v_mfma_f32_16x16x32_bf16 v[108:111], v[48:51], v[202:205], 0
	v_mfma_f32_16x16x32_bf16 v[104:107], v[60:63], v[202:205], 0
	v_mfma_f32_16x16x32_bf16 v[100:103], v[48:51], v[210:213], 0
	v_mfma_f32_16x16x32_bf16 v[96:99], v[60:63], v[210:213], 0
	v_mfma_f32_16x16x32_bf16 v[160:163], v[52:55], v[164:167], v[160:163]
	v_mfma_f32_16x16x32_bf16 v[156:159], v[64:67], v[164:167], v[156:159]
	v_mfma_f32_16x16x32_bf16 v[128:131], v[52:55], v[198:201], v[128:131]
	v_mfma_f32_16x16x32_bf16 v[124:127], v[64:67], v[198:201], v[124:127]
	v_mfma_f32_16x16x32_bf16 v[108:111], v[52:55], v[206:209], v[108:111]
	v_mfma_f32_16x16x32_bf16 v[104:107], v[64:67], v[206:209], v[104:107]
	v_mfma_f32_16x16x32_bf16 v[100:103], v[52:55], v[214:217], v[100:103]
	v_mfma_f32_16x16x32_bf16 v[96:99], v[64:67], v[214:217], v[96:99]
	v_mfma_f32_16x16x32_bf16 v[152:155], v[72:75], v[112:115], 0
	v_mfma_f32_16x16x32_bf16 v[120:123], v[72:75], v[194:197], 0
	v_mfma_f32_16x16x32_bf16 v[116:119], v[84:87], v[194:197], 0
	v_mfma_f32_16x16x32_bf16 v[144:147], v[72:75], v[202:205], 0
	v_mfma_f32_16x16x32_bf16 v[140:143], v[84:87], v[202:205], 0
	v_mfma_f32_16x16x32_bf16 v[136:139], v[72:75], v[210:213], 0
	v_mfma_f32_16x16x32_bf16 v[132:135], v[84:87], v[210:213], 0
	v_mfma_f32_16x16x32_bf16 v[152:155], v[80:83], v[164:167], v[152:155]
	v_mfma_f32_16x16x32_bf16 v[112:115], v[84:87], v[112:115], 0
	v_mfma_f32_16x16x32_bf16 v[120:123], v[80:83], v[198:201], v[120:123]
	v_mfma_f32_16x16x32_bf16 v[116:119], v[92:95], v[198:201], v[116:119]
	v_mfma_f32_16x16x32_bf16 v[144:147], v[80:83], v[206:209], v[144:147]
	v_mfma_f32_16x16x32_bf16 v[140:143], v[92:95], v[206:209], v[140:143]
	v_mfma_f32_16x16x32_bf16 v[136:139], v[80:83], v[214:217], v[136:139]
	v_mfma_f32_16x16x32_bf16 v[132:135], v[92:95], v[214:217], v[132:135]
	v_mfma_f32_16x16x32_bf16 v[112:115], v[92:95], v[164:167], v[112:115]
	s_setprio 0
	s_barrier
	s_add_i32 s0, s0, s96
	v_lshl_add_u64 v[218:219], s[64:65], 0, v[170:171]
	s_mov_b32 m0, s0
	ds_read_b128 v[148:151], v230 offset:16384
	ds_read_b128 v[164:167], v230 offset:17408
	ds_read_b128 v[194:197], v230 offset:18432
	ds_read_b128 v[198:201], v230 offset:19456
	ds_read_b128 v[202:205], v230 offset:20480
	ds_read_b128 v[206:209], v230 offset:21504
	ds_read_b128 v[210:213], v230 offset:22528
	ds_read_b128 v[214:217], v230 offset:23552
	global_load_lds_dwordx4 v[218:219], off
	s_add_i32 m0, s0, 0x2000
	s_add_u32 s0, s64, 0x40000
	v_lshl_add_u64 v[232:233], s[64:65], 0, v[188:189]
	s_addc_u32 s1, s65, 0
	s_add_i32 s13, s13, s96
	global_load_lds_dwordx4 v[232:233], off
	s_mov_b32 m0, s13
	v_lshl_add_u64 v[236:237], s[66:67], 0, v[186:187]
	global_load_lds_dwordx4 v170, s[0:1]
	s_add_i32 m0, s13, 0x2000
	s_nop 0
	global_load_lds_dwordx4 v188, s[0:1]
	v_lshl_add_u64 v[234:235], s[66:67], 0, v[184:185]
	s_nop 0
	s_waitcnt lgkmcnt(0)
	s_barrier
	s_setprio 1
	v_mfma_f32_16x16x32_bf16 v[88:91], v[48:51], v[148:151], 0
	v_mfma_f32_16x16x32_bf16 v[76:79], v[60:63], v[148:151], 0
	v_mfma_f32_16x16x32_bf16 v[28:31], v[48:51], v[194:197], 0
	v_mfma_f32_16x16x32_bf16 v[24:27], v[60:63], v[194:197], 0
	v_mfma_f32_16x16x32_bf16 v[12:15], v[48:51], v[202:205], 0
	v_mfma_f32_16x16x32_bf16 v[8:11], v[60:63], v[202:205], 0
	v_mfma_f32_16x16x32_bf16 v[4:7], v[48:51], v[210:213], 0
	v_mfma_f32_16x16x32_bf16 v[0:3], v[60:63], v[210:213], 0
	v_mfma_f32_16x16x32_bf16 v[88:91], v[52:55], v[164:167], v[88:91]
	v_mfma_f32_16x16x32_bf16 v[76:79], v[64:67], v[164:167], v[76:79]
	v_mfma_f32_16x16x32_bf16 v[28:31], v[52:55], v[198:201], v[28:31]
	v_mfma_f32_16x16x32_bf16 v[24:27], v[64:67], v[198:201], v[24:27]
	v_mfma_f32_16x16x32_bf16 v[12:15], v[52:55], v[206:209], v[12:15]
	v_mfma_f32_16x16x32_bf16 v[8:11], v[64:67], v[206:209], v[8:11]
	v_mfma_f32_16x16x32_bf16 v[4:7], v[52:55], v[214:217], v[4:7]
	v_mfma_f32_16x16x32_bf16 v[0:3], v[64:67], v[214:217], v[0:3]
	v_mfma_f32_16x16x32_bf16 v[20:23], v[72:75], v[194:197], 0
	v_mfma_f32_16x16x32_bf16 v[16:19], v[84:87], v[194:197], 0
	v_mfma_f32_16x16x32_bf16 v[44:47], v[72:75], v[202:205], 0
	v_mfma_f32_16x16x32_bf16 v[40:43], v[84:87], v[202:205], 0
	v_mfma_f32_16x16x32_bf16 v[36:39], v[72:75], v[210:213], 0
	v_mfma_f32_16x16x32_bf16 v[32:35], v[84:87], v[210:213], 0
	v_mfma_f32_16x16x32_bf16 v[48:51], v[72:75], v[148:151], 0
	v_mfma_f32_16x16x32_bf16 v[52:55], v[84:87], v[148:151], 0
	v_mfma_f32_16x16x32_bf16 v[20:23], v[80:83], v[198:201], v[20:23]
	v_mfma_f32_16x16x32_bf16 v[16:19], v[92:95], v[198:201], v[16:19]
	v_mfma_f32_16x16x32_bf16 v[44:47], v[80:83], v[206:209], v[44:47]
	v_mfma_f32_16x16x32_bf16 v[40:43], v[92:95], v[206:209], v[40:43]
	v_mfma_f32_16x16x32_bf16 v[36:39], v[80:83], v[214:217], v[36:39]
	v_mfma_f32_16x16x32_bf16 v[32:35], v[92:95], v[214:217], v[32:35]
	v_mfma_f32_16x16x32_bf16 v[48:51], v[80:83], v[164:167], v[48:51]
	v_mfma_f32_16x16x32_bf16 v[52:55], v[92:95], v[164:167], v[52:55]
	s_setprio 0
	s_barrier
	s_add_i32 s13, 0, 0x18000
	s_add_i32 s60, 0, 0x1c000
	v_add_u32_e32 v68, s13, v228
	v_add_u32_e32 v92, s60, v228
	ds_read_b128 v[56:59], v68
	ds_read_b128 v[60:63], v68 offset:1024
	ds_read_b128 v[64:67], v68 offset:2048
	ds_read_b128 v[68:71], v68 offset:3072
	ds_read_b128 v[72:75], v92
	ds_read_b128 v[80:83], v92 offset:1024
	ds_read_b128 v[84:87], v92 offset:2048
	ds_read_b128 v[92:95], v92 offset:3072
	s_add_u32 s0, s66, 0x40000
	s_addc_u32 s1, s67, 0
	s_mov_b32 m0, s39
	ds_read_b128 v[148:151], v230 offset:32768
	ds_read_b128 v[164:167], v230 offset:33792
	ds_read_b128 v[194:197], v230 offset:34816
	ds_read_b128 v[198:201], v230 offset:35840
	ds_read_b128 v[202:205], v230 offset:36864
	ds_read_b128 v[206:209], v230 offset:37888
	ds_read_b128 v[210:213], v230 offset:38912
	ds_read_b128 v[214:217], v230 offset:39936
	global_load_lds_dwordx4 v184, s[0:1]
	s_mov_b32 m0, s76
	s_nop 0
	global_load_lds_dwordx4 v186, s[0:1]
	s_mov_b32 m0, s59
	s_nop 0
	global_load_lds_dwordx4 v[234:235], off
	s_mov_b32 m0, s97
	s_nop 0
	global_load_lds_dwordx4 v[236:237], off
	s_waitcnt vmcnt(8)
	s_waitcnt lgkmcnt(0)
	s_barrier
	s_setprio 1
	v_mfma_f32_16x16x32_bf16 v[160:163], v[56:59], v[148:151], v[160:163]
	v_mfma_f32_16x16x32_bf16 v[156:159], v[64:67], v[148:151], v[156:159]
	v_mfma_f32_16x16x32_bf16 v[128:131], v[56:59], v[194:197], v[128:131]
	v_mfma_f32_16x16x32_bf16 v[124:127], v[64:67], v[194:197], v[124:127]
	v_mfma_f32_16x16x32_bf16 v[108:111], v[56:59], v[202:205], v[108:111]
	v_mfma_f32_16x16x32_bf16 v[104:107], v[64:67], v[202:205], v[104:107]
	v_mfma_f32_16x16x32_bf16 v[100:103], v[56:59], v[210:213], v[100:103]
	v_mfma_f32_16x16x32_bf16 v[96:99], v[64:67], v[210:213], v[96:99]
	v_mfma_f32_16x16x32_bf16 v[160:163], v[60:63], v[164:167], v[160:163]
	v_mfma_f32_16x16x32_bf16 v[156:159], v[68:71], v[164:167], v[156:159]
	v_mfma_f32_16x16x32_bf16 v[128:131], v[60:63], v[198:201], v[128:131]
	v_mfma_f32_16x16x32_bf16 v[124:127], v[68:71], v[198:201], v[124:127]
	v_mfma_f32_16x16x32_bf16 v[108:111], v[60:63], v[206:209], v[108:111]
	v_mfma_f32_16x16x32_bf16 v[104:107], v[68:71], v[206:209], v[104:107]
	v_mfma_f32_16x16x32_bf16 v[100:103], v[60:63], v[214:217], v[100:103]
	v_mfma_f32_16x16x32_bf16 v[96:99], v[68:71], v[214:217], v[96:99]
	v_mfma_f32_16x16x32_bf16 v[112:115], v[84:87], v[148:151], v[112:115]
	v_mfma_f32_16x16x32_bf16 v[152:155], v[72:75], v[148:151], v[152:155]
	v_mfma_f32_16x16x32_bf16 v[148:151], v[92:95], v[164:167], v[112:115]
	v_mfma_f32_16x16x32_bf16 v[112:115], v[72:75], v[194:197], v[120:123]
	v_mfma_f32_16x16x32_bf16 v[120:123], v[80:83], v[198:201], v[112:115]
	v_mfma_f32_16x16x32_bf16 v[112:115], v[84:87], v[194:197], v[116:119]
	v_mfma_f32_16x16x32_bf16 v[116:119], v[92:95], v[198:201], v[112:115]
	v_mfma_f32_16x16x32_bf16 v[112:115], v[72:75], v[202:205], v[144:147]
	v_mfma_f32_16x16x32_bf16 v[144:147], v[80:83], v[206:209], v[112:115]
	v_mfma_f32_16x16x32_bf16 v[112:115], v[84:87], v[202:205], v[140:143]
	v_mfma_f32_16x16x32_bf16 v[140:143], v[92:95], v[206:209], v[112:115]
	v_mfma_f32_16x16x32_bf16 v[112:115], v[72:75], v[210:213], v[136:139]
	v_mfma_f32_16x16x32_bf16 v[136:139], v[80:83], v[214:217], v[112:115]
	v_mfma_f32_16x16x32_bf16 v[112:115], v[84:87], v[210:213], v[132:135]
	v_mfma_f32_16x16x32_bf16 v[152:155], v[80:83], v[164:167], v[152:155]
	v_mfma_f32_16x16x32_bf16 v[132:135], v[92:95], v[214:217], v[112:115]
	s_setprio 0
	s_barrier
	s_add_i32 s0, s13, s96
	v_lshl_add_u64 v[218:219], v[218:219], 0, s[16:17]
	s_mov_b32 m0, s0
	s_nop 0
	ds_read_b128 v[112:115], v230 offset:49152
	ds_read_b128 v[164:167], v230 offset:50176
	ds_read_b128 v[194:197], v230 offset:51200
	ds_read_b128 v[198:201], v230 offset:52224
	ds_read_b128 v[202:205], v230 offset:53248
	ds_read_b128 v[206:209], v230 offset:54272
	ds_read_b128 v[210:213], v230 offset:55296
	ds_read_b128 v[214:217], v230 offset:56320
	global_load_lds_dwordx4 v[218:219], off
	s_add_i32 m0, s0, 0x2000
	s_add_u32 s0, s64, 0x40080
	v_lshl_add_u64 v[218:219], v[232:233], 0, s[16:17]
	s_addc_u32 s1, s65, 0
	s_add_i32 s13, s60, s96
	global_load_lds_dwordx4 v[218:219], off
	s_mov_b32 m0, s13
	s_nop 0
	global_load_lds_dwordx4 v170, s[0:1]
	s_add_i32 m0, s13, 0x2000
	s_nop 0
	global_load_lds_dwordx4 v188, s[0:1]
	v_lshl_add_u64 v[218:219], v[234:235], 0, s[16:17]
	s_mov_b32 m0, s75
	s_nop 0
	global_load_lds_dwordx4 v[218:219], off
	v_lshl_add_u64 v[218:219], v[236:237], 0, s[16:17]
	s_mov_b32 m0, s91
	s_nop 0
	global_load_lds_dwordx4 v[218:219], off
	s_waitcnt vmcnt(6)
	s_waitcnt lgkmcnt(0)
	s_barrier
	s_setprio 1
	v_mfma_f32_16x16x32_bf16 v[88:91], v[56:59], v[112:115], v[88:91]
	v_mfma_f32_16x16x32_bf16 v[76:79], v[64:67], v[112:115], v[76:79]
	v_mfma_f32_16x16x32_bf16 v[28:31], v[56:59], v[194:197], v[28:31]
	v_mfma_f32_16x16x32_bf16 v[24:27], v[64:67], v[194:197], v[24:27]
	v_mfma_f32_16x16x32_bf16 v[12:15], v[56:59], v[202:205], v[12:15]
	v_mfma_f32_16x16x32_bf16 v[8:11], v[64:67], v[202:205], v[8:11]
	v_mfma_f32_16x16x32_bf16 v[4:7], v[56:59], v[210:213], v[4:7]
	v_mfma_f32_16x16x32_bf16 v[0:3], v[64:67], v[210:213], v[0:3]
	v_mfma_f32_16x16x32_bf16 v[88:91], v[60:63], v[164:167], v[88:91]
	v_mfma_f32_16x16x32_bf16 v[76:79], v[68:71], v[164:167], v[76:79]
	v_mfma_f32_16x16x32_bf16 v[28:31], v[60:63], v[198:201], v[28:31]
	v_mfma_f32_16x16x32_bf16 v[24:27], v[68:71], v[198:201], v[24:27]
	v_mfma_f32_16x16x32_bf16 v[12:15], v[60:63], v[206:209], v[12:15]
	v_mfma_f32_16x16x32_bf16 v[8:11], v[68:71], v[206:209], v[8:11]
	v_mfma_f32_16x16x32_bf16 v[4:7], v[60:63], v[214:217], v[4:7]
	v_mfma_f32_16x16x32_bf16 v[0:3], v[68:71], v[214:217], v[0:3]
	v_mfma_f32_16x16x32_bf16 v[48:51], v[72:75], v[112:115], v[48:51]
	v_mfma_f32_16x16x32_bf16 v[68:71], v[80:83], v[164:167], v[48:51]
	v_mfma_f32_16x16x32_bf16 v[48:51], v[84:87], v[112:115], v[52:55]
	v_mfma_f32_16x16x32_bf16 v[20:23], v[72:75], v[194:197], v[20:23]
	v_mfma_f32_16x16x32_bf16 v[16:19], v[84:87], v[194:197], v[16:19]
	v_mfma_f32_16x16x32_bf16 v[44:47], v[72:75], v[202:205], v[44:47]
	v_mfma_f32_16x16x32_bf16 v[40:43], v[84:87], v[202:205], v[40:43]
	v_mfma_f32_16x16x32_bf16 v[36:39], v[72:75], v[210:213], v[36:39]
	v_mfma_f32_16x16x32_bf16 v[32:35], v[84:87], v[210:213], v[32:35]
	v_mfma_f32_16x16x32_bf16 v[56:59], v[92:95], v[164:167], v[48:51]
	v_mfma_f32_16x16x32_bf16 v[20:23], v[80:83], v[198:201], v[20:23]
	v_mfma_f32_16x16x32_bf16 v[16:19], v[92:95], v[198:201], v[16:19]
	v_mfma_f32_16x16x32_bf16 v[44:47], v[80:83], v[206:209], v[44:47]
	v_mfma_f32_16x16x32_bf16 v[40:43], v[92:95], v[206:209], v[40:43]
	v_mfma_f32_16x16x32_bf16 v[36:39], v[80:83], v[214:217], v[36:39]
	v_mfma_f32_16x16x32_bf16 v[32:35], v[92:95], v[214:217], v[32:35]
	s_setprio 0
	s_barrier
	s_add_i32 s12, s12, 2
	s_add_u32 vcc_lo, vcc_lo, 0x100
	s_addc_u32 vcc_hi, vcc_hi, 0
	s_cmp_gt_u32 s12, 13
	s_mov_b64 s[60:61], s[62:63]
.LBB0_863:
	s_add_u32 s62, s60, 0x100
	s_addc_u32 s63, s61, 0
	s_add_i32 s0, 0, 0x10000
	s_cmp_eq_u32 s12, 12
	s_cselect_b32 s67, s23, s63
	s_cselect_b32 s66, s51, s62
	s_cselect_b32 s65, s49, vcc_hi
	s_cselect_b32 s64, s57, vcc_lo
	s_add_i32 s13, 0, 0x14000
	v_add_u32_e32 v64, s0, v228
	v_add_u32_e32 v92, s13, v228
	ds_read_b128 v[48:51], v64
	ds_read_b128 v[52:55], v64 offset:1024
	ds_read_b128 v[60:63], v64 offset:2048
	ds_read_b128 v[64:67], v64 offset:3072
	ds_read_b128 v[72:75], v92
	ds_read_b128 v[80:83], v92 offset:1024
	ds_read_b128 v[84:87], v92 offset:2048
	ds_read_b128 v[92:95], v92 offset:3072
	s_add_i32 m0, s59, 0xc000
	ds_read_b128 v[112:115], v230
	ds_read_b128 v[164:167], v230 offset:1024
	ds_read_b128 v[194:197], v230 offset:2048
	ds_read_b128 v[198:201], v230 offset:3072
	ds_read_b128 v[202:205], v230 offset:4096
	ds_read_b128 v[206:209], v230 offset:5120
	ds_read_b128 v[210:213], v230 offset:6144
	ds_read_b128 v[214:217], v230 offset:7168
	global_load_lds_dwordx4 v190, s[60:61]
	s_add_i32 m0, s59, 0xe000
	s_nop 0
	global_load_lds_dwordx4 v192, s[60:61]
	s_waitcnt vmcnt(8)
	s_waitcnt lgkmcnt(0)
	s_barrier
	s_setprio 1
	v_mfma_f32_16x16x32_bf16 v[160:163], v[48:51], v[112:115], v[160:163]
	v_mfma_f32_16x16x32_bf16 v[156:159], v[60:63], v[112:115], v[156:159]
	v_mfma_f32_16x16x32_bf16 v[128:131], v[48:51], v[194:197], v[128:131]
	v_mfma_f32_16x16x32_bf16 v[124:127], v[60:63], v[194:197], v[124:127]
	v_mfma_f32_16x16x32_bf16 v[108:111], v[48:51], v[202:205], v[108:111]
	v_mfma_f32_16x16x32_bf16 v[104:107], v[60:63], v[202:205], v[104:107]
	v_mfma_f32_16x16x32_bf16 v[100:103], v[48:51], v[210:213], v[100:103]
	v_mfma_f32_16x16x32_bf16 v[96:99], v[60:63], v[210:213], v[96:99]
	v_mfma_f32_16x16x32_bf16 v[160:163], v[52:55], v[164:167], v[160:163]
	v_mfma_f32_16x16x32_bf16 v[156:159], v[64:67], v[164:167], v[156:159]
	v_mfma_f32_16x16x32_bf16 v[128:131], v[52:55], v[198:201], v[128:131]
	v_mfma_f32_16x16x32_bf16 v[124:127], v[64:67], v[198:201], v[124:127]
	v_mfma_f32_16x16x32_bf16 v[108:111], v[52:55], v[206:209], v[108:111]
	v_mfma_f32_16x16x32_bf16 v[104:107], v[64:67], v[206:209], v[104:107]
	v_mfma_f32_16x16x32_bf16 v[100:103], v[52:55], v[214:217], v[100:103]
	v_mfma_f32_16x16x32_bf16 v[96:99], v[64:67], v[214:217], v[96:99]
	v_mfma_f32_16x16x32_bf16 v[152:155], v[72:75], v[112:115], v[152:155]
	v_mfma_f32_16x16x32_bf16 v[120:123], v[72:75], v[194:197], v[120:123]
	v_mfma_f32_16x16x32_bf16 v[116:119], v[84:87], v[194:197], v[116:119]
	v_mfma_f32_16x16x32_bf16 v[144:147], v[72:75], v[202:205], v[144:147]
	v_mfma_f32_16x16x32_bf16 v[140:143], v[84:87], v[202:205], v[140:143]
	v_mfma_f32_16x16x32_bf16 v[136:139], v[72:75], v[210:213], v[136:139]
	v_mfma_f32_16x16x32_bf16 v[132:135], v[84:87], v[210:213], v[132:135]
	v_mfma_f32_16x16x32_bf16 v[152:155], v[80:83], v[164:167], v[152:155]
	v_mfma_f32_16x16x32_bf16 v[112:115], v[84:87], v[112:115], v[148:151]
	v_mfma_f32_16x16x32_bf16 v[120:123], v[80:83], v[198:201], v[120:123]
	v_mfma_f32_16x16x32_bf16 v[116:119], v[92:95], v[198:201], v[116:119]
	v_mfma_f32_16x16x32_bf16 v[144:147], v[80:83], v[206:209], v[144:147]
	v_mfma_f32_16x16x32_bf16 v[140:143], v[92:95], v[206:209], v[140:143]
	v_mfma_f32_16x16x32_bf16 v[136:139], v[80:83], v[214:217], v[136:139]
	v_mfma_f32_16x16x32_bf16 v[132:135], v[92:95], v[214:217], v[132:135]
	v_mfma_f32_16x16x32_bf16 v[112:115], v[92:95], v[164:167], v[112:115]
	s_setprio 0
	s_barrier
	s_add_i32 s0, s0, s96
	v_lshl_add_u64 v[218:219], s[64:65], 0, v[170:171]
	s_mov_b32 m0, s0
	ds_read_b128 v[148:151], v230 offset:16384
	ds_read_b128 v[164:167], v230 offset:17408
	ds_read_b128 v[194:197], v230 offset:18432
	ds_read_b128 v[198:201], v230 offset:19456
	ds_read_b128 v[202:205], v230 offset:20480
	ds_read_b128 v[206:209], v230 offset:21504
	ds_read_b128 v[210:213], v230 offset:22528
	ds_read_b128 v[214:217], v230 offset:23552
	global_load_lds_dwordx4 v[218:219], off
	s_add_i32 m0, s0, 0x2000
	s_add_u32 s0, s64, 0x40000
	v_lshl_add_u64 v[232:233], s[64:65], 0, v[188:189]
	s_addc_u32 s1, s65, 0
	s_add_i32 s13, s13, s96
	global_load_lds_dwordx4 v[232:233], off
	s_mov_b32 m0, s13
	v_lshl_add_u64 v[236:237], s[66:67], 0, v[186:187]
	global_load_lds_dwordx4 v170, s[0:1]
	s_add_i32 m0, s13, 0x2000
	s_nop 0
	global_load_lds_dwordx4 v188, s[0:1]
	v_lshl_add_u64 v[234:235], s[66:67], 0, v[184:185]
	s_waitcnt vmcnt(6)
	s_waitcnt lgkmcnt(0)
	s_barrier
	s_setprio 1
	v_mfma_f32_16x16x32_bf16 v[88:91], v[48:51], v[148:151], v[88:91]
	v_mfma_f32_16x16x32_bf16 v[76:79], v[60:63], v[148:151], v[76:79]
	v_mfma_f32_16x16x32_bf16 v[28:31], v[48:51], v[194:197], v[28:31]
	v_mfma_f32_16x16x32_bf16 v[24:27], v[60:63], v[194:197], v[24:27]
	v_mfma_f32_16x16x32_bf16 v[12:15], v[48:51], v[202:205], v[12:15]
	v_mfma_f32_16x16x32_bf16 v[8:11], v[60:63], v[202:205], v[8:11]
	v_mfma_f32_16x16x32_bf16 v[4:7], v[48:51], v[210:213], v[4:7]
	v_mfma_f32_16x16x32_bf16 v[0:3], v[60:63], v[210:213], v[0:3]
	v_mfma_f32_16x16x32_bf16 v[88:91], v[52:55], v[164:167], v[88:91]
	v_mfma_f32_16x16x32_bf16 v[76:79], v[64:67], v[164:167], v[76:79]
	v_mfma_f32_16x16x32_bf16 v[28:31], v[52:55], v[198:201], v[28:31]
	v_mfma_f32_16x16x32_bf16 v[24:27], v[64:67], v[198:201], v[24:27]
	v_mfma_f32_16x16x32_bf16 v[12:15], v[52:55], v[206:209], v[12:15]
	v_mfma_f32_16x16x32_bf16 v[8:11], v[64:67], v[206:209], v[8:11]
	v_mfma_f32_16x16x32_bf16 v[4:7], v[52:55], v[214:217], v[4:7]
	v_mfma_f32_16x16x32_bf16 v[0:3], v[64:67], v[214:217], v[0:3]
	v_mfma_f32_16x16x32_bf16 v[20:23], v[72:75], v[194:197], v[20:23]
	v_mfma_f32_16x16x32_bf16 v[16:19], v[84:87], v[194:197], v[16:19]
	v_mfma_f32_16x16x32_bf16 v[44:47], v[72:75], v[202:205], v[44:47]
	v_mfma_f32_16x16x32_bf16 v[40:43], v[84:87], v[202:205], v[40:43]
	v_mfma_f32_16x16x32_bf16 v[36:39], v[72:75], v[210:213], v[36:39]
	v_mfma_f32_16x16x32_bf16 v[32:35], v[84:87], v[210:213], v[32:35]
	v_mfma_f32_16x16x32_bf16 v[48:51], v[72:75], v[148:151], v[68:71]
	v_mfma_f32_16x16x32_bf16 v[52:55], v[84:87], v[148:151], v[56:59]
	v_mfma_f32_16x16x32_bf16 v[20:23], v[80:83], v[198:201], v[20:23]
	v_mfma_f32_16x16x32_bf16 v[16:19], v[92:95], v[198:201], v[16:19]
	v_mfma_f32_16x16x32_bf16 v[44:47], v[80:83], v[206:209], v[44:47]
	v_mfma_f32_16x16x32_bf16 v[40:43], v[92:95], v[206:209], v[40:43]
	v_mfma_f32_16x16x32_bf16 v[36:39], v[80:83], v[214:217], v[36:39]
	v_mfma_f32_16x16x32_bf16 v[32:35], v[92:95], v[214:217], v[32:35]
	v_mfma_f32_16x16x32_bf16 v[48:51], v[80:83], v[164:167], v[48:51]
	v_mfma_f32_16x16x32_bf16 v[52:55], v[92:95], v[164:167], v[52:55]
	s_setprio 0
	s_barrier
	s_add_i32 s13, 0, 0x18000
	s_add_i32 s60, 0, 0x1c000
	v_add_u32_e32 v68, s13, v228
	v_add_u32_e32 v92, s60, v228
	ds_read_b128 v[56:59], v68
	ds_read_b128 v[60:63], v68 offset:1024
	ds_read_b128 v[64:67], v68 offset:2048
	ds_read_b128 v[68:71], v68 offset:3072
	ds_read_b128 v[72:75], v92
	ds_read_b128 v[80:83], v92 offset:1024
	ds_read_b128 v[84:87], v92 offset:2048
	ds_read_b128 v[92:95], v92 offset:3072
	s_add_u32 s0, s66, 0x40000
	s_addc_u32 s1, s67, 0
	s_mov_b32 m0, s39
	ds_read_b128 v[148:151], v230 offset:32768
	ds_read_b128 v[164:167], v230 offset:33792
	ds_read_b128 v[194:197], v230 offset:34816
	ds_read_b128 v[198:201], v230 offset:35840
	ds_read_b128 v[202:205], v230 offset:36864
	ds_read_b128 v[206:209], v230 offset:37888
	ds_read_b128 v[210:213], v230 offset:38912
	ds_read_b128 v[214:217], v230 offset:39936
	global_load_lds_dwordx4 v184, s[0:1]
	s_mov_b32 m0, s76
	s_nop 0
	global_load_lds_dwordx4 v186, s[0:1]
	s_mov_b32 m0, s59
	s_nop 0
	global_load_lds_dwordx4 v[234:235], off
	s_mov_b32 m0, s97
	s_nop 0
	global_load_lds_dwordx4 v[236:237], off
	s_waitcnt vmcnt(8)
	s_waitcnt lgkmcnt(0)
	s_barrier
	s_setprio 1
	v_mfma_f32_16x16x32_bf16 v[160:163], v[56:59], v[148:151], v[160:163]
	v_mfma_f32_16x16x32_bf16 v[156:159], v[64:67], v[148:151], v[156:159]
	v_mfma_f32_16x16x32_bf16 v[128:131], v[56:59], v[194:197], v[128:131]
	v_mfma_f32_16x16x32_bf16 v[124:127], v[64:67], v[194:197], v[124:127]
	v_mfma_f32_16x16x32_bf16 v[108:111], v[56:59], v[202:205], v[108:111]
	v_mfma_f32_16x16x32_bf16 v[104:107], v[64:67], v[202:205], v[104:107]
	v_mfma_f32_16x16x32_bf16 v[100:103], v[56:59], v[210:213], v[100:103]
	v_mfma_f32_16x16x32_bf16 v[96:99], v[64:67], v[210:213], v[96:99]
	v_mfma_f32_16x16x32_bf16 v[160:163], v[60:63], v[164:167], v[160:163]
	v_mfma_f32_16x16x32_bf16 v[156:159], v[68:71], v[164:167], v[156:159]
	v_mfma_f32_16x16x32_bf16 v[128:131], v[60:63], v[198:201], v[128:131]
	v_mfma_f32_16x16x32_bf16 v[124:127], v[68:71], v[198:201], v[124:127]
	v_mfma_f32_16x16x32_bf16 v[108:111], v[60:63], v[206:209], v[108:111]
	v_mfma_f32_16x16x32_bf16 v[104:107], v[68:71], v[206:209], v[104:107]
	v_mfma_f32_16x16x32_bf16 v[100:103], v[60:63], v[214:217], v[100:103]
	v_mfma_f32_16x16x32_bf16 v[96:99], v[68:71], v[214:217], v[96:99]
	v_mfma_f32_16x16x32_bf16 v[112:115], v[84:87], v[148:151], v[112:115]
	v_mfma_f32_16x16x32_bf16 v[152:155], v[72:75], v[148:151], v[152:155]
	v_mfma_f32_16x16x32_bf16 v[148:151], v[92:95], v[164:167], v[112:115]
	v_mfma_f32_16x16x32_bf16 v[112:115], v[72:75], v[194:197], v[120:123]
	v_mfma_f32_16x16x32_bf16 v[120:123], v[80:83], v[198:201], v[112:115]
	v_mfma_f32_16x16x32_bf16 v[112:115], v[84:87], v[194:197], v[116:119]
	v_mfma_f32_16x16x32_bf16 v[116:119], v[92:95], v[198:201], v[112:115]
	v_mfma_f32_16x16x32_bf16 v[112:115], v[72:75], v[202:205], v[144:147]
	v_mfma_f32_16x16x32_bf16 v[144:147], v[80:83], v[206:209], v[112:115]
	v_mfma_f32_16x16x32_bf16 v[112:115], v[84:87], v[202:205], v[140:143]
	v_mfma_f32_16x16x32_bf16 v[140:143], v[92:95], v[206:209], v[112:115]
	v_mfma_f32_16x16x32_bf16 v[112:115], v[72:75], v[210:213], v[136:139]
	v_mfma_f32_16x16x32_bf16 v[136:139], v[80:83], v[214:217], v[112:115]
	v_mfma_f32_16x16x32_bf16 v[112:115], v[84:87], v[210:213], v[132:135]
	v_mfma_f32_16x16x32_bf16 v[152:155], v[80:83], v[164:167], v[152:155]
	v_mfma_f32_16x16x32_bf16 v[132:135], v[92:95], v[214:217], v[112:115]
	s_setprio 0
	s_barrier
	s_add_i32 s0, s13, s96
	v_lshl_add_u64 v[218:219], v[218:219], 0, s[16:17]
	s_mov_b32 m0, s0
	s_nop 0
	ds_read_b128 v[112:115], v230 offset:49152
	ds_read_b128 v[164:167], v230 offset:50176
	ds_read_b128 v[194:197], v230 offset:51200
	ds_read_b128 v[198:201], v230 offset:52224
	ds_read_b128 v[202:205], v230 offset:53248
	ds_read_b128 v[206:209], v230 offset:54272
	ds_read_b128 v[210:213], v230 offset:55296
	ds_read_b128 v[214:217], v230 offset:56320
	global_load_lds_dwordx4 v[218:219], off
	s_add_i32 m0, s0, 0x2000
	s_add_u32 s0, s64, 0x40080
	v_lshl_add_u64 v[218:219], v[232:233], 0, s[16:17]
	s_addc_u32 s1, s65, 0
	s_add_i32 s13, s60, s96
	global_load_lds_dwordx4 v[218:219], off
	s_mov_b32 m0, s13
	s_nop 0
	global_load_lds_dwordx4 v170, s[0:1]
	s_add_i32 m0, s13, 0x2000
	s_nop 0
	global_load_lds_dwordx4 v188, s[0:1]
	v_lshl_add_u64 v[218:219], v[234:235], 0, s[16:17]
	s_mov_b32 m0, s75
	s_nop 0
	global_load_lds_dwordx4 v[218:219], off
	v_lshl_add_u64 v[218:219], v[236:237], 0, s[16:17]
	s_mov_b32 m0, s91
	s_nop 0
	global_load_lds_dwordx4 v[218:219], off
	s_waitcnt vmcnt(6)
	s_waitcnt lgkmcnt(0)
	s_barrier
	s_setprio 1
	v_mfma_f32_16x16x32_bf16 v[88:91], v[56:59], v[112:115], v[88:91]
	v_mfma_f32_16x16x32_bf16 v[76:79], v[64:67], v[112:115], v[76:79]
	v_mfma_f32_16x16x32_bf16 v[28:31], v[56:59], v[194:197], v[28:31]
	v_mfma_f32_16x16x32_bf16 v[24:27], v[64:67], v[194:197], v[24:27]
	v_mfma_f32_16x16x32_bf16 v[12:15], v[56:59], v[202:205], v[12:15]
	v_mfma_f32_16x16x32_bf16 v[8:11], v[64:67], v[202:205], v[8:11]
	v_mfma_f32_16x16x32_bf16 v[4:7], v[56:59], v[210:213], v[4:7]
	v_mfma_f32_16x16x32_bf16 v[0:3], v[64:67], v[210:213], v[0:3]
	v_mfma_f32_16x16x32_bf16 v[88:91], v[60:63], v[164:167], v[88:91]
	v_mfma_f32_16x16x32_bf16 v[76:79], v[68:71], v[164:167], v[76:79]
	v_mfma_f32_16x16x32_bf16 v[28:31], v[60:63], v[198:201], v[28:31]
	v_mfma_f32_16x16x32_bf16 v[24:27], v[68:71], v[198:201], v[24:27]
	v_mfma_f32_16x16x32_bf16 v[12:15], v[60:63], v[206:209], v[12:15]
	v_mfma_f32_16x16x32_bf16 v[8:11], v[68:71], v[206:209], v[8:11]
	v_mfma_f32_16x16x32_bf16 v[4:7], v[60:63], v[214:217], v[4:7]
	v_mfma_f32_16x16x32_bf16 v[0:3], v[68:71], v[214:217], v[0:3]
	v_mfma_f32_16x16x32_bf16 v[48:51], v[72:75], v[112:115], v[48:51]
	v_mfma_f32_16x16x32_bf16 v[68:71], v[80:83], v[164:167], v[48:51]
	v_mfma_f32_16x16x32_bf16 v[48:51], v[84:87], v[112:115], v[52:55]
	v_mfma_f32_16x16x32_bf16 v[20:23], v[72:75], v[194:197], v[20:23]
	v_mfma_f32_16x16x32_bf16 v[16:19], v[84:87], v[194:197], v[16:19]
	v_mfma_f32_16x16x32_bf16 v[44:47], v[72:75], v[202:205], v[44:47]
	v_mfma_f32_16x16x32_bf16 v[40:43], v[84:87], v[202:205], v[40:43]
	v_mfma_f32_16x16x32_bf16 v[36:39], v[72:75], v[210:213], v[36:39]
	v_mfma_f32_16x16x32_bf16 v[32:35], v[84:87], v[210:213], v[32:35]
	v_mfma_f32_16x16x32_bf16 v[56:59], v[92:95], v[164:167], v[48:51]
	v_mfma_f32_16x16x32_bf16 v[20:23], v[80:83], v[198:201], v[20:23]
	v_mfma_f32_16x16x32_bf16 v[16:19], v[92:95], v[198:201], v[16:19]
	v_mfma_f32_16x16x32_bf16 v[44:47], v[80:83], v[206:209], v[44:47]
	v_mfma_f32_16x16x32_bf16 v[40:43], v[92:95], v[206:209], v[40:43]
	v_mfma_f32_16x16x32_bf16 v[36:39], v[80:83], v[214:217], v[36:39]
	v_mfma_f32_16x16x32_bf16 v[32:35], v[92:95], v[214:217], v[32:35]
	s_setprio 0
	s_barrier
	s_add_i32 s12, s12, 2
	s_add_u32 vcc_lo, vcc_lo, 0x100
	s_addc_u32 vcc_hi, vcc_hi, 0
	s_cmp_gt_u32 s12, 13
	s_mov_b64 s[60:61], s[62:63]
	s_cbranch_scc0 .LBB0_863
	s_and_b64 vcc, exec, s[42:43]
	s_cbranch_vccz .LBB0_866
	s_barrier

.Lrestag_1029:
	s_add_u32 s34, s30, 0x100
	s_addc_u32 s35, s31, 0
	s_add_i32 s0, 0, 0x10000
	s_cmp_eq_u32 s12, 40
	s_cselect_b32 s41, s7, s35
	s_cselect_b32 s40, s6, s34
	v_add_u32_e32 v150, s0, v153
	s_cselect_b32 s37, s27, s55
	s_cselect_b32 s36, s26, s54
	s_add_i32 s13, 0, 0x14000
	ds_read_b128 v[128:131], v150
	ds_read_b128 v[146:149], v150 offset:1024
	ds_read_b128 v[156:159], v150 offset:2048
	ds_read_b128 v[160:163], v150 offset:3072
	v_add_u32_e32 v150, s13, v153
	ds_read_b128 v[164:167], v150
	ds_read_b128 v[184:187], v150 offset:1024
	ds_read_b128 v[188:191], v150 offset:2048
	ds_read_b128 v[192:195], v150 offset:3072
	s_add_i32 m0, s43, 0xc000
	ds_read_b128 v[196:199], v154
	ds_read_b128 v[200:203], v154 offset:1024
	ds_read_b128 v[204:207], v154 offset:2048
	ds_read_b128 v[208:211], v154 offset:3072
	ds_read_b128 v[212:215], v154 offset:4096
	ds_read_b128 v[216:219], v154 offset:5120
	ds_read_b128 v[228:231], v154 offset:6144
	ds_read_b128 v[232:235], v154 offset:7168
	global_load_lds_dwordx4 v142, s[30:31]
	s_add_i32 m0, s43, 0xe000
	s_nop 0
	global_load_lds_dwordx4 v144, s[30:31]
	s_nop 0
	s_waitcnt lgkmcnt(0)
	s_barrier
	s_setprio 1
	v_mfma_f32_16x16x32_bf16 v[124:127], v[128:131], v[196:199], 0
	v_mfma_f32_16x16x32_bf16 v[120:123], v[156:159], v[196:199], 0
	v_mfma_f32_16x16x32_bf16 v[112:115], v[128:131], v[204:207], 0
	v_mfma_f32_16x16x32_bf16 v[104:107], v[156:159], v[204:207], 0
	v_mfma_f32_16x16x32_bf16 v[96:99], v[128:131], v[212:215], 0
	v_mfma_f32_16x16x32_bf16 v[88:91], v[156:159], v[212:215], 0
	v_mfma_f32_16x16x32_bf16 v[80:83], v[128:131], v[228:231], 0
	v_mfma_f32_16x16x32_bf16 v[72:75], v[156:159], v[228:231], 0
	v_mfma_f32_16x16x32_bf16 v[124:127], v[146:149], v[200:203], v[124:127]
	v_mfma_f32_16x16x32_bf16 v[120:123], v[160:163], v[200:203], v[120:123]
	v_mfma_f32_16x16x32_bf16 v[112:115], v[146:149], v[208:211], v[112:115]
	v_mfma_f32_16x16x32_bf16 v[104:107], v[160:163], v[208:211], v[104:107]
	v_mfma_f32_16x16x32_bf16 v[96:99], v[146:149], v[216:219], v[96:99]
	v_mfma_f32_16x16x32_bf16 v[88:91], v[160:163], v[216:219], v[88:91]
	v_mfma_f32_16x16x32_bf16 v[80:83], v[146:149], v[232:235], v[80:83]
	v_mfma_f32_16x16x32_bf16 v[72:75], v[160:163], v[232:235], v[72:75]
	v_mfma_f32_16x16x32_bf16 v[116:119], v[164:167], v[196:199], 0
	v_mfma_f32_16x16x32_bf16 v[108:111], v[188:191], v[196:199], 0
	v_mfma_f32_16x16x32_bf16 v[100:103], v[164:167], v[204:207], 0
	v_mfma_f32_16x16x32_bf16 v[92:95], v[188:191], v[204:207], 0
	v_mfma_f32_16x16x32_bf16 v[84:87], v[164:167], v[212:215], 0
	v_mfma_f32_16x16x32_bf16 v[76:79], v[188:191], v[212:215], 0
	v_mfma_f32_16x16x32_bf16 v[68:71], v[164:167], v[228:231], 0
	v_mfma_f32_16x16x32_bf16 v[64:67], v[188:191], v[228:231], 0
	v_mfma_f32_16x16x32_bf16 v[116:119], v[184:187], v[200:203], v[116:119]
	v_mfma_f32_16x16x32_bf16 v[108:111], v[192:195], v[200:203], v[108:111]
	v_mfma_f32_16x16x32_bf16 v[100:103], v[184:187], v[208:211], v[100:103]
	v_mfma_f32_16x16x32_bf16 v[92:95], v[192:195], v[208:211], v[92:95]
	v_mfma_f32_16x16x32_bf16 v[84:87], v[184:187], v[216:219], v[84:87]
	v_mfma_f32_16x16x32_bf16 v[76:79], v[192:195], v[216:219], v[76:79]
	v_mfma_f32_16x16x32_bf16 v[68:71], v[184:187], v[232:235], v[68:71]
	v_mfma_f32_16x16x32_bf16 v[64:67], v[192:195], v[232:235], v[64:67]
	s_setprio 0
	s_barrier
	s_add_i32 s0, s0, s42
	v_lshl_add_u64 v[150:151], s[36:37], 0, v[170:171]
	s_mov_b32 m0, s0
	ds_read_b128 v[196:199], v154 offset:16384
	ds_read_b128 v[200:203], v154 offset:17408
	ds_read_b128 v[204:207], v154 offset:18432
	ds_read_b128 v[208:211], v154 offset:19456
	ds_read_b128 v[212:215], v154 offset:20480
	ds_read_b128 v[216:219], v154 offset:21504
	ds_read_b128 v[228:231], v154 offset:22528
	ds_read_b128 v[232:235], v154 offset:23552
	global_load_lds_dwordx4 v[150:151], off
	s_add_i32 m0, s0, 0x2000
	s_add_u32 s0, s36, 0xb0000
	v_lshl_add_u64 v[236:237], s[36:37], 0, v[136:137]
	s_addc_u32 s1, s37, 0
	s_add_i32 s13, s13, s42
	global_load_lds_dwordx4 v[236:237], off
	s_mov_b32 m0, s13
	v_lshl_add_u64 v[240:241], s[40:41], 0, v[134:135]
	global_load_lds_dwordx4 v170, s[0:1]
	s_add_i32 m0, s13, 0x2000
	s_nop 0
	global_load_lds_dwordx4 v136, s[0:1]
	v_lshl_add_u64 v[238:239], s[40:41], 0, v[132:133]
	s_nop 0
	s_waitcnt lgkmcnt(0)
	s_barrier
	s_setprio 1
	v_mfma_f32_16x16x32_bf16 v[60:63], v[128:131], v[196:199], 0
	v_mfma_f32_16x16x32_bf16 v[56:59], v[156:159], v[196:199], 0
	v_mfma_f32_16x16x32_bf16 v[48:51], v[128:131], v[204:207], 0
	v_mfma_f32_16x16x32_bf16 v[40:43], v[156:159], v[204:207], 0
	v_mfma_f32_16x16x32_bf16 v[32:35], v[128:131], v[212:215], 0
	v_mfma_f32_16x16x32_bf16 v[24:27], v[156:159], v[212:215], 0
	v_mfma_f32_16x16x32_bf16 v[16:19], v[128:131], v[228:231], 0
	v_mfma_f32_16x16x32_bf16 v[8:11], v[156:159], v[228:231], 0
	v_mfma_f32_16x16x32_bf16 v[60:63], v[146:149], v[200:203], v[60:63]
	v_mfma_f32_16x16x32_bf16 v[56:59], v[160:163], v[200:203], v[56:59]
	v_mfma_f32_16x16x32_bf16 v[48:51], v[146:149], v[208:211], v[48:51]
	v_mfma_f32_16x16x32_bf16 v[40:43], v[160:163], v[208:211], v[40:43]
	v_mfma_f32_16x16x32_bf16 v[32:35], v[146:149], v[216:219], v[32:35]
	v_mfma_f32_16x16x32_bf16 v[24:27], v[160:163], v[216:219], v[24:27]
	v_mfma_f32_16x16x32_bf16 v[16:19], v[146:149], v[232:235], v[16:19]
	v_mfma_f32_16x16x32_bf16 v[8:11], v[160:163], v[232:235], v[8:11]
	v_mfma_f32_16x16x32_bf16 v[52:55], v[164:167], v[196:199], 0
	v_mfma_f32_16x16x32_bf16 v[44:47], v[188:191], v[196:199], 0
	v_mfma_f32_16x16x32_bf16 v[36:39], v[164:167], v[204:207], 0
	v_mfma_f32_16x16x32_bf16 v[28:31], v[188:191], v[204:207], 0
	v_mfma_f32_16x16x32_bf16 v[20:23], v[164:167], v[212:215], 0
	v_mfma_f32_16x16x32_bf16 v[12:15], v[188:191], v[212:215], 0
	v_mfma_f32_16x16x32_bf16 v[4:7], v[164:167], v[228:231], 0
	v_mfma_f32_16x16x32_bf16 v[0:3], v[188:191], v[228:231], 0
	v_mfma_f32_16x16x32_bf16 v[52:55], v[184:187], v[200:203], v[52:55]
	v_mfma_f32_16x16x32_bf16 v[44:47], v[192:195], v[200:203], v[44:47]
	v_mfma_f32_16x16x32_bf16 v[36:39], v[184:187], v[208:211], v[36:39]
	v_mfma_f32_16x16x32_bf16 v[28:31], v[192:195], v[208:211], v[28:31]
	v_mfma_f32_16x16x32_bf16 v[20:23], v[184:187], v[216:219], v[20:23]
	v_mfma_f32_16x16x32_bf16 v[12:15], v[192:195], v[216:219], v[12:15]
	v_mfma_f32_16x16x32_bf16 v[4:7], v[184:187], v[232:235], v[4:7]
	v_mfma_f32_16x16x32_bf16 v[0:3], v[192:195], v[232:235], v[0:3]
	s_setprio 0
	s_barrier
	s_add_i32 s13, 0, 0x18000
	v_add_u32_e32 v155, s13, v153
	s_add_i32 s30, 0, 0x1c000
	ds_read_b128 v[128:131], v155
	ds_read_b128 v[146:149], v155 offset:1024
	ds_read_b128 v[156:159], v155 offset:2048
	ds_read_b128 v[160:163], v155 offset:3072
	v_add_u32_e32 v155, s30, v153
	ds_read_b128 v[164:167], v155
	ds_read_b128 v[184:187], v155 offset:1024
	ds_read_b128 v[188:191], v155 offset:2048
	ds_read_b128 v[192:195], v155 offset:3072
	s_add_u32 s0, s40, 0xb0000
	s_addc_u32 s1, s41, 0
	s_mov_b32 m0, s45
	ds_read_b128 v[196:199], v154 offset:32768
	ds_read_b128 v[200:203], v154 offset:33792
	ds_read_b128 v[204:207], v154 offset:34816
	ds_read_b128 v[208:211], v154 offset:35840
	ds_read_b128 v[212:215], v154 offset:36864
	ds_read_b128 v[216:219], v154 offset:37888
	ds_read_b128 v[228:231], v154 offset:38912
	ds_read_b128 v[232:235], v154 offset:39936
	global_load_lds_dwordx4 v132, s[0:1]
	s_mov_b32 m0, s46
	s_nop 0
	global_load_lds_dwordx4 v134, s[0:1]
	s_mov_b32 m0, s43
	s_nop 0
	global_load_lds_dwordx4 v[238:239], off
	s_mov_b32 m0, s44
	s_nop 0
	global_load_lds_dwordx4 v[240:241], off
	s_waitcnt vmcnt(8)
	s_waitcnt lgkmcnt(0)
	s_barrier
	s_setprio 1
	v_mfma_f32_16x16x32_bf16 v[124:127], v[128:131], v[196:199], v[124:127]
	v_mfma_f32_16x16x32_bf16 v[120:123], v[156:159], v[196:199], v[120:123]
	v_mfma_f32_16x16x32_bf16 v[112:115], v[128:131], v[204:207], v[112:115]
	v_mfma_f32_16x16x32_bf16 v[104:107], v[156:159], v[204:207], v[104:107]
	v_mfma_f32_16x16x32_bf16 v[96:99], v[128:131], v[212:215], v[96:99]
	v_mfma_f32_16x16x32_bf16 v[88:91], v[156:159], v[212:215], v[88:91]
	v_mfma_f32_16x16x32_bf16 v[80:83], v[128:131], v[228:231], v[80:83]
	v_mfma_f32_16x16x32_bf16 v[72:75], v[156:159], v[228:231], v[72:75]
	v_mfma_f32_16x16x32_bf16 v[124:127], v[146:149], v[200:203], v[124:127]
	v_mfma_f32_16x16x32_bf16 v[120:123], v[160:163], v[200:203], v[120:123]
	v_mfma_f32_16x16x32_bf16 v[112:115], v[146:149], v[208:211], v[112:115]
	v_mfma_f32_16x16x32_bf16 v[104:107], v[160:163], v[208:211], v[104:107]
	v_mfma_f32_16x16x32_bf16 v[96:99], v[146:149], v[216:219], v[96:99]
	v_mfma_f32_16x16x32_bf16 v[88:91], v[160:163], v[216:219], v[88:91]
	v_mfma_f32_16x16x32_bf16 v[80:83], v[146:149], v[232:235], v[80:83]
	v_mfma_f32_16x16x32_bf16 v[72:75], v[160:163], v[232:235], v[72:75]
	v_mfma_f32_16x16x32_bf16 v[116:119], v[164:167], v[196:199], v[116:119]
	v_mfma_f32_16x16x32_bf16 v[108:111], v[188:191], v[196:199], v[108:111]
	v_mfma_f32_16x16x32_bf16 v[100:103], v[164:167], v[204:207], v[100:103]
	v_mfma_f32_16x16x32_bf16 v[92:95], v[188:191], v[204:207], v[92:95]
	v_mfma_f32_16x16x32_bf16 v[84:87], v[164:167], v[212:215], v[84:87]
	v_mfma_f32_16x16x32_bf16 v[76:79], v[188:191], v[212:215], v[76:79]
	v_mfma_f32_16x16x32_bf16 v[68:71], v[164:167], v[228:231], v[68:71]
	v_mfma_f32_16x16x32_bf16 v[64:67], v[188:191], v[228:231], v[64:67]
	v_mfma_f32_16x16x32_bf16 v[116:119], v[184:187], v[200:203], v[116:119]
	v_mfma_f32_16x16x32_bf16 v[108:111], v[192:195], v[200:203], v[108:111]
	v_mfma_f32_16x16x32_bf16 v[100:103], v[184:187], v[208:211], v[100:103]
	v_mfma_f32_16x16x32_bf16 v[92:95], v[192:195], v[208:211], v[92:95]
	v_mfma_f32_16x16x32_bf16 v[84:87], v[184:187], v[216:219], v[84:87]
	v_mfma_f32_16x16x32_bf16 v[76:79], v[192:195], v[216:219], v[76:79]
	v_mfma_f32_16x16x32_bf16 v[68:71], v[184:187], v[232:235], v[68:71]
	v_mfma_f32_16x16x32_bf16 v[64:67], v[192:195], v[232:235], v[64:67]
	s_setprio 0
	s_barrier
	s_add_i32 s0, s13, s42
	v_lshl_add_u64 v[150:151], v[150:151], 0, s[16:17]
	s_mov_b32 m0, s0
	ds_read_b128 v[196:199], v154 offset:49152
	ds_read_b128 v[200:203], v154 offset:50176
	ds_read_b128 v[204:207], v154 offset:51200
	ds_read_b128 v[208:211], v154 offset:52224
	ds_read_b128 v[212:215], v154 offset:53248
	ds_read_b128 v[216:219], v154 offset:54272
	ds_read_b128 v[228:231], v154 offset:55296
	ds_read_b128 v[232:235], v154 offset:56320
	global_load_lds_dwordx4 v[150:151], off
	s_add_i32 m0, s0, 0x2000
	s_add_u32 s0, s36, 0xb0080
	v_lshl_add_u64 v[150:151], v[236:237], 0, s[16:17]
	s_addc_u32 s1, s37, 0
	s_add_i32 s13, s30, s42
	global_load_lds_dwordx4 v[150:151], off
	s_mov_b32 m0, s13
	s_nop 0
	global_load_lds_dwordx4 v170, s[0:1]
	s_add_i32 m0, s13, 0x2000
	s_nop 0
	global_load_lds_dwordx4 v136, s[0:1]
	v_lshl_add_u64 v[150:151], v[238:239], 0, s[16:17]
	s_mov_b32 m0, s47
	s_nop 0
	global_load_lds_dwordx4 v[150:151], off
	v_lshl_add_u64 v[150:151], v[240:241], 0, s[16:17]
	s_mov_b32 m0, s48
	s_nop 0
	global_load_lds_dwordx4 v[150:151], off
	s_waitcnt vmcnt(6)
	s_waitcnt lgkmcnt(0)
	s_barrier
	s_setprio 1
	v_mfma_f32_16x16x32_bf16 v[60:63], v[128:131], v[196:199], v[60:63]
	v_mfma_f32_16x16x32_bf16 v[56:59], v[156:159], v[196:199], v[56:59]
	v_mfma_f32_16x16x32_bf16 v[48:51], v[128:131], v[204:207], v[48:51]
	v_mfma_f32_16x16x32_bf16 v[40:43], v[156:159], v[204:207], v[40:43]
	v_mfma_f32_16x16x32_bf16 v[32:35], v[128:131], v[212:215], v[32:35]
	v_mfma_f32_16x16x32_bf16 v[24:27], v[156:159], v[212:215], v[24:27]
	v_mfma_f32_16x16x32_bf16 v[16:19], v[128:131], v[228:231], v[16:19]
	v_mfma_f32_16x16x32_bf16 v[8:11], v[156:159], v[228:231], v[8:11]
	v_mfma_f32_16x16x32_bf16 v[60:63], v[146:149], v[200:203], v[60:63]
	v_mfma_f32_16x16x32_bf16 v[56:59], v[160:163], v[200:203], v[56:59]
	v_mfma_f32_16x16x32_bf16 v[48:51], v[146:149], v[208:211], v[48:51]
	v_mfma_f32_16x16x32_bf16 v[40:43], v[160:163], v[208:211], v[40:43]
	v_mfma_f32_16x16x32_bf16 v[32:35], v[146:149], v[216:219], v[32:35]
	v_mfma_f32_16x16x32_bf16 v[24:27], v[160:163], v[216:219], v[24:27]
	v_mfma_f32_16x16x32_bf16 v[16:19], v[146:149], v[232:235], v[16:19]
	v_mfma_f32_16x16x32_bf16 v[8:11], v[160:163], v[232:235], v[8:11]
	v_mfma_f32_16x16x32_bf16 v[52:55], v[164:167], v[196:199], v[52:55]
	v_mfma_f32_16x16x32_bf16 v[44:47], v[188:191], v[196:199], v[44:47]
	v_mfma_f32_16x16x32_bf16 v[36:39], v[164:167], v[204:207], v[36:39]
	v_mfma_f32_16x16x32_bf16 v[28:31], v[188:191], v[204:207], v[28:31]
	v_mfma_f32_16x16x32_bf16 v[20:23], v[164:167], v[212:215], v[20:23]
	v_mfma_f32_16x16x32_bf16 v[12:15], v[188:191], v[212:215], v[12:15]
	v_mfma_f32_16x16x32_bf16 v[4:7], v[164:167], v[228:231], v[4:7]
	v_mfma_f32_16x16x32_bf16 v[0:3], v[188:191], v[228:231], v[0:3]
	v_mfma_f32_16x16x32_bf16 v[52:55], v[184:187], v[200:203], v[52:55]
	v_mfma_f32_16x16x32_bf16 v[44:47], v[192:195], v[200:203], v[44:47]
	v_mfma_f32_16x16x32_bf16 v[36:39], v[184:187], v[208:211], v[36:39]
	v_mfma_f32_16x16x32_bf16 v[28:31], v[192:195], v[208:211], v[28:31]
	v_mfma_f32_16x16x32_bf16 v[20:23], v[184:187], v[216:219], v[20:23]
	v_mfma_f32_16x16x32_bf16 v[12:15], v[192:195], v[216:219], v[12:15]
	v_mfma_f32_16x16x32_bf16 v[4:7], v[184:187], v[232:235], v[4:7]
	v_mfma_f32_16x16x32_bf16 v[0:3], v[192:195], v[232:235], v[0:3]
	s_setprio 0
	s_barrier
	s_add_i32 s12, s12, 2
	s_add_u32 s54, s54, 0x100
	s_addc_u32 s55, s55, 0
	s_cmp_gt_u32 s12, 41
	s_mov_b64 s[30:31], s[34:35]
.LBB0_1029:
	s_add_u32 s34, s30, 0x100
	s_addc_u32 s35, s31, 0
	s_add_i32 s0, 0, 0x10000
	s_cmp_eq_u32 s12, 40
	s_cselect_b32 s41, s7, s35
	s_cselect_b32 s40, s6, s34
	v_add_u32_e32 v150, s0, v153
	s_cselect_b32 s37, s27, s55
	s_cselect_b32 s36, s26, s54
	s_add_i32 s13, 0, 0x14000
	ds_read_b128 v[128:131], v150
	ds_read_b128 v[146:149], v150 offset:1024
	ds_read_b128 v[156:159], v150 offset:2048
	ds_read_b128 v[160:163], v150 offset:3072
	v_add_u32_e32 v150, s13, v153
	ds_read_b128 v[164:167], v150
	ds_read_b128 v[184:187], v150 offset:1024
	ds_read_b128 v[188:191], v150 offset:2048
	ds_read_b128 v[192:195], v150 offset:3072
	s_add_i32 m0, s43, 0xc000
	ds_read_b128 v[196:199], v154
	ds_read_b128 v[200:203], v154 offset:1024
	ds_read_b128 v[204:207], v154 offset:2048
	ds_read_b128 v[208:211], v154 offset:3072
	ds_read_b128 v[212:215], v154 offset:4096
	ds_read_b128 v[216:219], v154 offset:5120
	ds_read_b128 v[228:231], v154 offset:6144
	ds_read_b128 v[232:235], v154 offset:7168
	global_load_lds_dwordx4 v142, s[30:31]
	s_add_i32 m0, s43, 0xe000
	s_nop 0
	global_load_lds_dwordx4 v144, s[30:31]
	s_waitcnt vmcnt(8)
	s_waitcnt lgkmcnt(0)
	s_barrier
	s_setprio 1
	v_mfma_f32_16x16x32_bf16 v[124:127], v[128:131], v[196:199], v[124:127]
	v_mfma_f32_16x16x32_bf16 v[120:123], v[156:159], v[196:199], v[120:123]
	v_mfma_f32_16x16x32_bf16 v[112:115], v[128:131], v[204:207], v[112:115]
	v_mfma_f32_16x16x32_bf16 v[104:107], v[156:159], v[204:207], v[104:107]
	v_mfma_f32_16x16x32_bf16 v[96:99], v[128:131], v[212:215], v[96:99]
	v_mfma_f32_16x16x32_bf16 v[88:91], v[156:159], v[212:215], v[88:91]
	v_mfma_f32_16x16x32_bf16 v[80:83], v[128:131], v[228:231], v[80:83]
	v_mfma_f32_16x16x32_bf16 v[72:75], v[156:159], v[228:231], v[72:75]
	v_mfma_f32_16x16x32_bf16 v[124:127], v[146:149], v[200:203], v[124:127]
	v_mfma_f32_16x16x32_bf16 v[120:123], v[160:163], v[200:203], v[120:123]
	v_mfma_f32_16x16x32_bf16 v[112:115], v[146:149], v[208:211], v[112:115]
	v_mfma_f32_16x16x32_bf16 v[104:107], v[160:163], v[208:211], v[104:107]
	v_mfma_f32_16x16x32_bf16 v[96:99], v[146:149], v[216:219], v[96:99]
	v_mfma_f32_16x16x32_bf16 v[88:91], v[160:163], v[216:219], v[88:91]
	v_mfma_f32_16x16x32_bf16 v[80:83], v[146:149], v[232:235], v[80:83]
	v_mfma_f32_16x16x32_bf16 v[72:75], v[160:163], v[232:235], v[72:75]
	v_mfma_f32_16x16x32_bf16 v[116:119], v[164:167], v[196:199], v[116:119]
	v_mfma_f32_16x16x32_bf16 v[108:111], v[188:191], v[196:199], v[108:111]
	v_mfma_f32_16x16x32_bf16 v[100:103], v[164:167], v[204:207], v[100:103]
	v_mfma_f32_16x16x32_bf16 v[92:95], v[188:191], v[204:207], v[92:95]
	v_mfma_f32_16x16x32_bf16 v[84:87], v[164:167], v[212:215], v[84:87]
	v_mfma_f32_16x16x32_bf16 v[76:79], v[188:191], v[212:215], v[76:79]
	v_mfma_f32_16x16x32_bf16 v[68:71], v[164:167], v[228:231], v[68:71]
	v_mfma_f32_16x16x32_bf16 v[64:67], v[188:191], v[228:231], v[64:67]
	v_mfma_f32_16x16x32_bf16 v[116:119], v[184:187], v[200:203], v[116:119]
	v_mfma_f32_16x16x32_bf16 v[108:111], v[192:195], v[200:203], v[108:111]
	v_mfma_f32_16x16x32_bf16 v[100:103], v[184:187], v[208:211], v[100:103]
	v_mfma_f32_16x16x32_bf16 v[92:95], v[192:195], v[208:211], v[92:95]
	v_mfma_f32_16x16x32_bf16 v[84:87], v[184:187], v[216:219], v[84:87]
	v_mfma_f32_16x16x32_bf16 v[76:79], v[192:195], v[216:219], v[76:79]
	v_mfma_f32_16x16x32_bf16 v[68:71], v[184:187], v[232:235], v[68:71]
	v_mfma_f32_16x16x32_bf16 v[64:67], v[192:195], v[232:235], v[64:67]
	s_setprio 0
	s_barrier
	s_add_i32 s0, s0, s42
	v_lshl_add_u64 v[150:151], s[36:37], 0, v[170:171]
	s_mov_b32 m0, s0
	ds_read_b128 v[196:199], v154 offset:16384
	ds_read_b128 v[200:203], v154 offset:17408
	ds_read_b128 v[204:207], v154 offset:18432
	ds_read_b128 v[208:211], v154 offset:19456
	ds_read_b128 v[212:215], v154 offset:20480
	ds_read_b128 v[216:219], v154 offset:21504
	ds_read_b128 v[228:231], v154 offset:22528
	ds_read_b128 v[232:235], v154 offset:23552
	global_load_lds_dwordx4 v[150:151], off
	s_add_i32 m0, s0, 0x2000
	s_add_u32 s0, s36, 0xb0000
	v_lshl_add_u64 v[236:237], s[36:37], 0, v[136:137]
	s_addc_u32 s1, s37, 0
	s_add_i32 s13, s13, s42
	global_load_lds_dwordx4 v[236:237], off
	s_mov_b32 m0, s13
	v_lshl_add_u64 v[240:241], s[40:41], 0, v[134:135]
	global_load_lds_dwordx4 v170, s[0:1]
	s_add_i32 m0, s13, 0x2000
	s_nop 0
	global_load_lds_dwordx4 v136, s[0:1]
	v_lshl_add_u64 v[238:239], s[40:41], 0, v[132:133]
	s_waitcnt vmcnt(6)
	s_waitcnt lgkmcnt(0)
	s_barrier
	s_setprio 1
	v_mfma_f32_16x16x32_bf16 v[60:63], v[128:131], v[196:199], v[60:63]
	v_mfma_f32_16x16x32_bf16 v[56:59], v[156:159], v[196:199], v[56:59]
	v_mfma_f32_16x16x32_bf16 v[48:51], v[128:131], v[204:207], v[48:51]
	v_mfma_f32_16x16x32_bf16 v[40:43], v[156:159], v[204:207], v[40:43]
	v_mfma_f32_16x16x32_bf16 v[32:35], v[128:131], v[212:215], v[32:35]
	v_mfma_f32_16x16x32_bf16 v[24:27], v[156:159], v[212:215], v[24:27]
	v_mfma_f32_16x16x32_bf16 v[16:19], v[128:131], v[228:231], v[16:19]
	v_mfma_f32_16x16x32_bf16 v[8:11], v[156:159], v[228:231], v[8:11]
	v_mfma_f32_16x16x32_bf16 v[60:63], v[146:149], v[200:203], v[60:63]
	v_mfma_f32_16x16x32_bf16 v[56:59], v[160:163], v[200:203], v[56:59]
	v_mfma_f32_16x16x32_bf16 v[48:51], v[146:149], v[208:211], v[48:51]
	v_mfma_f32_16x16x32_bf16 v[40:43], v[160:163], v[208:211], v[40:43]
	v_mfma_f32_16x16x32_bf16 v[32:35], v[146:149], v[216:219], v[32:35]
	v_mfma_f32_16x16x32_bf16 v[24:27], v[160:163], v[216:219], v[24:27]
	v_mfma_f32_16x16x32_bf16 v[16:19], v[146:149], v[232:235], v[16:19]
	v_mfma_f32_16x16x32_bf16 v[8:11], v[160:163], v[232:235], v[8:11]
	v_mfma_f32_16x16x32_bf16 v[52:55], v[164:167], v[196:199], v[52:55]
	v_mfma_f32_16x16x32_bf16 v[44:47], v[188:191], v[196:199], v[44:47]
	v_mfma_f32_16x16x32_bf16 v[36:39], v[164:167], v[204:207], v[36:39]
	v_mfma_f32_16x16x32_bf16 v[28:31], v[188:191], v[204:207], v[28:31]
	v_mfma_f32_16x16x32_bf16 v[20:23], v[164:167], v[212:215], v[20:23]
	v_mfma_f32_16x16x32_bf16 v[12:15], v[188:191], v[212:215], v[12:15]
	v_mfma_f32_16x16x32_bf16 v[4:7], v[164:167], v[228:231], v[4:7]
	v_mfma_f32_16x16x32_bf16 v[0:3], v[188:191], v[228:231], v[0:3]
	v_mfma_f32_16x16x32_bf16 v[52:55], v[184:187], v[200:203], v[52:55]
	v_mfma_f32_16x16x32_bf16 v[44:47], v[192:195], v[200:203], v[44:47]
	v_mfma_f32_16x16x32_bf16 v[36:39], v[184:187], v[208:211], v[36:39]
	v_mfma_f32_16x16x32_bf16 v[28:31], v[192:195], v[208:211], v[28:31]
	v_mfma_f32_16x16x32_bf16 v[20:23], v[184:187], v[216:219], v[20:23]
	v_mfma_f32_16x16x32_bf16 v[12:15], v[192:195], v[216:219], v[12:15]
	v_mfma_f32_16x16x32_bf16 v[4:7], v[184:187], v[232:235], v[4:7]
	v_mfma_f32_16x16x32_bf16 v[0:3], v[192:195], v[232:235], v[0:3]
	s_setprio 0
	s_barrier
	s_add_i32 s13, 0, 0x18000
	v_add_u32_e32 v155, s13, v153
	s_add_i32 s30, 0, 0x1c000
	ds_read_b128 v[128:131], v155
	ds_read_b128 v[146:149], v155 offset:1024
	ds_read_b128 v[156:159], v155 offset:2048
	ds_read_b128 v[160:163], v155 offset:3072
	v_add_u32_e32 v155, s30, v153
	ds_read_b128 v[164:167], v155
	ds_read_b128 v[184:187], v155 offset:1024
	ds_read_b128 v[188:191], v155 offset:2048
	ds_read_b128 v[192:195], v155 offset:3072
	s_add_u32 s0, s40, 0xb0000
	s_addc_u32 s1, s41, 0
	s_mov_b32 m0, s45
	ds_read_b128 v[196:199], v154 offset:32768
	ds_read_b128 v[200:203], v154 offset:33792
	ds_read_b128 v[204:207], v154 offset:34816
	ds_read_b128 v[208:211], v154 offset:35840
	ds_read_b128 v[212:215], v154 offset:36864
	ds_read_b128 v[216:219], v154 offset:37888
	ds_read_b128 v[228:231], v154 offset:38912
	ds_read_b128 v[232:235], v154 offset:39936
	global_load_lds_dwordx4 v132, s[0:1]
	s_mov_b32 m0, s46
	s_nop 0
	global_load_lds_dwordx4 v134, s[0:1]
	s_mov_b32 m0, s43
	s_nop 0
	global_load_lds_dwordx4 v[238:239], off
	s_mov_b32 m0, s44
	s_nop 0
	global_load_lds_dwordx4 v[240:241], off
	s_waitcnt vmcnt(8)
	s_waitcnt lgkmcnt(0)
	s_barrier
	s_setprio 1
	v_mfma_f32_16x16x32_bf16 v[124:127], v[128:131], v[196:199], v[124:127]
	v_mfma_f32_16x16x32_bf16 v[120:123], v[156:159], v[196:199], v[120:123]
	v_mfma_f32_16x16x32_bf16 v[112:115], v[128:131], v[204:207], v[112:115]
	v_mfma_f32_16x16x32_bf16 v[104:107], v[156:159], v[204:207], v[104:107]
	v_mfma_f32_16x16x32_bf16 v[96:99], v[128:131], v[212:215], v[96:99]
	v_mfma_f32_16x16x32_bf16 v[88:91], v[156:159], v[212:215], v[88:91]
	v_mfma_f32_16x16x32_bf16 v[80:83], v[128:131], v[228:231], v[80:83]
	v_mfma_f32_16x16x32_bf16 v[72:75], v[156:159], v[228:231], v[72:75]
	v_mfma_f32_16x16x32_bf16 v[124:127], v[146:149], v[200:203], v[124:127]
	v_mfma_f32_16x16x32_bf16 v[120:123], v[160:163], v[200:203], v[120:123]
	v_mfma_f32_16x16x32_bf16 v[112:115], v[146:149], v[208:211], v[112:115]
	v_mfma_f32_16x16x32_bf16 v[104:107], v[160:163], v[208:211], v[104:107]
	v_mfma_f32_16x16x32_bf16 v[96:99], v[146:149], v[216:219], v[96:99]
	v_mfma_f32_16x16x32_bf16 v[88:91], v[160:163], v[216:219], v[88:91]
	v_mfma_f32_16x16x32_bf16 v[80:83], v[146:149], v[232:235], v[80:83]
	v_mfma_f32_16x16x32_bf16 v[72:75], v[160:163], v[232:235], v[72:75]
	v_mfma_f32_16x16x32_bf16 v[116:119], v[164:167], v[196:199], v[116:119]
	v_mfma_f32_16x16x32_bf16 v[108:111], v[188:191], v[196:199], v[108:111]
	v_mfma_f32_16x16x32_bf16 v[100:103], v[164:167], v[204:207], v[100:103]
	v_mfma_f32_16x16x32_bf16 v[92:95], v[188:191], v[204:207], v[92:95]
	v_mfma_f32_16x16x32_bf16 v[84:87], v[164:167], v[212:215], v[84:87]
	v_mfma_f32_16x16x32_bf16 v[76:79], v[188:191], v[212:215], v[76:79]
	v_mfma_f32_16x16x32_bf16 v[68:71], v[164:167], v[228:231], v[68:71]
	v_mfma_f32_16x16x32_bf16 v[64:67], v[188:191], v[228:231], v[64:67]
	v_mfma_f32_16x16x32_bf16 v[116:119], v[184:187], v[200:203], v[116:119]
	v_mfma_f32_16x16x32_bf16 v[108:111], v[192:195], v[200:203], v[108:111]
	v_mfma_f32_16x16x32_bf16 v[100:103], v[184:187], v[208:211], v[100:103]
	v_mfma_f32_16x16x32_bf16 v[92:95], v[192:195], v[208:211], v[92:95]
	v_mfma_f32_16x16x32_bf16 v[84:87], v[184:187], v[216:219], v[84:87]
	v_mfma_f32_16x16x32_bf16 v[76:79], v[192:195], v[216:219], v[76:79]
	v_mfma_f32_16x16x32_bf16 v[68:71], v[184:187], v[232:235], v[68:71]
	v_mfma_f32_16x16x32_bf16 v[64:67], v[192:195], v[232:235], v[64:67]
	s_setprio 0
	s_barrier
	s_add_i32 s0, s13, s42
	v_lshl_add_u64 v[150:151], v[150:151], 0, s[16:17]
	s_mov_b32 m0, s0
	ds_read_b128 v[196:199], v154 offset:49152
	ds_read_b128 v[200:203], v154 offset:50176
	ds_read_b128 v[204:207], v154 offset:51200
	ds_read_b128 v[208:211], v154 offset:52224
	ds_read_b128 v[212:215], v154 offset:53248
	ds_read_b128 v[216:219], v154 offset:54272
	ds_read_b128 v[228:231], v154 offset:55296
	ds_read_b128 v[232:235], v154 offset:56320
	global_load_lds_dwordx4 v[150:151], off
	s_add_i32 m0, s0, 0x2000
	s_add_u32 s0, s36, 0xb0080
	v_lshl_add_u64 v[150:151], v[236:237], 0, s[16:17]
	s_addc_u32 s1, s37, 0
	s_add_i32 s13, s30, s42
	global_load_lds_dwordx4 v[150:151], off
	s_mov_b32 m0, s13
	s_nop 0
	global_load_lds_dwordx4 v170, s[0:1]
	s_add_i32 m0, s13, 0x2000
	s_nop 0
	global_load_lds_dwordx4 v136, s[0:1]
	v_lshl_add_u64 v[150:151], v[238:239], 0, s[16:17]
	s_mov_b32 m0, s47
	s_nop 0
	global_load_lds_dwordx4 v[150:151], off
	v_lshl_add_u64 v[150:151], v[240:241], 0, s[16:17]
	s_mov_b32 m0, s48
	s_nop 0
	global_load_lds_dwordx4 v[150:151], off
	s_waitcnt vmcnt(6)
	s_waitcnt lgkmcnt(0)
	s_barrier
	s_setprio 1
	v_mfma_f32_16x16x32_bf16 v[60:63], v[128:131], v[196:199], v[60:63]
	v_mfma_f32_16x16x32_bf16 v[56:59], v[156:159], v[196:199], v[56:59]
	v_mfma_f32_16x16x32_bf16 v[48:51], v[128:131], v[204:207], v[48:51]
	v_mfma_f32_16x16x32_bf16 v[40:43], v[156:159], v[204:207], v[40:43]
	v_mfma_f32_16x16x32_bf16 v[32:35], v[128:131], v[212:215], v[32:35]
	v_mfma_f32_16x16x32_bf16 v[24:27], v[156:159], v[212:215], v[24:27]
	v_mfma_f32_16x16x32_bf16 v[16:19], v[128:131], v[228:231], v[16:19]
	v_mfma_f32_16x16x32_bf16 v[8:11], v[156:159], v[228:231], v[8:11]
	v_mfma_f32_16x16x32_bf16 v[60:63], v[146:149], v[200:203], v[60:63]
	v_mfma_f32_16x16x32_bf16 v[56:59], v[160:163], v[200:203], v[56:59]
	v_mfma_f32_16x16x32_bf16 v[48:51], v[146:149], v[208:211], v[48:51]
	v_mfma_f32_16x16x32_bf16 v[40:43], v[160:163], v[208:211], v[40:43]
	v_mfma_f32_16x16x32_bf16 v[32:35], v[146:149], v[216:219], v[32:35]
	v_mfma_f32_16x16x32_bf16 v[24:27], v[160:163], v[216:219], v[24:27]
	v_mfma_f32_16x16x32_bf16 v[16:19], v[146:149], v[232:235], v[16:19]
	v_mfma_f32_16x16x32_bf16 v[8:11], v[160:163], v[232:235], v[8:11]
	v_mfma_f32_16x16x32_bf16 v[52:55], v[164:167], v[196:199], v[52:55]
	v_mfma_f32_16x16x32_bf16 v[44:47], v[188:191], v[196:199], v[44:47]
	v_mfma_f32_16x16x32_bf16 v[36:39], v[164:167], v[204:207], v[36:39]
	v_mfma_f32_16x16x32_bf16 v[28:31], v[188:191], v[204:207], v[28:31]
	v_mfma_f32_16x16x32_bf16 v[20:23], v[164:167], v[212:215], v[20:23]
	v_mfma_f32_16x16x32_bf16 v[12:15], v[188:191], v[212:215], v[12:15]
	v_mfma_f32_16x16x32_bf16 v[4:7], v[164:167], v[228:231], v[4:7]
	v_mfma_f32_16x16x32_bf16 v[0:3], v[188:191], v[228:231], v[0:3]
	v_mfma_f32_16x16x32_bf16 v[52:55], v[184:187], v[200:203], v[52:55]
	v_mfma_f32_16x16x32_bf16 v[44:47], v[192:195], v[200:203], v[44:47]
	v_mfma_f32_16x16x32_bf16 v[36:39], v[184:187], v[208:211], v[36:39]
	v_mfma_f32_16x16x32_bf16 v[28:31], v[192:195], v[208:211], v[28:31]
	v_mfma_f32_16x16x32_bf16 v[20:23], v[184:187], v[216:219], v[20:23]
	v_mfma_f32_16x16x32_bf16 v[12:15], v[192:195], v[216:219], v[12:15]
	v_mfma_f32_16x16x32_bf16 v[4:7], v[184:187], v[232:235], v[4:7]
	v_mfma_f32_16x16x32_bf16 v[0:3], v[192:195], v[232:235], v[0:3]
	s_setprio 0
	s_barrier
	s_add_i32 s12, s12, 2
	s_add_u32 s54, s54, 0x100
	s_addc_u32 s55, s55, 0
	s_cmp_gt_u32 s12, 41
	s_mov_b64 s[30:31], s[34:35]
	s_cbranch_scc0 .LBB0_1029
	s_and_b64 vcc, exec, s[24:25]
	s_cbranch_vccz .LBB0_1032
	s_barrier

.Lrestag_1061:
	s_add_u32 s40, s36, 0x100
	s_addc_u32 s41, s37, 0
	s_add_i32 s0, 0, 0x10000
	s_cmp_eq_u32 s12, 40
	s_cselect_b32 s45, s9, s41
	s_cselect_b32 s44, s8, s40
	s_cselect_b32 s43, s35, s59
	s_cselect_b32 s42, s34, s58
	s_add_i32 s13, 0, 0x14000
	v_add_u32_e32 v140, s0, v197
	v_add_u32_e32 v184, s13, v197
	ds_read_b128 v[128:131], v140
	ds_read_b128 v[132:135], v140 offset:1024
	ds_read_b128 v[136:139], v140 offset:2048
	ds_read_b128 v[140:143], v140 offset:3072
	ds_read_b128 v[144:147], v184
	ds_read_b128 v[148:151], v184 offset:1024
	ds_read_b128 v[164:167], v184 offset:2048
	ds_read_b128 v[184:187], v184 offset:3072
	s_add_i32 m0, s47, 0xc000
	ds_read_b128 v[188:191], v198
	ds_read_b128 v[192:195], v198 offset:1024
	ds_read_b128 v[200:203], v198 offset:2048
	ds_read_b128 v[204:207], v198 offset:3072
	ds_read_b128 v[208:211], v198 offset:4096
	ds_read_b128 v[212:215], v198 offset:5120
	ds_read_b128 v[216:219], v198 offset:6144
	ds_read_b128 v[228:231], v198 offset:7168
	global_load_lds_dwordx4 v160, s[36:37]
	s_add_i32 m0, s47, 0xe000
	s_nop 0
	global_load_lds_dwordx4 v162, s[36:37]
	s_nop 0
	s_waitcnt lgkmcnt(0)
	s_barrier
	s_setprio 1
	v_mfma_f32_16x16x32_bf16 v[124:127], v[128:131], v[188:191], 0
	v_mfma_f32_16x16x32_bf16 v[120:123], v[136:139], v[188:191], 0
	v_mfma_f32_16x16x32_bf16 v[108:111], v[128:131], v[200:203], 0
	v_mfma_f32_16x16x32_bf16 v[104:107], v[136:139], v[200:203], 0
	v_mfma_f32_16x16x32_bf16 v[92:95], v[128:131], v[208:211], 0
	v_mfma_f32_16x16x32_bf16 v[88:91], v[136:139], v[208:211], 0
	v_mfma_f32_16x16x32_bf16 v[76:79], v[128:131], v[216:219], 0
	v_mfma_f32_16x16x32_bf16 v[72:75], v[136:139], v[216:219], 0
	v_mfma_f32_16x16x32_bf16 v[124:127], v[132:135], v[192:195], v[124:127]
	v_mfma_f32_16x16x32_bf16 v[120:123], v[140:143], v[192:195], v[120:123]
	v_mfma_f32_16x16x32_bf16 v[108:111], v[132:135], v[204:207], v[108:111]
	v_mfma_f32_16x16x32_bf16 v[104:107], v[140:143], v[204:207], v[104:107]
	v_mfma_f32_16x16x32_bf16 v[92:95], v[132:135], v[212:215], v[92:95]
	v_mfma_f32_16x16x32_bf16 v[88:91], v[140:143], v[212:215], v[88:91]
	v_mfma_f32_16x16x32_bf16 v[76:79], v[132:135], v[228:231], v[76:79]
	v_mfma_f32_16x16x32_bf16 v[72:75], v[140:143], v[228:231], v[72:75]
	v_mfma_f32_16x16x32_bf16 v[116:119], v[144:147], v[188:191], 0
	v_mfma_f32_16x16x32_bf16 v[112:115], v[164:167], v[188:191], 0
	v_mfma_f32_16x16x32_bf16 v[100:103], v[144:147], v[200:203], 0
	v_mfma_f32_16x16x32_bf16 v[96:99], v[164:167], v[200:203], 0
	v_mfma_f32_16x16x32_bf16 v[84:87], v[144:147], v[208:211], 0
	v_mfma_f32_16x16x32_bf16 v[80:83], v[164:167], v[208:211], 0
	v_mfma_f32_16x16x32_bf16 v[68:71], v[144:147], v[216:219], 0
	v_mfma_f32_16x16x32_bf16 v[64:67], v[164:167], v[216:219], 0
	v_mfma_f32_16x16x32_bf16 v[116:119], v[148:151], v[192:195], v[116:119]
	v_mfma_f32_16x16x32_bf16 v[112:115], v[184:187], v[192:195], v[112:115]
	v_mfma_f32_16x16x32_bf16 v[100:103], v[148:151], v[204:207], v[100:103]
	v_mfma_f32_16x16x32_bf16 v[96:99], v[184:187], v[204:207], v[96:99]
	v_mfma_f32_16x16x32_bf16 v[84:87], v[148:151], v[212:215], v[84:87]
	v_mfma_f32_16x16x32_bf16 v[80:83], v[184:187], v[212:215], v[80:83]
	v_mfma_f32_16x16x32_bf16 v[68:71], v[148:151], v[228:231], v[68:71]
	v_mfma_f32_16x16x32_bf16 v[64:67], v[184:187], v[228:231], v[64:67]
	s_setprio 0
	s_barrier
	s_add_i32 s0, s0, s46
	v_lshl_add_u64 v[232:233], s[42:43], 0, v[170:171]
	s_mov_b32 m0, s0
	ds_read_b128 v[188:191], v198 offset:16384
	ds_read_b128 v[192:195], v198 offset:17408
	ds_read_b128 v[200:203], v198 offset:18432
	ds_read_b128 v[204:207], v198 offset:19456
	ds_read_b128 v[208:211], v198 offset:20480
	ds_read_b128 v[212:215], v198 offset:21504
	ds_read_b128 v[216:219], v198 offset:22528
	ds_read_b128 v[228:231], v198 offset:23552
	global_load_lds_dwordx4 v[232:233], off
	s_add_i32 m0, s0, 0x2000
	s_add_u32 s0, s42, 0xb0000
	v_lshl_add_u64 v[234:235], s[42:43], 0, v[156:157]
	s_addc_u32 s1, s43, 0
	s_add_i32 s13, s13, s46
	global_load_lds_dwordx4 v[234:235], off
	s_mov_b32 m0, s13
	v_lshl_add_u64 v[238:239], s[44:45], 0, v[154:155]
	global_load_lds_dwordx4 v170, s[0:1]
	s_add_i32 m0, s13, 0x2000
	s_nop 0
	global_load_lds_dwordx4 v156, s[0:1]
	v_lshl_add_u64 v[236:237], s[44:45], 0, v[152:153]
	s_nop 0
	s_waitcnt lgkmcnt(0)
	s_barrier
	s_setprio 1
	v_mfma_f32_16x16x32_bf16 v[60:63], v[128:131], v[188:191], 0
	v_mfma_f32_16x16x32_bf16 v[56:59], v[136:139], v[188:191], 0
	v_mfma_f32_16x16x32_bf16 v[44:47], v[128:131], v[200:203], 0
	v_mfma_f32_16x16x32_bf16 v[40:43], v[136:139], v[200:203], 0
	v_mfma_f32_16x16x32_bf16 v[28:31], v[128:131], v[208:211], 0
	v_mfma_f32_16x16x32_bf16 v[24:27], v[136:139], v[208:211], 0
	v_mfma_f32_16x16x32_bf16 v[12:15], v[128:131], v[216:219], 0
	v_mfma_f32_16x16x32_bf16 v[8:11], v[136:139], v[216:219], 0
	v_mfma_f32_16x16x32_bf16 v[60:63], v[132:135], v[192:195], v[60:63]
	v_mfma_f32_16x16x32_bf16 v[56:59], v[140:143], v[192:195], v[56:59]
	v_mfma_f32_16x16x32_bf16 v[44:47], v[132:135], v[204:207], v[44:47]
	v_mfma_f32_16x16x32_bf16 v[40:43], v[140:143], v[204:207], v[40:43]
	v_mfma_f32_16x16x32_bf16 v[28:31], v[132:135], v[212:215], v[28:31]
	v_mfma_f32_16x16x32_bf16 v[24:27], v[140:143], v[212:215], v[24:27]
	v_mfma_f32_16x16x32_bf16 v[12:15], v[132:135], v[228:231], v[12:15]
	v_mfma_f32_16x16x32_bf16 v[8:11], v[140:143], v[228:231], v[8:11]
	v_mfma_f32_16x16x32_bf16 v[52:55], v[144:147], v[188:191], 0
	v_mfma_f32_16x16x32_bf16 v[48:51], v[164:167], v[188:191], 0
	v_mfma_f32_16x16x32_bf16 v[36:39], v[144:147], v[200:203], 0
	v_mfma_f32_16x16x32_bf16 v[32:35], v[164:167], v[200:203], 0
	v_mfma_f32_16x16x32_bf16 v[20:23], v[144:147], v[208:211], 0
	v_mfma_f32_16x16x32_bf16 v[16:19], v[164:167], v[208:211], 0
	v_mfma_f32_16x16x32_bf16 v[4:7], v[144:147], v[216:219], 0
	v_mfma_f32_16x16x32_bf16 v[0:3], v[164:167], v[216:219], 0
	v_mfma_f32_16x16x32_bf16 v[52:55], v[148:151], v[192:195], v[52:55]
	v_mfma_f32_16x16x32_bf16 v[48:51], v[184:187], v[192:195], v[48:51]
	v_mfma_f32_16x16x32_bf16 v[36:39], v[148:151], v[204:207], v[36:39]
	v_mfma_f32_16x16x32_bf16 v[32:35], v[184:187], v[204:207], v[32:35]
	v_mfma_f32_16x16x32_bf16 v[20:23], v[148:151], v[212:215], v[20:23]
	v_mfma_f32_16x16x32_bf16 v[16:19], v[184:187], v[212:215], v[16:19]
	v_mfma_f32_16x16x32_bf16 v[4:7], v[148:151], v[228:231], v[4:7]
	v_mfma_f32_16x16x32_bf16 v[0:3], v[184:187], v[228:231], v[0:3]
	s_setprio 0
	s_barrier
	s_add_i32 s13, 0, 0x18000
	s_add_i32 s36, 0, 0x1c000
	v_add_u32_e32 v140, s13, v197
	v_add_u32_e32 v184, s36, v197
	ds_read_b128 v[128:131], v140
	ds_read_b128 v[132:135], v140 offset:1024
	ds_read_b128 v[136:139], v140 offset:2048
	ds_read_b128 v[140:143], v140 offset:3072
	ds_read_b128 v[144:147], v184
	ds_read_b128 v[148:151], v184 offset:1024
	ds_read_b128 v[164:167], v184 offset:2048
	ds_read_b128 v[184:187], v184 offset:3072
	s_add_u32 s0, s44, 0xb0000
	s_addc_u32 s1, s45, 0
	s_mov_b32 m0, s49
	ds_read_b128 v[188:191], v198 offset:32768
	ds_read_b128 v[192:195], v198 offset:33792
	ds_read_b128 v[200:203], v198 offset:34816
	ds_read_b128 v[204:207], v198 offset:35840
	ds_read_b128 v[208:211], v198 offset:36864
	ds_read_b128 v[212:215], v198 offset:37888
	ds_read_b128 v[216:219], v198 offset:38912
	ds_read_b128 v[228:231], v198 offset:39936
	global_load_lds_dwordx4 v152, s[0:1]
	s_mov_b32 m0, s50
	s_nop 0
	global_load_lds_dwordx4 v154, s[0:1]
	s_mov_b32 m0, s47
	s_nop 0
	global_load_lds_dwordx4 v[236:237], off
	s_mov_b32 m0, s48
	s_nop 0
	global_load_lds_dwordx4 v[238:239], off
	s_waitcnt vmcnt(8)
	s_waitcnt lgkmcnt(0)
	s_barrier
	s_setprio 1
	v_mfma_f32_16x16x32_bf16 v[124:127], v[128:131], v[188:191], v[124:127]
	v_mfma_f32_16x16x32_bf16 v[120:123], v[136:139], v[188:191], v[120:123]
	v_mfma_f32_16x16x32_bf16 v[108:111], v[128:131], v[200:203], v[108:111]
	v_mfma_f32_16x16x32_bf16 v[104:107], v[136:139], v[200:203], v[104:107]
	v_mfma_f32_16x16x32_bf16 v[92:95], v[128:131], v[208:211], v[92:95]
	v_mfma_f32_16x16x32_bf16 v[88:91], v[136:139], v[208:211], v[88:91]
	v_mfma_f32_16x16x32_bf16 v[76:79], v[128:131], v[216:219], v[76:79]
	v_mfma_f32_16x16x32_bf16 v[72:75], v[136:139], v[216:219], v[72:75]
	v_mfma_f32_16x16x32_bf16 v[124:127], v[132:135], v[192:195], v[124:127]
	v_mfma_f32_16x16x32_bf16 v[120:123], v[140:143], v[192:195], v[120:123]
	v_mfma_f32_16x16x32_bf16 v[108:111], v[132:135], v[204:207], v[108:111]
	v_mfma_f32_16x16x32_bf16 v[104:107], v[140:143], v[204:207], v[104:107]
	v_mfma_f32_16x16x32_bf16 v[92:95], v[132:135], v[212:215], v[92:95]
	v_mfma_f32_16x16x32_bf16 v[88:91], v[140:143], v[212:215], v[88:91]
	v_mfma_f32_16x16x32_bf16 v[76:79], v[132:135], v[228:231], v[76:79]
	v_mfma_f32_16x16x32_bf16 v[72:75], v[140:143], v[228:231], v[72:75]
	v_mfma_f32_16x16x32_bf16 v[116:119], v[144:147], v[188:191], v[116:119]
	v_mfma_f32_16x16x32_bf16 v[112:115], v[164:167], v[188:191], v[112:115]
	v_mfma_f32_16x16x32_bf16 v[100:103], v[144:147], v[200:203], v[100:103]
	v_mfma_f32_16x16x32_bf16 v[96:99], v[164:167], v[200:203], v[96:99]
	v_mfma_f32_16x16x32_bf16 v[84:87], v[144:147], v[208:211], v[84:87]
	v_mfma_f32_16x16x32_bf16 v[80:83], v[164:167], v[208:211], v[80:83]
	v_mfma_f32_16x16x32_bf16 v[68:71], v[144:147], v[216:219], v[68:71]
	v_mfma_f32_16x16x32_bf16 v[64:67], v[164:167], v[216:219], v[64:67]
	v_mfma_f32_16x16x32_bf16 v[116:119], v[148:151], v[192:195], v[116:119]
	v_mfma_f32_16x16x32_bf16 v[112:115], v[184:187], v[192:195], v[112:115]
	v_mfma_f32_16x16x32_bf16 v[100:103], v[148:151], v[204:207], v[100:103]
	v_mfma_f32_16x16x32_bf16 v[96:99], v[184:187], v[204:207], v[96:99]
	v_mfma_f32_16x16x32_bf16 v[84:87], v[148:151], v[212:215], v[84:87]
	v_mfma_f32_16x16x32_bf16 v[80:83], v[184:187], v[212:215], v[80:83]
	v_mfma_f32_16x16x32_bf16 v[68:71], v[148:151], v[228:231], v[68:71]
	v_mfma_f32_16x16x32_bf16 v[64:67], v[184:187], v[228:231], v[64:67]
	s_setprio 0
	s_barrier
	s_add_i32 s0, s13, s46
	v_lshl_add_u64 v[232:233], v[232:233], 0, s[16:17]
	s_mov_b32 m0, s0
	ds_read_b128 v[188:191], v198 offset:49152
	ds_read_b128 v[192:195], v198 offset:50176
	ds_read_b128 v[200:203], v198 offset:51200
	ds_read_b128 v[204:207], v198 offset:52224
	ds_read_b128 v[208:211], v198 offset:53248
	ds_read_b128 v[212:215], v198 offset:54272
	ds_read_b128 v[216:219], v198 offset:55296
	ds_read_b128 v[228:231], v198 offset:56320
	global_load_lds_dwordx4 v[232:233], off
	s_add_i32 m0, s0, 0x2000
	s_add_u32 s0, s42, 0xb0080
	v_lshl_add_u64 v[232:233], v[234:235], 0, s[16:17]
	s_addc_u32 s1, s43, 0
	s_add_i32 s13, s36, s46
	global_load_lds_dwordx4 v[232:233], off
	s_mov_b32 m0, s13
	s_nop 0
	global_load_lds_dwordx4 v170, s[0:1]
	s_add_i32 m0, s13, 0x2000
	s_nop 0
	global_load_lds_dwordx4 v156, s[0:1]
	v_lshl_add_u64 v[232:233], v[236:237], 0, s[16:17]
	s_mov_b32 m0, s51
	s_nop 0
	global_load_lds_dwordx4 v[232:233], off
	v_lshl_add_u64 v[232:233], v[238:239], 0, s[16:17]
	s_mov_b32 m0, s52
	s_nop 0
	global_load_lds_dwordx4 v[232:233], off
	s_waitcnt vmcnt(6)
	s_waitcnt lgkmcnt(0)
	s_barrier
	s_setprio 1
	v_mfma_f32_16x16x32_bf16 v[60:63], v[128:131], v[188:191], v[60:63]
	v_mfma_f32_16x16x32_bf16 v[56:59], v[136:139], v[188:191], v[56:59]
	v_mfma_f32_16x16x32_bf16 v[44:47], v[128:131], v[200:203], v[44:47]
	v_mfma_f32_16x16x32_bf16 v[40:43], v[136:139], v[200:203], v[40:43]
	v_mfma_f32_16x16x32_bf16 v[28:31], v[128:131], v[208:211], v[28:31]
	v_mfma_f32_16x16x32_bf16 v[24:27], v[136:139], v[208:211], v[24:27]
	v_mfma_f32_16x16x32_bf16 v[12:15], v[128:131], v[216:219], v[12:15]
	v_mfma_f32_16x16x32_bf16 v[8:11], v[136:139], v[216:219], v[8:11]
	v_mfma_f32_16x16x32_bf16 v[60:63], v[132:135], v[192:195], v[60:63]
	v_mfma_f32_16x16x32_bf16 v[56:59], v[140:143], v[192:195], v[56:59]
	v_mfma_f32_16x16x32_bf16 v[44:47], v[132:135], v[204:207], v[44:47]
	v_mfma_f32_16x16x32_bf16 v[40:43], v[140:143], v[204:207], v[40:43]
	v_mfma_f32_16x16x32_bf16 v[28:31], v[132:135], v[212:215], v[28:31]
	v_mfma_f32_16x16x32_bf16 v[24:27], v[140:143], v[212:215], v[24:27]
	v_mfma_f32_16x16x32_bf16 v[12:15], v[132:135], v[228:231], v[12:15]
	v_mfma_f32_16x16x32_bf16 v[8:11], v[140:143], v[228:231], v[8:11]
	v_mfma_f32_16x16x32_bf16 v[52:55], v[144:147], v[188:191], v[52:55]
	v_mfma_f32_16x16x32_bf16 v[48:51], v[164:167], v[188:191], v[48:51]
	v_mfma_f32_16x16x32_bf16 v[36:39], v[144:147], v[200:203], v[36:39]
	v_mfma_f32_16x16x32_bf16 v[32:35], v[164:167], v[200:203], v[32:35]
	v_mfma_f32_16x16x32_bf16 v[20:23], v[144:147], v[208:211], v[20:23]
	v_mfma_f32_16x16x32_bf16 v[16:19], v[164:167], v[208:211], v[16:19]
	v_mfma_f32_16x16x32_bf16 v[4:7], v[144:147], v[216:219], v[4:7]
	v_mfma_f32_16x16x32_bf16 v[0:3], v[164:167], v[216:219], v[0:3]
	v_mfma_f32_16x16x32_bf16 v[52:55], v[148:151], v[192:195], v[52:55]
	v_mfma_f32_16x16x32_bf16 v[48:51], v[184:187], v[192:195], v[48:51]
	v_mfma_f32_16x16x32_bf16 v[36:39], v[148:151], v[204:207], v[36:39]
	v_mfma_f32_16x16x32_bf16 v[32:35], v[184:187], v[204:207], v[32:35]
	v_mfma_f32_16x16x32_bf16 v[20:23], v[148:151], v[212:215], v[20:23]
	v_mfma_f32_16x16x32_bf16 v[16:19], v[184:187], v[212:215], v[16:19]
	v_mfma_f32_16x16x32_bf16 v[4:7], v[148:151], v[228:231], v[4:7]
	v_mfma_f32_16x16x32_bf16 v[0:3], v[184:187], v[228:231], v[0:3]
	s_setprio 0
	s_barrier
	s_add_i32 s12, s12, 2
	s_add_u32 s58, s58, 0x100
	s_addc_u32 s59, s59, 0
	s_cmp_gt_u32 s12, 41
	s_mov_b64 s[36:37], s[40:41]
.LBB0_1061:
	s_add_u32 s40, s36, 0x100
	s_addc_u32 s41, s37, 0
	s_add_i32 s0, 0, 0x10000
	s_cmp_eq_u32 s12, 40
	s_cselect_b32 s45, s9, s41
	s_cselect_b32 s44, s8, s40
	s_cselect_b32 s43, s35, s59
	s_cselect_b32 s42, s34, s58
	s_add_i32 s13, 0, 0x14000
	v_add_u32_e32 v140, s0, v197
	v_add_u32_e32 v184, s13, v197
	ds_read_b128 v[128:131], v140
	ds_read_b128 v[132:135], v140 offset:1024
	ds_read_b128 v[136:139], v140 offset:2048
	ds_read_b128 v[140:143], v140 offset:3072
	ds_read_b128 v[144:147], v184
	ds_read_b128 v[148:151], v184 offset:1024
	ds_read_b128 v[164:167], v184 offset:2048
	ds_read_b128 v[184:187], v184 offset:3072
	s_add_i32 m0, s47, 0xc000
	ds_read_b128 v[188:191], v198
	ds_read_b128 v[192:195], v198 offset:1024
	ds_read_b128 v[200:203], v198 offset:2048
	ds_read_b128 v[204:207], v198 offset:3072
	ds_read_b128 v[208:211], v198 offset:4096
	ds_read_b128 v[212:215], v198 offset:5120
	ds_read_b128 v[216:219], v198 offset:6144
	ds_read_b128 v[228:231], v198 offset:7168
	global_load_lds_dwordx4 v160, s[36:37]
	s_add_i32 m0, s47, 0xe000
	s_nop 0
	global_load_lds_dwordx4 v162, s[36:37]
	s_waitcnt vmcnt(8)
	s_waitcnt lgkmcnt(0)
	s_barrier
	s_setprio 1
	v_mfma_f32_16x16x32_bf16 v[124:127], v[128:131], v[188:191], v[124:127]
	v_mfma_f32_16x16x32_bf16 v[120:123], v[136:139], v[188:191], v[120:123]
	v_mfma_f32_16x16x32_bf16 v[108:111], v[128:131], v[200:203], v[108:111]
	v_mfma_f32_16x16x32_bf16 v[104:107], v[136:139], v[200:203], v[104:107]
	v_mfma_f32_16x16x32_bf16 v[92:95], v[128:131], v[208:211], v[92:95]
	v_mfma_f32_16x16x32_bf16 v[88:91], v[136:139], v[208:211], v[88:91]
	v_mfma_f32_16x16x32_bf16 v[76:79], v[128:131], v[216:219], v[76:79]
	v_mfma_f32_16x16x32_bf16 v[72:75], v[136:139], v[216:219], v[72:75]
	v_mfma_f32_16x16x32_bf16 v[124:127], v[132:135], v[192:195], v[124:127]
	v_mfma_f32_16x16x32_bf16 v[120:123], v[140:143], v[192:195], v[120:123]
	v_mfma_f32_16x16x32_bf16 v[108:111], v[132:135], v[204:207], v[108:111]
	v_mfma_f32_16x16x32_bf16 v[104:107], v[140:143], v[204:207], v[104:107]
	v_mfma_f32_16x16x32_bf16 v[92:95], v[132:135], v[212:215], v[92:95]
	v_mfma_f32_16x16x32_bf16 v[88:91], v[140:143], v[212:215], v[88:91]
	v_mfma_f32_16x16x32_bf16 v[76:79], v[132:135], v[228:231], v[76:79]
	v_mfma_f32_16x16x32_bf16 v[72:75], v[140:143], v[228:231], v[72:75]
	v_mfma_f32_16x16x32_bf16 v[116:119], v[144:147], v[188:191], v[116:119]
	v_mfma_f32_16x16x32_bf16 v[112:115], v[164:167], v[188:191], v[112:115]
	v_mfma_f32_16x16x32_bf16 v[100:103], v[144:147], v[200:203], v[100:103]
	v_mfma_f32_16x16x32_bf16 v[96:99], v[164:167], v[200:203], v[96:99]
	v_mfma_f32_16x16x32_bf16 v[84:87], v[144:147], v[208:211], v[84:87]
	v_mfma_f32_16x16x32_bf16 v[80:83], v[164:167], v[208:211], v[80:83]
	v_mfma_f32_16x16x32_bf16 v[68:71], v[144:147], v[216:219], v[68:71]
	v_mfma_f32_16x16x32_bf16 v[64:67], v[164:167], v[216:219], v[64:67]
	v_mfma_f32_16x16x32_bf16 v[116:119], v[148:151], v[192:195], v[116:119]
	v_mfma_f32_16x16x32_bf16 v[112:115], v[184:187], v[192:195], v[112:115]
	v_mfma_f32_16x16x32_bf16 v[100:103], v[148:151], v[204:207], v[100:103]
	v_mfma_f32_16x16x32_bf16 v[96:99], v[184:187], v[204:207], v[96:99]
	v_mfma_f32_16x16x32_bf16 v[84:87], v[148:151], v[212:215], v[84:87]
	v_mfma_f32_16x16x32_bf16 v[80:83], v[184:187], v[212:215], v[80:83]
	v_mfma_f32_16x16x32_bf16 v[68:71], v[148:151], v[228:231], v[68:71]
	v_mfma_f32_16x16x32_bf16 v[64:67], v[184:187], v[228:231], v[64:67]
	s_setprio 0
	s_barrier
	s_add_i32 s0, s0, s46
	v_lshl_add_u64 v[232:233], s[42:43], 0, v[170:171]
	s_mov_b32 m0, s0
	ds_read_b128 v[188:191], v198 offset:16384
	ds_read_b128 v[192:195], v198 offset:17408
	ds_read_b128 v[200:203], v198 offset:18432
	ds_read_b128 v[204:207], v198 offset:19456
	ds_read_b128 v[208:211], v198 offset:20480
	ds_read_b128 v[212:215], v198 offset:21504
	ds_read_b128 v[216:219], v198 offset:22528
	ds_read_b128 v[228:231], v198 offset:23552
	global_load_lds_dwordx4 v[232:233], off
	s_add_i32 m0, s0, 0x2000
	s_add_u32 s0, s42, 0xb0000
	v_lshl_add_u64 v[234:235], s[42:43], 0, v[156:157]
	s_addc_u32 s1, s43, 0
	s_add_i32 s13, s13, s46
	global_load_lds_dwordx4 v[234:235], off
	s_mov_b32 m0, s13
	v_lshl_add_u64 v[238:239], s[44:45], 0, v[154:155]
	global_load_lds_dwordx4 v170, s[0:1]
	s_add_i32 m0, s13, 0x2000
	s_nop 0
	global_load_lds_dwordx4 v156, s[0:1]
	v_lshl_add_u64 v[236:237], s[44:45], 0, v[152:153]
	s_waitcnt vmcnt(6)
	s_waitcnt lgkmcnt(0)
	s_barrier
	s_setprio 1
	v_mfma_f32_16x16x32_bf16 v[60:63], v[128:131], v[188:191], v[60:63]
	v_mfma_f32_16x16x32_bf16 v[56:59], v[136:139], v[188:191], v[56:59]
	v_mfma_f32_16x16x32_bf16 v[44:47], v[128:131], v[200:203], v[44:47]
	v_mfma_f32_16x16x32_bf16 v[40:43], v[136:139], v[200:203], v[40:43]
	v_mfma_f32_16x16x32_bf16 v[28:31], v[128:131], v[208:211], v[28:31]
	v_mfma_f32_16x16x32_bf16 v[24:27], v[136:139], v[208:211], v[24:27]
	v_mfma_f32_16x16x32_bf16 v[12:15], v[128:131], v[216:219], v[12:15]
	v_mfma_f32_16x16x32_bf16 v[8:11], v[136:139], v[216:219], v[8:11]
	v_mfma_f32_16x16x32_bf16 v[60:63], v[132:135], v[192:195], v[60:63]
	v_mfma_f32_16x16x32_bf16 v[56:59], v[140:143], v[192:195], v[56:59]
	v_mfma_f32_16x16x32_bf16 v[44:47], v[132:135], v[204:207], v[44:47]
	v_mfma_f32_16x16x32_bf16 v[40:43], v[140:143], v[204:207], v[40:43]
	v_mfma_f32_16x16x32_bf16 v[28:31], v[132:135], v[212:215], v[28:31]
	v_mfma_f32_16x16x32_bf16 v[24:27], v[140:143], v[212:215], v[24:27]
	v_mfma_f32_16x16x32_bf16 v[12:15], v[132:135], v[228:231], v[12:15]
	v_mfma_f32_16x16x32_bf16 v[8:11], v[140:143], v[228:231], v[8:11]
	v_mfma_f32_16x16x32_bf16 v[52:55], v[144:147], v[188:191], v[52:55]
	v_mfma_f32_16x16x32_bf16 v[48:51], v[164:167], v[188:191], v[48:51]
	v_mfma_f32_16x16x32_bf16 v[36:39], v[144:147], v[200:203], v[36:39]
	v_mfma_f32_16x16x32_bf16 v[32:35], v[164:167], v[200:203], v[32:35]
	v_mfma_f32_16x16x32_bf16 v[20:23], v[144:147], v[208:211], v[20:23]
	v_mfma_f32_16x16x32_bf16 v[16:19], v[164:167], v[208:211], v[16:19]
	v_mfma_f32_16x16x32_bf16 v[4:7], v[144:147], v[216:219], v[4:7]
	v_mfma_f32_16x16x32_bf16 v[0:3], v[164:167], v[216:219], v[0:3]
	v_mfma_f32_16x16x32_bf16 v[52:55], v[148:151], v[192:195], v[52:55]
	v_mfma_f32_16x16x32_bf16 v[48:51], v[184:187], v[192:195], v[48:51]
	v_mfma_f32_16x16x32_bf16 v[36:39], v[148:151], v[204:207], v[36:39]
	v_mfma_f32_16x16x32_bf16 v[32:35], v[184:187], v[204:207], v[32:35]
	v_mfma_f32_16x16x32_bf16 v[20:23], v[148:151], v[212:215], v[20:23]
	v_mfma_f32_16x16x32_bf16 v[16:19], v[184:187], v[212:215], v[16:19]
	v_mfma_f32_16x16x32_bf16 v[4:7], v[148:151], v[228:231], v[4:7]
	v_mfma_f32_16x16x32_bf16 v[0:3], v[184:187], v[228:231], v[0:3]
	s_setprio 0
	s_barrier
	s_add_i32 s13, 0, 0x18000
	s_add_i32 s36, 0, 0x1c000
	v_add_u32_e32 v140, s13, v197
	v_add_u32_e32 v184, s36, v197
	ds_read_b128 v[128:131], v140
	ds_read_b128 v[132:135], v140 offset:1024
	ds_read_b128 v[136:139], v140 offset:2048
	ds_read_b128 v[140:143], v140 offset:3072
	ds_read_b128 v[144:147], v184
	ds_read_b128 v[148:151], v184 offset:1024
	ds_read_b128 v[164:167], v184 offset:2048
	ds_read_b128 v[184:187], v184 offset:3072
	s_add_u32 s0, s44, 0xb0000
	s_addc_u32 s1, s45, 0
	s_mov_b32 m0, s49
	ds_read_b128 v[188:191], v198 offset:32768
	ds_read_b128 v[192:195], v198 offset:33792
	ds_read_b128 v[200:203], v198 offset:34816
	ds_read_b128 v[204:207], v198 offset:35840
	ds_read_b128 v[208:211], v198 offset:36864
	ds_read_b128 v[212:215], v198 offset:37888
	ds_read_b128 v[216:219], v198 offset:38912
	ds_read_b128 v[228:231], v198 offset:39936
	global_load_lds_dwordx4 v152, s[0:1]
	s_mov_b32 m0, s50
	s_nop 0
	global_load_lds_dwordx4 v154, s[0:1]
	s_mov_b32 m0, s47
	s_nop 0
	global_load_lds_dwordx4 v[236:237], off
	s_mov_b32 m0, s48
	s_nop 0
	global_load_lds_dwordx4 v[238:239], off
	s_waitcnt vmcnt(8)
	s_waitcnt lgkmcnt(0)
	s_barrier
	s_setprio 1
	v_mfma_f32_16x16x32_bf16 v[124:127], v[128:131], v[188:191], v[124:127]
	v_mfma_f32_16x16x32_bf16 v[120:123], v[136:139], v[188:191], v[120:123]
	v_mfma_f32_16x16x32_bf16 v[108:111], v[128:131], v[200:203], v[108:111]
	v_mfma_f32_16x16x32_bf16 v[104:107], v[136:139], v[200:203], v[104:107]
	v_mfma_f32_16x16x32_bf16 v[92:95], v[128:131], v[208:211], v[92:95]
	v_mfma_f32_16x16x32_bf16 v[88:91], v[136:139], v[208:211], v[88:91]
	v_mfma_f32_16x16x32_bf16 v[76:79], v[128:131], v[216:219], v[76:79]
	v_mfma_f32_16x16x32_bf16 v[72:75], v[136:139], v[216:219], v[72:75]
	v_mfma_f32_16x16x32_bf16 v[124:127], v[132:135], v[192:195], v[124:127]
	v_mfma_f32_16x16x32_bf16 v[120:123], v[140:143], v[192:195], v[120:123]
	v_mfma_f32_16x16x32_bf16 v[108:111], v[132:135], v[204:207], v[108:111]
	v_mfma_f32_16x16x32_bf16 v[104:107], v[140:143], v[204:207], v[104:107]
	v_mfma_f32_16x16x32_bf16 v[92:95], v[132:135], v[212:215], v[92:95]
	v_mfma_f32_16x16x32_bf16 v[88:91], v[140:143], v[212:215], v[88:91]
	v_mfma_f32_16x16x32_bf16 v[76:79], v[132:135], v[228:231], v[76:79]
	v_mfma_f32_16x16x32_bf16 v[72:75], v[140:143], v[228:231], v[72:75]
	v_mfma_f32_16x16x32_bf16 v[116:119], v[144:147], v[188:191], v[116:119]
	v_mfma_f32_16x16x32_bf16 v[112:115], v[164:167], v[188:191], v[112:115]
	v_mfma_f32_16x16x32_bf16 v[100:103], v[144:147], v[200:203], v[100:103]
	v_mfma_f32_16x16x32_bf16 v[96:99], v[164:167], v[200:203], v[96:99]
	v_mfma_f32_16x16x32_bf16 v[84:87], v[144:147], v[208:211], v[84:87]
	v_mfma_f32_16x16x32_bf16 v[80:83], v[164:167], v[208:211], v[80:83]
	v_mfma_f32_16x16x32_bf16 v[68:71], v[144:147], v[216:219], v[68:71]
	v_mfma_f32_16x16x32_bf16 v[64:67], v[164:167], v[216:219], v[64:67]
	v_mfma_f32_16x16x32_bf16 v[116:119], v[148:151], v[192:195], v[116:119]
	v_mfma_f32_16x16x32_bf16 v[112:115], v[184:187], v[192:195], v[112:115]
	v_mfma_f32_16x16x32_bf16 v[100:103], v[148:151], v[204:207], v[100:103]
	v_mfma_f32_16x16x32_bf16 v[96:99], v[184:187], v[204:207], v[96:99]
	v_mfma_f32_16x16x32_bf16 v[84:87], v[148:151], v[212:215], v[84:87]
	v_mfma_f32_16x16x32_bf16 v[80:83], v[184:187], v[212:215], v[80:83]
	v_mfma_f32_16x16x32_bf16 v[68:71], v[148:151], v[228:231], v[68:71]
	v_mfma_f32_16x16x32_bf16 v[64:67], v[184:187], v[228:231], v[64:67]
	s_setprio 0
	s_barrier
	s_add_i32 s0, s13, s46
	v_lshl_add_u64 v[232:233], v[232:233], 0, s[16:17]
	s_mov_b32 m0, s0
	ds_read_b128 v[188:191], v198 offset:49152
	ds_read_b128 v[192:195], v198 offset:50176
	ds_read_b128 v[200:203], v198 offset:51200
	ds_read_b128 v[204:207], v198 offset:52224
	ds_read_b128 v[208:211], v198 offset:53248
	ds_read_b128 v[212:215], v198 offset:54272
	ds_read_b128 v[216:219], v198 offset:55296
	ds_read_b128 v[228:231], v198 offset:56320
	global_load_lds_dwordx4 v[232:233], off
	s_add_i32 m0, s0, 0x2000
	s_add_u32 s0, s42, 0xb0080
	v_lshl_add_u64 v[232:233], v[234:235], 0, s[16:17]
	s_addc_u32 s1, s43, 0
	s_add_i32 s13, s36, s46
	global_load_lds_dwordx4 v[232:233], off
	s_mov_b32 m0, s13
	s_nop 0
	global_load_lds_dwordx4 v170, s[0:1]
	s_add_i32 m0, s13, 0x2000
	s_nop 0
	global_load_lds_dwordx4 v156, s[0:1]
	v_lshl_add_u64 v[232:233], v[236:237], 0, s[16:17]
	s_mov_b32 m0, s51
	s_nop 0
	global_load_lds_dwordx4 v[232:233], off
	v_lshl_add_u64 v[232:233], v[238:239], 0, s[16:17]
	s_mov_b32 m0, s52
	s_nop 0
	global_load_lds_dwordx4 v[232:233], off
	s_waitcnt vmcnt(6)
	s_waitcnt lgkmcnt(0)
	s_barrier
	s_setprio 1
	v_mfma_f32_16x16x32_bf16 v[60:63], v[128:131], v[188:191], v[60:63]
	v_mfma_f32_16x16x32_bf16 v[56:59], v[136:139], v[188:191], v[56:59]
	v_mfma_f32_16x16x32_bf16 v[44:47], v[128:131], v[200:203], v[44:47]
	v_mfma_f32_16x16x32_bf16 v[40:43], v[136:139], v[200:203], v[40:43]
	v_mfma_f32_16x16x32_bf16 v[28:31], v[128:131], v[208:211], v[28:31]
	v_mfma_f32_16x16x32_bf16 v[24:27], v[136:139], v[208:211], v[24:27]
	v_mfma_f32_16x16x32_bf16 v[12:15], v[128:131], v[216:219], v[12:15]
	v_mfma_f32_16x16x32_bf16 v[8:11], v[136:139], v[216:219], v[8:11]
	v_mfma_f32_16x16x32_bf16 v[60:63], v[132:135], v[192:195], v[60:63]
	v_mfma_f32_16x16x32_bf16 v[56:59], v[140:143], v[192:195], v[56:59]
	v_mfma_f32_16x16x32_bf16 v[44:47], v[132:135], v[204:207], v[44:47]
	v_mfma_f32_16x16x32_bf16 v[40:43], v[140:143], v[204:207], v[40:43]
	v_mfma_f32_16x16x32_bf16 v[28:31], v[132:135], v[212:215], v[28:31]
	v_mfma_f32_16x16x32_bf16 v[24:27], v[140:143], v[212:215], v[24:27]
	v_mfma_f32_16x16x32_bf16 v[12:15], v[132:135], v[228:231], v[12:15]
	v_mfma_f32_16x16x32_bf16 v[8:11], v[140:143], v[228:231], v[8:11]
	v_mfma_f32_16x16x32_bf16 v[52:55], v[144:147], v[188:191], v[52:55]
	v_mfma_f32_16x16x32_bf16 v[48:51], v[164:167], v[188:191], v[48:51]
	v_mfma_f32_16x16x32_bf16 v[36:39], v[144:147], v[200:203], v[36:39]
	v_mfma_f32_16x16x32_bf16 v[32:35], v[164:167], v[200:203], v[32:35]
	v_mfma_f32_16x16x32_bf16 v[20:23], v[144:147], v[208:211], v[20:23]
	v_mfma_f32_16x16x32_bf16 v[16:19], v[164:167], v[208:211], v[16:19]
	v_mfma_f32_16x16x32_bf16 v[4:7], v[144:147], v[216:219], v[4:7]
	v_mfma_f32_16x16x32_bf16 v[0:3], v[164:167], v[216:219], v[0:3]
	v_mfma_f32_16x16x32_bf16 v[52:55], v[148:151], v[192:195], v[52:55]
	v_mfma_f32_16x16x32_bf16 v[48:51], v[184:187], v[192:195], v[48:51]
	v_mfma_f32_16x16x32_bf16 v[36:39], v[148:151], v[204:207], v[36:39]
	v_mfma_f32_16x16x32_bf16 v[32:35], v[184:187], v[204:207], v[32:35]
	v_mfma_f32_16x16x32_bf16 v[20:23], v[148:151], v[212:215], v[20:23]
	v_mfma_f32_16x16x32_bf16 v[16:19], v[184:187], v[212:215], v[16:19]
	v_mfma_f32_16x16x32_bf16 v[4:7], v[148:151], v[228:231], v[4:7]
	v_mfma_f32_16x16x32_bf16 v[0:3], v[184:187], v[228:231], v[0:3]
	s_setprio 0
	s_barrier
	s_add_i32 s12, s12, 2
	s_add_u32 s58, s58, 0x100
	s_addc_u32 s59, s59, 0
	s_cmp_gt_u32 s12, 41
	s_mov_b64 s[36:37], s[40:41]
	s_cbranch_scc0 .LBB0_1061
	s_and_b64 vcc, exec, s[30:31]
	s_cbranch_vccz .LBB0_1064
	s_barrier
